# combo11: combo10 + GEMM K-loop barrier handoff: s_setprio 1 issued before waiting at the segment-opening barrier, redundant lgkmcnt wait after it removed, s_setprio 0 moved after the segment-closing b
# speedup vs baseline: 1.0174x; 1.0090x over previous
; #define PG8_STAGE(bufoff, gbase, voff) do { _Pragma("unroll") for (int _i = 0; _i < 2; ++_i) \
;         __builtin_amdgcn_global_load_lds((const unsigned*)((const char*)(gbase) + (voff)[_i]), (PG8_LAS unsigned*)(lds + (bufoff) + ldsw + _i * 8192), 16, 0, 0); } while (0)
; #define PG8_LDA(dst, b, h) do { _Pragma("unroll") for (int m = 0; m < 4; ++m) _Pragma("unroll") for (int k = 0; k < 2; ++k) dst[m][k] = *(const PG8_LAS bf16x8*)(lds + PG8_SA(b, h) + aoff + m * 2048 + k * 1024); } while (0)
; #define PG8_LDB(dst, b, h) do { _Pragma("unroll") for (int n = 0; n < 2; ++n) _Pragma("unroll") for (int k = 0; k < 2; ++k) dst[n][k] = *(const PG8_LAS bf16x8*)(lds + PG8_SB(b, h) + boff + n * 2048 + k * 1024); } while (0)
; #define PG8_MMA(ai, bj, At, Bt) do { __builtin_amdgcn_s_setprio(1); _Pragma("unroll") for (int m = 0; m < 4; ++m) _Pragma("unroll") for (int n = 0; n < 2; ++n) _Pragma("unroll") for (int k = 0; k < 2; ++k) \
;         acc[ai][bj][m][n] = __builtin_amdgcn_mfma_f32_16x16x32_bf16(Bt[n][k], At[m][k], acc[ai][bj][m][n], 0, 0, 0); __builtin_amdgcn_s_setprio(0); } while (0)
; #define PG8_WAIT_V(n) asm volatile("s_waitcnt vmcnt(" #n ")" ::: "memory")
; #define PG8_WAIT_L(n) asm volatile("s_waitcnt lgkmcnt(" #n ")" ::: "memory")
; #define PG8_BAR __builtin_amdgcn_s_barrier()
; #define PG8_SCHED __builtin_amdgcn_sched_barrier(0)
; template <class Epi, class Sched, bool ALIGN_EPI = false, bool SP2 = false>
; __device__ __forceinline__ void gemm_phase(PG8_LAS unsigned char* lds, const Gemm g, const Sched& S, const Epi& E, const int tid_arg) {
;     ...
;             PG8_LDB(B0, 0, 0); PG8_LDB(B1, 0, 1); PG8_SCHED; PG8_LDA(At, 0, 0); PG8_STAGE(PG8_SA(1, 1), a1 + hstep, voffA);
;             PG8_WAIT_V(8); PG8_WAIT_L(0); PG8_BAR; PG8_MMA(0, 0, At, B0); PG8_MMA(0, 1, At, B1); PG8_BAR; PG8_SCHED;
;             PG8_LDA(At, 0, 1); PG8_STAGE(PG8_SB(0, 0), b2, voffB); PG8_STAGE(PG8_SB(0, 1), b2 + hstep, voffB); PG8_STAGE(PG8_SA(0, 0), a2, voffA);
;             PG8_WAIT_V(8); PG8_WAIT_L(0); PG8_BAR; PG8_MMA(1, 0, At, B0); PG8_MMA(1, 1, At, B1); PG8_BAR; PG8_SCHED;
.LBB0_253:
	ds_read_b128 v[144:147], v166
	ds_read_b128 v[148:151], v167
	ds_read_b128 v[152:155], v168
	ds_read_b128 v[156:159], v169
	ds_read_b128 v[184:187], v170
	ds_read_b128 v[188:191], v171
	ds_read_b128 v[192:195], v172
	ds_read_b128 v[196:199], v173
	s_add_u32 s0, s8, 0xfffc0080
	s_addc_u32 s1, s9, -1
	s_cmp_eq_u32 s70, 12
	s_cselect_b32 s35, s23, s1
	s_cselect_b32 s34, s36, s0
	s_cselect_b32 s1, s21, s69
	s_cselect_b32 s0, s37, s68
	s_mov_b32 m0, s57
	v_lshl_add_u64 v[160:161], s[8:9], 0, v[138:139]
	ds_read_b128 v[200:203], v165
	ds_read_b128 v[204:207], v165 offset:1024
	ds_read_b128 v[208:211], v165 offset:2048
	ds_read_b128 v[212:215], v165 offset:3072
	ds_read_b128 v[216:219], v165 offset:4096
	ds_read_b128 v[220:223], v165 offset:5120
	ds_read_b128 v[224:227], v165 offset:6144
	ds_read_b128 v[228:231], v165 offset:7168
	global_load_lds_dwordx4 v[160:161], off
	v_lshl_add_u64 v[160:161], s[8:9], 0, v[136:137]
	s_mov_b32 m0, s58
	s_nop 0
	global_load_lds_dwordx4 v[160:161], off
	s_waitcnt vmcnt(8)
	s_waitcnt lgkmcnt(0)
	s_setprio 1
	s_barrier
	v_mfma_f32_16x16x32_bf16 v[124:127], v[144:147], v[200:203], v[124:127]
	v_mfma_f32_16x16x32_bf16 v[120:123], v[152:155], v[200:203], v[120:123]
	v_mfma_f32_16x16x32_bf16 v[108:111], v[144:147], v[208:211], v[108:111]
	v_mfma_f32_16x16x32_bf16 v[104:107], v[152:155], v[208:211], v[104:107]
	v_mfma_f32_16x16x32_bf16 v[92:95], v[144:147], v[216:219], v[92:95]
	v_mfma_f32_16x16x32_bf16 v[88:91], v[152:155], v[216:219], v[88:91]
	v_mfma_f32_16x16x32_bf16 v[76:79], v[144:147], v[224:227], v[76:79]
	v_mfma_f32_16x16x32_bf16 v[72:75], v[152:155], v[224:227], v[72:75]
	v_mfma_f32_16x16x32_bf16 v[124:127], v[148:151], v[204:207], v[124:127]
	v_mfma_f32_16x16x32_bf16 v[120:123], v[156:159], v[204:207], v[120:123]
	v_mfma_f32_16x16x32_bf16 v[108:111], v[148:151], v[212:215], v[108:111]
	v_mfma_f32_16x16x32_bf16 v[104:107], v[156:159], v[212:215], v[104:107]
	v_mfma_f32_16x16x32_bf16 v[92:95], v[148:151], v[220:223], v[92:95]
	v_mfma_f32_16x16x32_bf16 v[88:91], v[156:159], v[220:223], v[88:91]
	v_mfma_f32_16x16x32_bf16 v[76:79], v[148:151], v[228:231], v[76:79]
	v_mfma_f32_16x16x32_bf16 v[72:75], v[156:159], v[228:231], v[72:75]
	s_setprio 0
	s_setprio 1
	v_mfma_f32_16x16x32_bf16 v[116:119], v[184:187], v[200:203], v[116:119]
	v_mfma_f32_16x16x32_bf16 v[112:115], v[192:195], v[200:203], v[112:115]
	v_mfma_f32_16x16x32_bf16 v[100:103], v[184:187], v[208:211], v[100:103]
	v_mfma_f32_16x16x32_bf16 v[96:99], v[192:195], v[208:211], v[96:99]
	v_mfma_f32_16x16x32_bf16 v[84:87], v[184:187], v[216:219], v[84:87]
	v_mfma_f32_16x16x32_bf16 v[80:83], v[192:195], v[216:219], v[80:83]
	v_mfma_f32_16x16x32_bf16 v[68:71], v[184:187], v[224:227], v[68:71]
	v_mfma_f32_16x16x32_bf16 v[64:67], v[192:195], v[224:227], v[64:67]
	v_mfma_f32_16x16x32_bf16 v[116:119], v[188:191], v[204:207], v[116:119]
	v_mfma_f32_16x16x32_bf16 v[112:115], v[196:199], v[204:207], v[112:115]
	v_mfma_f32_16x16x32_bf16 v[100:103], v[188:191], v[212:215], v[100:103]
	v_mfma_f32_16x16x32_bf16 v[96:99], v[196:199], v[212:215], v[96:99]
	v_mfma_f32_16x16x32_bf16 v[84:87], v[188:191], v[220:223], v[84:87]
	v_mfma_f32_16x16x32_bf16 v[80:83], v[196:199], v[220:223], v[80:83]
	v_mfma_f32_16x16x32_bf16 v[68:71], v[188:191], v[228:231], v[68:71]
	v_mfma_f32_16x16x32_bf16 v[64:67], v[196:199], v[228:231], v[64:67]
	s_barrier
	s_setprio 0
	s_mov_b32 m0, s29
	v_lshl_add_u64 v[160:161], s[0:1], 0, v[130:131]
	s_add_u32 s72, s0, 0x40000
	ds_read_b128 v[200:203], v165 offset:16384
	ds_read_b128 v[204:207], v165 offset:17408
	ds_read_b128 v[208:211], v165 offset:18432
	ds_read_b128 v[212:215], v165 offset:19456
	ds_read_b128 v[216:219], v165 offset:20480
	ds_read_b128 v[220:223], v165 offset:21504
	ds_read_b128 v[224:227], v165 offset:22528
	ds_read_b128 v[228:231], v165 offset:23552
	global_load_lds_dwordx4 v[160:161], off
	v_lshl_add_u64 v[232:233], s[0:1], 0, v[134:135]
	s_mov_b32 m0, s31
	s_addc_u32 s73, s1, 0
	global_load_lds_dwordx4 v[232:233], off
	v_lshl_add_u64 v[234:235], s[72:73], 0, v[130:131]
	s_mov_b32 m0, s40
	v_lshl_add_u64 v[236:237], s[34:35], 0, v[132:133]
	global_load_lds_dwordx4 v[234:235], off
	v_lshl_add_u64 v[234:235], s[72:73], 0, v[134:135]
	s_mov_b32 m0, s41
	s_nop 0
	global_load_lds_dwordx4 v[234:235], off
	v_lshl_add_u64 v[234:235], s[34:35], 0, v[128:129]
	s_mov_b32 m0, s39
	s_nop 0
	global_load_lds_dwordx4 v[234:235], off
	s_mov_b32 m0, s42
	s_nop 0
	global_load_lds_dwordx4 v[236:237], off
	s_waitcnt vmcnt(8)
	s_waitcnt lgkmcnt(0)
	s_setprio 1
	s_barrier
; #define PG8_STAGE(bufoff, gbase, voff) do { _Pragma("unroll") for (int _i = 0; _i < 2; ++_i) \
;         __builtin_amdgcn_global_load_lds((const unsigned*)((const char*)(gbase) + (voff)[_i]), (PG8_LAS unsigned*)(lds + (bufoff) + ldsw + _i * 8192), 16, 0, 0); } while (0)
; #define PG8_LDA(dst, b, h) do { _Pragma("unroll") for (int m = 0; m < 4; ++m) _Pragma("unroll") for (int k = 0; k < 2; ++k) dst[m][k] = *(const PG8_LAS bf16x8*)(lds + PG8_SA(b, h) + aoff + m * 2048 + k * 1024); } while (0)
; #define PG8_LDB(dst, b, h) do { _Pragma("unroll") for (int n = 0; n < 2; ++n) _Pragma("unroll") for (int k = 0; k < 2; ++k) dst[n][k] = *(const PG8_LAS bf16x8*)(lds + PG8_SB(b, h) + boff + n * 2048 + k * 1024); } while (0)
; #define PG8_MMA(ai, bj, At, Bt) do { __builtin_amdgcn_s_setprio(1); _Pragma("unroll") for (int m = 0; m < 4; ++m) _Pragma("unroll") for (int n = 0; n < 2; ++n) _Pragma("unroll") for (int k = 0; k < 2; ++k) \
;         acc[ai][bj][m][n] = __builtin_amdgcn_mfma_f32_16x16x32_bf16(Bt[n][k], At[m][k], acc[ai][bj][m][n], 0, 0, 0); __builtin_amdgcn_s_setprio(0); } while (0)
; #define PG8_WAIT_V(n) asm volatile("s_waitcnt vmcnt(" #n ")" ::: "memory")
; #define PG8_WAIT_L(n) asm volatile("s_waitcnt lgkmcnt(" #n ")" ::: "memory")
; #define PG8_BAR __builtin_amdgcn_s_barrier()
; #define PG8_SCHED __builtin_amdgcn_sched_barrier(0)
; template <class Epi, class Sched, bool ALIGN_EPI = false, bool SP2 = false>
; __device__ __forceinline__ void gemm_phase(PG8_LAS unsigned char* lds, const Gemm g, const Sched& S, const Epi& E, const int tid_arg) {
;     ...
;             PG8_WAIT_V(8); PG8_WAIT_L(0); PG8_BAR; PG8_MMA(1, 0, At, B0); PG8_MMA(1, 1, At, B1); PG8_BAR; PG8_SCHED;
;             PG8_LDB(B0, 1, 0); PG8_LDB(B1, 1, 1); PG8_SCHED; PG8_LDA(At, 1, 0); PG8_STAGE(PG8_SA(0, 1), a2 + hstep, voffA);
;             PG8_WAIT_V(8); PG8_WAIT_L(0); PG8_BAR; PG8_MMA(0, 0, At, B0); PG8_MMA(0, 1, At, B1); PG8_BAR; PG8_SCHED;
	v_mfma_f32_16x16x32_bf16 v[60:63], v[144:147], v[200:203], v[60:63]
	v_mfma_f32_16x16x32_bf16 v[56:59], v[152:155], v[200:203], v[56:59]
	v_mfma_f32_16x16x32_bf16 v[44:47], v[144:147], v[208:211], v[44:47]
	v_mfma_f32_16x16x32_bf16 v[40:43], v[152:155], v[208:211], v[40:43]
	v_mfma_f32_16x16x32_bf16 v[28:31], v[144:147], v[216:219], v[28:31]
	v_mfma_f32_16x16x32_bf16 v[24:27], v[152:155], v[216:219], v[24:27]
	v_mfma_f32_16x16x32_bf16 v[12:15], v[144:147], v[224:227], v[12:15]
	v_mfma_f32_16x16x32_bf16 v[8:11], v[152:155], v[224:227], v[8:11]
	v_mfma_f32_16x16x32_bf16 v[60:63], v[148:151], v[204:207], v[60:63]
	v_mfma_f32_16x16x32_bf16 v[56:59], v[156:159], v[204:207], v[56:59]
	v_mfma_f32_16x16x32_bf16 v[44:47], v[148:151], v[212:215], v[44:47]
	v_mfma_f32_16x16x32_bf16 v[40:43], v[156:159], v[212:215], v[40:43]
	v_mfma_f32_16x16x32_bf16 v[28:31], v[148:151], v[220:223], v[28:31]
	v_mfma_f32_16x16x32_bf16 v[24:27], v[156:159], v[220:223], v[24:27]
	v_mfma_f32_16x16x32_bf16 v[12:15], v[148:151], v[228:231], v[12:15]
	v_mfma_f32_16x16x32_bf16 v[8:11], v[156:159], v[228:231], v[8:11]
	s_setprio 0
	s_setprio 1
	v_mfma_f32_16x16x32_bf16 v[52:55], v[184:187], v[200:203], v[52:55]
	v_mfma_f32_16x16x32_bf16 v[48:51], v[192:195], v[200:203], v[48:51]
	v_mfma_f32_16x16x32_bf16 v[36:39], v[184:187], v[208:211], v[36:39]
	v_mfma_f32_16x16x32_bf16 v[32:35], v[192:195], v[208:211], v[32:35]
	v_mfma_f32_16x16x32_bf16 v[20:23], v[184:187], v[216:219], v[20:23]
	v_mfma_f32_16x16x32_bf16 v[16:19], v[192:195], v[216:219], v[16:19]
	v_mfma_f32_16x16x32_bf16 v[4:7], v[184:187], v[224:227], v[4:7]
	v_mfma_f32_16x16x32_bf16 v[0:3], v[192:195], v[224:227], v[0:3]
	v_mfma_f32_16x16x32_bf16 v[52:55], v[188:191], v[204:207], v[52:55]
	v_mfma_f32_16x16x32_bf16 v[48:51], v[196:199], v[204:207], v[48:51]
	v_mfma_f32_16x16x32_bf16 v[36:39], v[188:191], v[212:215], v[36:39]
	v_mfma_f32_16x16x32_bf16 v[32:35], v[196:199], v[212:215], v[32:35]
	v_mfma_f32_16x16x32_bf16 v[20:23], v[188:191], v[220:223], v[20:23]
	v_mfma_f32_16x16x32_bf16 v[16:19], v[196:199], v[220:223], v[16:19]
	v_mfma_f32_16x16x32_bf16 v[4:7], v[188:191], v[228:231], v[4:7]
	v_mfma_f32_16x16x32_bf16 v[0:3], v[196:199], v[228:231], v[0:3]
	s_barrier
	s_setprio 0
	ds_read_b128 v[144:147], v174
	ds_read_b128 v[148:151], v175
	ds_read_b128 v[152:155], v176
	ds_read_b128 v[156:159], v177
	ds_read_b128 v[184:187], v178
	ds_read_b128 v[188:191], v179
	ds_read_b128 v[192:195], v180
	ds_read_b128 v[196:199], v181
	s_add_u32 s34, s34, 0x40000
	s_addc_u32 s35, s35, 0
	s_mov_b32 m0, s43
	v_lshl_add_u64 v[238:239], s[34:35], 0, v[128:129]
	ds_read_b128 v[200:203], v165 offset:32768
	ds_read_b128 v[204:207], v165 offset:33792
	ds_read_b128 v[208:211], v165 offset:34816
	ds_read_b128 v[212:215], v165 offset:35840
	ds_read_b128 v[216:219], v165 offset:36864
	ds_read_b128 v[220:223], v165 offset:37888
	ds_read_b128 v[224:227], v165 offset:38912
	ds_read_b128 v[228:231], v165 offset:39936
	global_load_lds_dwordx4 v[238:239], off
	v_lshl_add_u64 v[238:239], s[34:35], 0, v[132:133]
	s_mov_b32 m0, s44
	s_nop 0
	global_load_lds_dwordx4 v[238:239], off
	s_waitcnt vmcnt(8)
	s_waitcnt lgkmcnt(0)
	s_setprio 1
	s_barrier
	v_mfma_f32_16x16x32_bf16 v[124:127], v[144:147], v[200:203], v[124:127]
	v_mfma_f32_16x16x32_bf16 v[120:123], v[152:155], v[200:203], v[120:123]
	v_mfma_f32_16x16x32_bf16 v[108:111], v[144:147], v[208:211], v[108:111]
	v_mfma_f32_16x16x32_bf16 v[104:107], v[152:155], v[208:211], v[104:107]
	v_mfma_f32_16x16x32_bf16 v[92:95], v[144:147], v[216:219], v[92:95]
	v_mfma_f32_16x16x32_bf16 v[88:91], v[152:155], v[216:219], v[88:91]
	v_mfma_f32_16x16x32_bf16 v[76:79], v[144:147], v[224:227], v[76:79]
	v_mfma_f32_16x16x32_bf16 v[72:75], v[152:155], v[224:227], v[72:75]
	v_mfma_f32_16x16x32_bf16 v[124:127], v[148:151], v[204:207], v[124:127]
	v_mfma_f32_16x16x32_bf16 v[120:123], v[156:159], v[204:207], v[120:123]
	v_mfma_f32_16x16x32_bf16 v[108:111], v[148:151], v[212:215], v[108:111]
	v_mfma_f32_16x16x32_bf16 v[104:107], v[156:159], v[212:215], v[104:107]
	v_mfma_f32_16x16x32_bf16 v[92:95], v[148:151], v[220:223], v[92:95]
	v_mfma_f32_16x16x32_bf16 v[88:91], v[156:159], v[220:223], v[88:91]
	v_mfma_f32_16x16x32_bf16 v[76:79], v[148:151], v[228:231], v[76:79]
	v_mfma_f32_16x16x32_bf16 v[72:75], v[156:159], v[228:231], v[72:75]
	s_setprio 0
	s_setprio 1
	v_mfma_f32_16x16x32_bf16 v[116:119], v[184:187], v[200:203], v[116:119]
	v_mfma_f32_16x16x32_bf16 v[112:115], v[192:195], v[200:203], v[112:115]
	v_mfma_f32_16x16x32_bf16 v[100:103], v[184:187], v[208:211], v[100:103]
	v_mfma_f32_16x16x32_bf16 v[96:99], v[192:195], v[208:211], v[96:99]
	v_mfma_f32_16x16x32_bf16 v[84:87], v[184:187], v[216:219], v[84:87]
	v_mfma_f32_16x16x32_bf16 v[80:83], v[192:195], v[216:219], v[80:83]
	v_mfma_f32_16x16x32_bf16 v[68:71], v[184:187], v[224:227], v[68:71]
	v_mfma_f32_16x16x32_bf16 v[64:67], v[192:195], v[224:227], v[64:67]
	v_mfma_f32_16x16x32_bf16 v[116:119], v[188:191], v[204:207], v[116:119]
	v_mfma_f32_16x16x32_bf16 v[112:115], v[196:199], v[204:207], v[112:115]
	v_mfma_f32_16x16x32_bf16 v[100:103], v[188:191], v[212:215], v[100:103]
	v_mfma_f32_16x16x32_bf16 v[96:99], v[196:199], v[212:215], v[96:99]
	v_mfma_f32_16x16x32_bf16 v[84:87], v[188:191], v[220:223], v[84:87]
	v_mfma_f32_16x16x32_bf16 v[80:83], v[196:199], v[220:223], v[80:83]
	v_mfma_f32_16x16x32_bf16 v[68:71], v[188:191], v[228:231], v[68:71]
	v_mfma_f32_16x16x32_bf16 v[64:67], v[196:199], v[228:231], v[64:67]
	s_barrier
; #define PG8_STAGE(bufoff, gbase, voff) do { _Pragma("unroll") for (int _i = 0; _i < 2; ++_i) \
;         __builtin_amdgcn_global_load_lds((const unsigned*)((const char*)(gbase) + (voff)[_i]), (PG8_LAS unsigned*)(lds + (bufoff) + ldsw + _i * 8192), 16, 0, 0); } while (0)
; #define PG8_LDA(dst, b, h) do { _Pragma("unroll") for (int m = 0; m < 4; ++m) _Pragma("unroll") for (int k = 0; k < 2; ++k) dst[m][k] = *(const PG8_LAS bf16x8*)(lds + PG8_SA(b, h) + aoff + m * 2048 + k * 1024); } while (0)
; #define PG8_MMA(ai, bj, At, Bt) do { __builtin_amdgcn_s_setprio(1); _Pragma("unroll") for (int m = 0; m < 4; ++m) _Pragma("unroll") for (int n = 0; n < 2; ++n) _Pragma("unroll") for (int k = 0; k < 2; ++k) \
;         acc[ai][bj][m][n] = __builtin_amdgcn_mfma_f32_16x16x32_bf16(Bt[n][k], At[m][k], acc[ai][bj][m][n], 0, 0, 0); __builtin_amdgcn_s_setprio(0); } while (0)
; #define PG8_WAIT_V(n) asm volatile("s_waitcnt vmcnt(" #n ")" ::: "memory")
; #define PG8_WAIT_L(n) asm volatile("s_waitcnt lgkmcnt(" #n ")" ::: "memory")
; #define PG8_BAR __builtin_amdgcn_s_barrier()
; #define PG8_SCHED __builtin_amdgcn_sched_barrier(0)
; template <class Epi, class Sched, bool ALIGN_EPI = false, bool SP2 = false>
; __device__ __forceinline__ void gemm_phase(PG8_LAS unsigned char* lds, const Gemm g, const Sched& S, const Epi& E, const int tid_arg) {
;     ...
;             PG8_WAIT_V(8); PG8_WAIT_L(0); PG8_BAR; PG8_MMA(0, 0, At, B0); PG8_MMA(0, 1, At, B1); PG8_BAR; PG8_SCHED;
;             PG8_LDA(At, 1, 1); PG8_STAGE(PG8_SB(1, 0), b3, voffB); PG8_STAGE(PG8_SB(1, 1), b3 + hstep, voffB); PG8_STAGE(PG8_SA(1, 0), a3, voffA);
;             PG8_WAIT_V(8); PG8_WAIT_L(0); PG8_BAR; PG8_MMA(1, 0, At, B0); PG8_MMA(1, 1, At, B1); PG8_BAR; PG8_SCHED;
	s_setprio 0
	s_mov_b32 m0, s47
	v_lshl_add_u64 v[160:161], v[160:161], 0, s[14:15]
	s_add_u32 s0, s0, 0x40080
	ds_read_b128 v[200:203], v165 offset:49152
	ds_read_b128 v[204:207], v165 offset:50176
	ds_read_b128 v[208:211], v165 offset:51200
	ds_read_b128 v[212:215], v165 offset:52224
	ds_read_b128 v[216:219], v165 offset:53248
	ds_read_b128 v[220:223], v165 offset:54272
	ds_read_b128 v[224:227], v165 offset:55296
	ds_read_b128 v[228:231], v165 offset:56320
	global_load_lds_dwordx4 v[160:161], off
	v_lshl_add_u64 v[160:161], v[232:233], 0, s[14:15]
	s_mov_b32 m0, s48
	s_addc_u32 s1, s1, 0
	global_load_lds_dwordx4 v[160:161], off
	v_lshl_add_u64 v[160:161], s[0:1], 0, v[130:131]
	s_mov_b32 m0, s51
	s_nop 0
	global_load_lds_dwordx4 v[160:161], off
	v_lshl_add_u64 v[160:161], s[0:1], 0, v[134:135]
	s_mov_b32 m0, s52
	s_nop 0
	global_load_lds_dwordx4 v[160:161], off
	v_lshl_add_u64 v[160:161], v[234:235], 0, s[14:15]
	s_mov_b32 m0, s49
	s_nop 0
	global_load_lds_dwordx4 v[160:161], off
	v_lshl_add_u64 v[160:161], v[236:237], 0, s[14:15]
	s_mov_b32 m0, s50
	s_nop 0
	global_load_lds_dwordx4 v[160:161], off
	s_waitcnt vmcnt(8)
	s_waitcnt lgkmcnt(0)
	s_setprio 1
	s_barrier
	v_mfma_f32_16x16x32_bf16 v[60:63], v[144:147], v[200:203], v[60:63]
	v_mfma_f32_16x16x32_bf16 v[56:59], v[152:155], v[200:203], v[56:59]
	v_mfma_f32_16x16x32_bf16 v[44:47], v[144:147], v[208:211], v[44:47]
	v_mfma_f32_16x16x32_bf16 v[40:43], v[152:155], v[208:211], v[40:43]
	v_mfma_f32_16x16x32_bf16 v[28:31], v[144:147], v[216:219], v[28:31]
	v_mfma_f32_16x16x32_bf16 v[24:27], v[152:155], v[216:219], v[24:27]
	v_mfma_f32_16x16x32_bf16 v[12:15], v[144:147], v[224:227], v[12:15]
	v_mfma_f32_16x16x32_bf16 v[8:11], v[152:155], v[224:227], v[8:11]
	v_mfma_f32_16x16x32_bf16 v[60:63], v[148:151], v[204:207], v[60:63]
	v_mfma_f32_16x16x32_bf16 v[56:59], v[156:159], v[204:207], v[56:59]
	v_mfma_f32_16x16x32_bf16 v[44:47], v[148:151], v[212:215], v[44:47]
	v_mfma_f32_16x16x32_bf16 v[40:43], v[156:159], v[212:215], v[40:43]
	v_mfma_f32_16x16x32_bf16 v[28:31], v[148:151], v[220:223], v[28:31]
	v_mfma_f32_16x16x32_bf16 v[24:27], v[156:159], v[220:223], v[24:27]
	v_mfma_f32_16x16x32_bf16 v[12:15], v[148:151], v[228:231], v[12:15]
	v_mfma_f32_16x16x32_bf16 v[8:11], v[156:159], v[228:231], v[8:11]
	s_setprio 0
	s_setprio 1
	v_mfma_f32_16x16x32_bf16 v[52:55], v[184:187], v[200:203], v[52:55]
	v_mfma_f32_16x16x32_bf16 v[48:51], v[192:195], v[200:203], v[48:51]
	v_mfma_f32_16x16x32_bf16 v[36:39], v[184:187], v[208:211], v[36:39]
	v_mfma_f32_16x16x32_bf16 v[32:35], v[192:195], v[208:211], v[32:35]
	v_mfma_f32_16x16x32_bf16 v[20:23], v[184:187], v[216:219], v[20:23]
	v_mfma_f32_16x16x32_bf16 v[16:19], v[192:195], v[216:219], v[16:19]
	v_mfma_f32_16x16x32_bf16 v[4:7], v[184:187], v[224:227], v[4:7]
	v_mfma_f32_16x16x32_bf16 v[0:3], v[192:195], v[224:227], v[0:3]
	v_mfma_f32_16x16x32_bf16 v[52:55], v[188:191], v[204:207], v[52:55]
	v_mfma_f32_16x16x32_bf16 v[48:51], v[196:199], v[204:207], v[48:51]
	v_mfma_f32_16x16x32_bf16 v[36:39], v[188:191], v[212:215], v[36:39]
	v_mfma_f32_16x16x32_bf16 v[32:35], v[196:199], v[212:215], v[32:35]
	v_mfma_f32_16x16x32_bf16 v[20:23], v[188:191], v[220:223], v[20:23]
	v_mfma_f32_16x16x32_bf16 v[16:19], v[196:199], v[220:223], v[16:19]
	v_mfma_f32_16x16x32_bf16 v[4:7], v[188:191], v[228:231], v[4:7]
	v_mfma_f32_16x16x32_bf16 v[0:3], v[196:199], v[228:231], v[0:3]
	s_barrier
	s_setprio 0
	s_add_i32 s70, s70, 2
	s_add_u32 s68, s68, 0x100
	s_addc_u32 s69, s69, 0
	s_add_u32 s8, s8, 0x100
	s_addc_u32 s9, s9, 0
	s_cmp_gt_u32 s70, 13
	s_cbranch_scc0 .LBB0_253
	s_and_b64 vcc, exec, s[16:17]
	s_cbranch_vccz .LBB0_256
	s_barrier

; #define PG8_STAGE(bufoff, gbase, voff) do { _Pragma("unroll") for (int _i = 0; _i < 2; ++_i) \
;         __builtin_amdgcn_global_load_lds((const unsigned*)((const char*)(gbase) + (voff)[_i]), (PG8_LAS unsigned*)(lds + (bufoff) + ldsw + _i * 8192), 16, 0, 0); } while (0)
; #define PG8_LDA(dst, b, h) do { _Pragma("unroll") for (int m = 0; m < 4; ++m) _Pragma("unroll") for (int k = 0; k < 2; ++k) dst[m][k] = *(const PG8_LAS bf16x8*)(lds + PG8_SA(b, h) + aoff + m * 2048 + k * 1024); } while (0)
; #define PG8_LDB(dst, b, h) do { _Pragma("unroll") for (int n = 0; n < 2; ++n) _Pragma("unroll") for (int k = 0; k < 2; ++k) dst[n][k] = *(const PG8_LAS bf16x8*)(lds + PG8_SB(b, h) + boff + n * 2048 + k * 1024); } while (0)
; #define PG8_MMA(ai, bj, At, Bt) do { __builtin_amdgcn_s_setprio(1); _Pragma("unroll") for (int m = 0; m < 4; ++m) _Pragma("unroll") for (int n = 0; n < 2; ++n) _Pragma("unroll") for (int k = 0; k < 2; ++k) \
;         acc[ai][bj][m][n] = __builtin_amdgcn_mfma_f32_16x16x32_bf16(Bt[n][k], At[m][k], acc[ai][bj][m][n], 0, 0, 0); __builtin_amdgcn_s_setprio(0); } while (0)
; #define PG8_WAIT_V(n) asm volatile("s_waitcnt vmcnt(" #n ")" ::: "memory")
; #define PG8_WAIT_L(n) asm volatile("s_waitcnt lgkmcnt(" #n ")" ::: "memory")
; #define PG8_BAR __builtin_amdgcn_s_barrier()
; #define PG8_SCHED __builtin_amdgcn_sched_barrier(0)
; template <class Epi, class Sched, bool ALIGN_EPI = false, bool SP2 = false>
; __device__ __forceinline__ void gemm_phase(PG8_LAS unsigned char* lds, const Gemm g, const Sched& S, const Epi& E, const int tid_arg) {
;     ...
;             PG8_LDB(B0, 0, 0); PG8_LDB(B1, 0, 1); PG8_SCHED; PG8_LDA(At, 0, 0); PG8_STAGE(PG8_SA(1, 1), a1 + hstep, voffA);
;             PG8_WAIT_V(8); PG8_WAIT_L(0); PG8_BAR; PG8_MMA(0, 0, At, B0); PG8_MMA(0, 1, At, B1); PG8_BAR; PG8_SCHED;
;             PG8_LDA(At, 0, 1); PG8_STAGE(PG8_SB(0, 0), b2, voffB); PG8_STAGE(PG8_SB(0, 1), b2 + hstep, voffB); PG8_STAGE(PG8_SA(0, 0), a2, voffA);
;             PG8_WAIT_V(8); PG8_WAIT_L(0); PG8_BAR; PG8_MMA(1, 0, At, B0); PG8_MMA(1, 1, At, B1); PG8_BAR; PG8_SCHED;
.LBB0_533:
	ds_read_b128 v[128:131], v165
	ds_read_b128 v[132:135], v166
	ds_read_b128 v[152:155], v167
	ds_read_b128 v[156:159], v168
	ds_read_b128 v[182:185], v169
	ds_read_b128 v[186:189], v170
	ds_read_b128 v[190:193], v171
	ds_read_b128 v[194:197], v172
	s_add_u32 s0, s12, 0xfffc0080
	s_addc_u32 s1, s13, -1
	s_cmp_eq_u32 s65, 12
	s_cselect_b32 s37, s11, s1
	s_cselect_b32 s36, s29, s0
	s_cselect_b32 s1, s27, s64
	s_cselect_b32 s0, s62, s63
	s_mov_b32 m0, s59
	v_lshl_add_u64 v[160:161], s[12:13], 0, v[146:147]
	ds_read_b128 v[198:201], v164
	ds_read_b128 v[202:205], v164 offset:1024
	ds_read_b128 v[206:209], v164 offset:2048
	ds_read_b128 v[210:213], v164 offset:3072
	ds_read_b128 v[214:217], v164 offset:4096
	ds_read_b128 v[218:221], v164 offset:5120
	ds_read_b128 v[222:225], v164 offset:6144
	ds_read_b128 v[226:229], v164 offset:7168
	global_load_lds_dwordx4 v[160:161], off
	v_lshl_add_u64 v[160:161], s[12:13], 0, v[144:145]
	s_mov_b32 m0, s60
	s_nop 0
	global_load_lds_dwordx4 v[160:161], off
	s_waitcnt vmcnt(8)
	s_waitcnt lgkmcnt(0)
	s_setprio 1
	s_barrier
	v_mfma_f32_16x16x32_bf16 v[124:127], v[128:131], v[198:201], v[124:127]
	v_mfma_f32_16x16x32_bf16 v[120:123], v[152:155], v[198:201], v[120:123]
	v_mfma_f32_16x16x32_bf16 v[108:111], v[128:131], v[206:209], v[108:111]
	v_mfma_f32_16x16x32_bf16 v[104:107], v[152:155], v[206:209], v[104:107]
	v_mfma_f32_16x16x32_bf16 v[92:95], v[128:131], v[214:217], v[92:95]
	v_mfma_f32_16x16x32_bf16 v[88:91], v[152:155], v[214:217], v[88:91]
	v_mfma_f32_16x16x32_bf16 v[76:79], v[128:131], v[222:225], v[76:79]
	v_mfma_f32_16x16x32_bf16 v[72:75], v[152:155], v[222:225], v[72:75]
	v_mfma_f32_16x16x32_bf16 v[124:127], v[132:135], v[202:205], v[124:127]
	v_mfma_f32_16x16x32_bf16 v[120:123], v[156:159], v[202:205], v[120:123]
	v_mfma_f32_16x16x32_bf16 v[108:111], v[132:135], v[210:213], v[108:111]
	v_mfma_f32_16x16x32_bf16 v[104:107], v[156:159], v[210:213], v[104:107]
	v_mfma_f32_16x16x32_bf16 v[92:95], v[132:135], v[218:221], v[92:95]
	v_mfma_f32_16x16x32_bf16 v[88:91], v[156:159], v[218:221], v[88:91]
	v_mfma_f32_16x16x32_bf16 v[76:79], v[132:135], v[226:229], v[76:79]
	v_mfma_f32_16x16x32_bf16 v[72:75], v[156:159], v[226:229], v[72:75]
	s_setprio 0
	s_setprio 1
	v_mfma_f32_16x16x32_bf16 v[116:119], v[182:185], v[198:201], v[116:119]
	v_mfma_f32_16x16x32_bf16 v[112:115], v[190:193], v[198:201], v[112:115]
	v_mfma_f32_16x16x32_bf16 v[100:103], v[182:185], v[206:209], v[100:103]
	v_mfma_f32_16x16x32_bf16 v[96:99], v[190:193], v[206:209], v[96:99]
	v_mfma_f32_16x16x32_bf16 v[84:87], v[182:185], v[214:217], v[84:87]
	v_mfma_f32_16x16x32_bf16 v[80:83], v[190:193], v[214:217], v[80:83]
	v_mfma_f32_16x16x32_bf16 v[68:71], v[182:185], v[222:225], v[68:71]
	v_mfma_f32_16x16x32_bf16 v[64:67], v[190:193], v[222:225], v[64:67]
	v_mfma_f32_16x16x32_bf16 v[116:119], v[186:189], v[202:205], v[116:119]
	v_mfma_f32_16x16x32_bf16 v[112:115], v[194:197], v[202:205], v[112:115]
	v_mfma_f32_16x16x32_bf16 v[100:103], v[186:189], v[210:213], v[100:103]
	v_mfma_f32_16x16x32_bf16 v[96:99], v[194:197], v[210:213], v[96:99]
	v_mfma_f32_16x16x32_bf16 v[84:87], v[186:189], v[218:221], v[84:87]
	v_mfma_f32_16x16x32_bf16 v[80:83], v[194:197], v[218:221], v[80:83]
	v_mfma_f32_16x16x32_bf16 v[68:71], v[186:189], v[226:229], v[68:71]
	v_mfma_f32_16x16x32_bf16 v[64:67], v[194:197], v[226:229], v[64:67]
	s_barrier
	s_setprio 0
	s_mov_b32 m0, s5
	v_lshl_add_u64 v[160:161], s[0:1], 0, v[138:139]
	s_add_u32 s66, s0, 0x40000
	ds_read_b128 v[198:201], v164 offset:16384
	ds_read_b128 v[202:205], v164 offset:17408
	ds_read_b128 v[206:209], v164 offset:18432
	ds_read_b128 v[210:213], v164 offset:19456
	ds_read_b128 v[214:217], v164 offset:20480
	ds_read_b128 v[218:221], v164 offset:21504
	ds_read_b128 v[222:225], v164 offset:22528
	ds_read_b128 v[226:229], v164 offset:23552
	global_load_lds_dwordx4 v[160:161], off
	v_lshl_add_u64 v[230:231], s[0:1], 0, v[142:143]
	s_mov_b32 m0, s40
	s_addc_u32 s67, s1, 0
	global_load_lds_dwordx4 v[230:231], off
	v_lshl_add_u64 v[232:233], s[66:67], 0, v[138:139]
	s_mov_b32 m0, s41
	v_lshl_add_u64 v[234:235], s[36:37], 0, v[140:141]
	global_load_lds_dwordx4 v[232:233], off
	v_lshl_add_u64 v[232:233], s[66:67], 0, v[142:143]
	s_mov_b32 m0, s42
	s_nop 0
	global_load_lds_dwordx4 v[232:233], off
	v_lshl_add_u64 v[232:233], s[36:37], 0, v[136:137]
	s_mov_b32 m0, s39
	s_nop 0
	global_load_lds_dwordx4 v[232:233], off
	s_mov_b32 m0, s43
	s_nop 0
	global_load_lds_dwordx4 v[234:235], off
	s_waitcnt vmcnt(8)
	s_waitcnt lgkmcnt(0)
	s_setprio 1
	s_barrier
; #define PG8_STAGE(bufoff, gbase, voff) do { _Pragma("unroll") for (int _i = 0; _i < 2; ++_i) \
;         __builtin_amdgcn_global_load_lds((const unsigned*)((const char*)(gbase) + (voff)[_i]), (PG8_LAS unsigned*)(lds + (bufoff) + ldsw + _i * 8192), 16, 0, 0); } while (0)
; #define PG8_LDA(dst, b, h) do { _Pragma("unroll") for (int m = 0; m < 4; ++m) _Pragma("unroll") for (int k = 0; k < 2; ++k) dst[m][k] = *(const PG8_LAS bf16x8*)(lds + PG8_SA(b, h) + aoff + m * 2048 + k * 1024); } while (0)
; #define PG8_LDB(dst, b, h) do { _Pragma("unroll") for (int n = 0; n < 2; ++n) _Pragma("unroll") for (int k = 0; k < 2; ++k) dst[n][k] = *(const PG8_LAS bf16x8*)(lds + PG8_SB(b, h) + boff + n * 2048 + k * 1024); } while (0)
; #define PG8_MMA(ai, bj, At, Bt) do { __builtin_amdgcn_s_setprio(1); _Pragma("unroll") for (int m = 0; m < 4; ++m) _Pragma("unroll") for (int n = 0; n < 2; ++n) _Pragma("unroll") for (int k = 0; k < 2; ++k) \
;         acc[ai][bj][m][n] = __builtin_amdgcn_mfma_f32_16x16x32_bf16(Bt[n][k], At[m][k], acc[ai][bj][m][n], 0, 0, 0); __builtin_amdgcn_s_setprio(0); } while (0)
; #define PG8_WAIT_V(n) asm volatile("s_waitcnt vmcnt(" #n ")" ::: "memory")
; #define PG8_WAIT_L(n) asm volatile("s_waitcnt lgkmcnt(" #n ")" ::: "memory")
; #define PG8_BAR __builtin_amdgcn_s_barrier()
; #define PG8_SCHED __builtin_amdgcn_sched_barrier(0)
; template <class Epi, class Sched, bool ALIGN_EPI = false, bool SP2 = false>
; __device__ __forceinline__ void gemm_phase(PG8_LAS unsigned char* lds, const Gemm g, const Sched& S, const Epi& E, const int tid_arg) {
;     ...
;             PG8_WAIT_V(8); PG8_WAIT_L(0); PG8_BAR; PG8_MMA(1, 0, At, B0); PG8_MMA(1, 1, At, B1); PG8_BAR; PG8_SCHED;
;             PG8_LDB(B0, 1, 0); PG8_LDB(B1, 1, 1); PG8_SCHED; PG8_LDA(At, 1, 0); PG8_STAGE(PG8_SA(0, 1), a2 + hstep, voffA);
;             PG8_WAIT_V(8); PG8_WAIT_L(0); PG8_BAR; PG8_MMA(0, 0, At, B0); PG8_MMA(0, 1, At, B1); PG8_BAR; PG8_SCHED;
	v_mfma_f32_16x16x32_bf16 v[60:63], v[128:131], v[198:201], v[60:63]
	v_mfma_f32_16x16x32_bf16 v[56:59], v[152:155], v[198:201], v[56:59]
	v_mfma_f32_16x16x32_bf16 v[44:47], v[128:131], v[206:209], v[44:47]
	v_mfma_f32_16x16x32_bf16 v[40:43], v[152:155], v[206:209], v[40:43]
	v_mfma_f32_16x16x32_bf16 v[28:31], v[128:131], v[214:217], v[28:31]
	v_mfma_f32_16x16x32_bf16 v[24:27], v[152:155], v[214:217], v[24:27]
	v_mfma_f32_16x16x32_bf16 v[12:15], v[128:131], v[222:225], v[12:15]
	v_mfma_f32_16x16x32_bf16 v[8:11], v[152:155], v[222:225], v[8:11]
	v_mfma_f32_16x16x32_bf16 v[60:63], v[132:135], v[202:205], v[60:63]
	v_mfma_f32_16x16x32_bf16 v[56:59], v[156:159], v[202:205], v[56:59]
	v_mfma_f32_16x16x32_bf16 v[44:47], v[132:135], v[210:213], v[44:47]
	v_mfma_f32_16x16x32_bf16 v[40:43], v[156:159], v[210:213], v[40:43]
	v_mfma_f32_16x16x32_bf16 v[28:31], v[132:135], v[218:221], v[28:31]
	v_mfma_f32_16x16x32_bf16 v[24:27], v[156:159], v[218:221], v[24:27]
	v_mfma_f32_16x16x32_bf16 v[12:15], v[132:135], v[226:229], v[12:15]
	v_mfma_f32_16x16x32_bf16 v[8:11], v[156:159], v[226:229], v[8:11]
	s_setprio 0
	s_setprio 1
	v_mfma_f32_16x16x32_bf16 v[52:55], v[182:185], v[198:201], v[52:55]
	v_mfma_f32_16x16x32_bf16 v[48:51], v[190:193], v[198:201], v[48:51]
	v_mfma_f32_16x16x32_bf16 v[36:39], v[182:185], v[206:209], v[36:39]
	v_mfma_f32_16x16x32_bf16 v[32:35], v[190:193], v[206:209], v[32:35]
	v_mfma_f32_16x16x32_bf16 v[20:23], v[182:185], v[214:217], v[20:23]
	v_mfma_f32_16x16x32_bf16 v[16:19], v[190:193], v[214:217], v[16:19]
	v_mfma_f32_16x16x32_bf16 v[4:7], v[182:185], v[222:225], v[4:7]
	v_mfma_f32_16x16x32_bf16 v[0:3], v[190:193], v[222:225], v[0:3]
	v_mfma_f32_16x16x32_bf16 v[52:55], v[186:189], v[202:205], v[52:55]
	v_mfma_f32_16x16x32_bf16 v[48:51], v[194:197], v[202:205], v[48:51]
	v_mfma_f32_16x16x32_bf16 v[36:39], v[186:189], v[210:213], v[36:39]
	v_mfma_f32_16x16x32_bf16 v[32:35], v[194:197], v[210:213], v[32:35]
	v_mfma_f32_16x16x32_bf16 v[20:23], v[186:189], v[218:221], v[20:23]
	v_mfma_f32_16x16x32_bf16 v[16:19], v[194:197], v[218:221], v[16:19]
	v_mfma_f32_16x16x32_bf16 v[4:7], v[186:189], v[226:229], v[4:7]
	v_mfma_f32_16x16x32_bf16 v[0:3], v[194:197], v[226:229], v[0:3]
	s_barrier
	s_setprio 0
	ds_read_b128 v[128:131], v173
	ds_read_b128 v[132:135], v174
	ds_read_b128 v[152:155], v175
	ds_read_b128 v[156:159], v176
	ds_read_b128 v[182:185], v177
	ds_read_b128 v[186:189], v178
	ds_read_b128 v[190:193], v179
	ds_read_b128 v[194:197], v180
	s_add_u32 s36, s36, 0x40000
	s_addc_u32 s37, s37, 0
	s_mov_b32 m0, s44
	v_lshl_add_u64 v[236:237], s[36:37], 0, v[136:137]
	ds_read_b128 v[198:201], v164 offset:32768
	ds_read_b128 v[202:205], v164 offset:33792
	ds_read_b128 v[206:209], v164 offset:34816
	ds_read_b128 v[210:213], v164 offset:35840
	ds_read_b128 v[214:217], v164 offset:36864
	ds_read_b128 v[218:221], v164 offset:37888
	ds_read_b128 v[222:225], v164 offset:38912
	ds_read_b128 v[226:229], v164 offset:39936
	global_load_lds_dwordx4 v[236:237], off
	v_lshl_add_u64 v[236:237], s[36:37], 0, v[140:141]
	s_mov_b32 m0, s45
	s_nop 0
	global_load_lds_dwordx4 v[236:237], off
	s_waitcnt vmcnt(8)
	s_waitcnt lgkmcnt(0)
	s_setprio 1
	s_barrier
	v_mfma_f32_16x16x32_bf16 v[124:127], v[128:131], v[198:201], v[124:127]
	v_mfma_f32_16x16x32_bf16 v[120:123], v[152:155], v[198:201], v[120:123]
	v_mfma_f32_16x16x32_bf16 v[108:111], v[128:131], v[206:209], v[108:111]
	v_mfma_f32_16x16x32_bf16 v[104:107], v[152:155], v[206:209], v[104:107]
	v_mfma_f32_16x16x32_bf16 v[92:95], v[128:131], v[214:217], v[92:95]
	v_mfma_f32_16x16x32_bf16 v[88:91], v[152:155], v[214:217], v[88:91]
	v_mfma_f32_16x16x32_bf16 v[76:79], v[128:131], v[222:225], v[76:79]
	v_mfma_f32_16x16x32_bf16 v[72:75], v[152:155], v[222:225], v[72:75]
	v_mfma_f32_16x16x32_bf16 v[124:127], v[132:135], v[202:205], v[124:127]
	v_mfma_f32_16x16x32_bf16 v[120:123], v[156:159], v[202:205], v[120:123]
	v_mfma_f32_16x16x32_bf16 v[108:111], v[132:135], v[210:213], v[108:111]
	v_mfma_f32_16x16x32_bf16 v[104:107], v[156:159], v[210:213], v[104:107]
	v_mfma_f32_16x16x32_bf16 v[92:95], v[132:135], v[218:221], v[92:95]
	v_mfma_f32_16x16x32_bf16 v[88:91], v[156:159], v[218:221], v[88:91]
	v_mfma_f32_16x16x32_bf16 v[76:79], v[132:135], v[226:229], v[76:79]
	v_mfma_f32_16x16x32_bf16 v[72:75], v[156:159], v[226:229], v[72:75]
	s_setprio 0
	s_setprio 1
	v_mfma_f32_16x16x32_bf16 v[116:119], v[182:185], v[198:201], v[116:119]
	v_mfma_f32_16x16x32_bf16 v[112:115], v[190:193], v[198:201], v[112:115]
	v_mfma_f32_16x16x32_bf16 v[100:103], v[182:185], v[206:209], v[100:103]
	v_mfma_f32_16x16x32_bf16 v[96:99], v[190:193], v[206:209], v[96:99]
	v_mfma_f32_16x16x32_bf16 v[84:87], v[182:185], v[214:217], v[84:87]
	v_mfma_f32_16x16x32_bf16 v[80:83], v[190:193], v[214:217], v[80:83]
	v_mfma_f32_16x16x32_bf16 v[68:71], v[182:185], v[222:225], v[68:71]
	v_mfma_f32_16x16x32_bf16 v[64:67], v[190:193], v[222:225], v[64:67]
	v_mfma_f32_16x16x32_bf16 v[116:119], v[186:189], v[202:205], v[116:119]
	v_mfma_f32_16x16x32_bf16 v[112:115], v[194:197], v[202:205], v[112:115]
	v_mfma_f32_16x16x32_bf16 v[100:103], v[186:189], v[210:213], v[100:103]
	v_mfma_f32_16x16x32_bf16 v[96:99], v[194:197], v[210:213], v[96:99]
	v_mfma_f32_16x16x32_bf16 v[84:87], v[186:189], v[218:221], v[84:87]
	v_mfma_f32_16x16x32_bf16 v[80:83], v[194:197], v[218:221], v[80:83]
	v_mfma_f32_16x16x32_bf16 v[68:71], v[186:189], v[226:229], v[68:71]
	v_mfma_f32_16x16x32_bf16 v[64:67], v[194:197], v[226:229], v[64:67]
	s_barrier
; #define PG8_STAGE(bufoff, gbase, voff) do { _Pragma("unroll") for (int _i = 0; _i < 2; ++_i) \
;         __builtin_amdgcn_global_load_lds((const unsigned*)((const char*)(gbase) + (voff)[_i]), (PG8_LAS unsigned*)(lds + (bufoff) + ldsw + _i * 8192), 16, 0, 0); } while (0)
; #define PG8_LDA(dst, b, h) do { _Pragma("unroll") for (int m = 0; m < 4; ++m) _Pragma("unroll") for (int k = 0; k < 2; ++k) dst[m][k] = *(const PG8_LAS bf16x8*)(lds + PG8_SA(b, h) + aoff + m * 2048 + k * 1024); } while (0)
; #define PG8_MMA(ai, bj, At, Bt) do { __builtin_amdgcn_s_setprio(1); _Pragma("unroll") for (int m = 0; m < 4; ++m) _Pragma("unroll") for (int n = 0; n < 2; ++n) _Pragma("unroll") for (int k = 0; k < 2; ++k) \
;         acc[ai][bj][m][n] = __builtin_amdgcn_mfma_f32_16x16x32_bf16(Bt[n][k], At[m][k], acc[ai][bj][m][n], 0, 0, 0); __builtin_amdgcn_s_setprio(0); } while (0)
; #define PG8_WAIT_V(n) asm volatile("s_waitcnt vmcnt(" #n ")" ::: "memory")
; #define PG8_WAIT_L(n) asm volatile("s_waitcnt lgkmcnt(" #n ")" ::: "memory")
; #define PG8_BAR __builtin_amdgcn_s_barrier()
; #define PG8_SCHED __builtin_amdgcn_sched_barrier(0)
; template <class Epi, class Sched, bool ALIGN_EPI = false, bool SP2 = false>
; __device__ __forceinline__ void gemm_phase(PG8_LAS unsigned char* lds, const Gemm g, const Sched& S, const Epi& E, const int tid_arg) {
;     ...
;             PG8_WAIT_V(8); PG8_WAIT_L(0); PG8_BAR; PG8_MMA(0, 0, At, B0); PG8_MMA(0, 1, At, B1); PG8_BAR; PG8_SCHED;
;             PG8_LDA(At, 1, 1); PG8_STAGE(PG8_SB(1, 0), b3, voffB); PG8_STAGE(PG8_SB(1, 1), b3 + hstep, voffB); PG8_STAGE(PG8_SA(1, 0), a3, voffA);
;             PG8_WAIT_V(8); PG8_WAIT_L(0); PG8_BAR; PG8_MMA(1, 0, At, B0); PG8_MMA(1, 1, At, B1); PG8_BAR; PG8_SCHED;
	s_setprio 0
	s_mov_b32 m0, s49
	v_lshl_add_u64 v[160:161], v[160:161], 0, s[20:21]
	s_add_u32 s0, s0, 0x40080
	ds_read_b128 v[198:201], v164 offset:49152
	ds_read_b128 v[202:205], v164 offset:50176
	ds_read_b128 v[206:209], v164 offset:51200
	ds_read_b128 v[210:213], v164 offset:52224
	ds_read_b128 v[214:217], v164 offset:53248
	ds_read_b128 v[218:221], v164 offset:54272
	ds_read_b128 v[222:225], v164 offset:55296
	ds_read_b128 v[226:229], v164 offset:56320
	global_load_lds_dwordx4 v[160:161], off
	v_lshl_add_u64 v[160:161], v[230:231], 0, s[20:21]
	s_mov_b32 m0, s50
	s_addc_u32 s1, s1, 0
	global_load_lds_dwordx4 v[160:161], off
	v_lshl_add_u64 v[160:161], s[0:1], 0, v[138:139]
	s_mov_b32 m0, s53
	s_nop 0
	global_load_lds_dwordx4 v[160:161], off
	v_lshl_add_u64 v[160:161], s[0:1], 0, v[142:143]
	s_mov_b32 m0, s54
	s_nop 0
	global_load_lds_dwordx4 v[160:161], off
	v_lshl_add_u64 v[160:161], v[232:233], 0, s[20:21]
	s_mov_b32 m0, s51
	s_nop 0
	global_load_lds_dwordx4 v[160:161], off
	v_lshl_add_u64 v[160:161], v[234:235], 0, s[20:21]
	s_mov_b32 m0, s52
	s_nop 0
	global_load_lds_dwordx4 v[160:161], off
	s_waitcnt vmcnt(8)
	s_waitcnt lgkmcnt(0)
	s_setprio 1
	s_barrier
	v_mfma_f32_16x16x32_bf16 v[60:63], v[128:131], v[198:201], v[60:63]
	v_mfma_f32_16x16x32_bf16 v[56:59], v[152:155], v[198:201], v[56:59]
	v_mfma_f32_16x16x32_bf16 v[44:47], v[128:131], v[206:209], v[44:47]
	v_mfma_f32_16x16x32_bf16 v[40:43], v[152:155], v[206:209], v[40:43]
	v_mfma_f32_16x16x32_bf16 v[28:31], v[128:131], v[214:217], v[28:31]
	v_mfma_f32_16x16x32_bf16 v[24:27], v[152:155], v[214:217], v[24:27]
	v_mfma_f32_16x16x32_bf16 v[12:15], v[128:131], v[222:225], v[12:15]
	v_mfma_f32_16x16x32_bf16 v[8:11], v[152:155], v[222:225], v[8:11]
	v_mfma_f32_16x16x32_bf16 v[60:63], v[132:135], v[202:205], v[60:63]
	v_mfma_f32_16x16x32_bf16 v[56:59], v[156:159], v[202:205], v[56:59]
	v_mfma_f32_16x16x32_bf16 v[44:47], v[132:135], v[210:213], v[44:47]
	v_mfma_f32_16x16x32_bf16 v[40:43], v[156:159], v[210:213], v[40:43]
	v_mfma_f32_16x16x32_bf16 v[28:31], v[132:135], v[218:221], v[28:31]
	v_mfma_f32_16x16x32_bf16 v[24:27], v[156:159], v[218:221], v[24:27]
	v_mfma_f32_16x16x32_bf16 v[12:15], v[132:135], v[226:229], v[12:15]
	v_mfma_f32_16x16x32_bf16 v[8:11], v[156:159], v[226:229], v[8:11]
	s_setprio 0
	s_setprio 1
	v_mfma_f32_16x16x32_bf16 v[52:55], v[182:185], v[198:201], v[52:55]
	v_mfma_f32_16x16x32_bf16 v[48:51], v[190:193], v[198:201], v[48:51]
	v_mfma_f32_16x16x32_bf16 v[36:39], v[182:185], v[206:209], v[36:39]
	v_mfma_f32_16x16x32_bf16 v[32:35], v[190:193], v[206:209], v[32:35]
	v_mfma_f32_16x16x32_bf16 v[20:23], v[182:185], v[214:217], v[20:23]
	v_mfma_f32_16x16x32_bf16 v[16:19], v[190:193], v[214:217], v[16:19]
	v_mfma_f32_16x16x32_bf16 v[4:7], v[182:185], v[222:225], v[4:7]
	v_mfma_f32_16x16x32_bf16 v[0:3], v[190:193], v[222:225], v[0:3]
	v_mfma_f32_16x16x32_bf16 v[52:55], v[186:189], v[202:205], v[52:55]
	v_mfma_f32_16x16x32_bf16 v[48:51], v[194:197], v[202:205], v[48:51]
	v_mfma_f32_16x16x32_bf16 v[36:39], v[186:189], v[210:213], v[36:39]
	v_mfma_f32_16x16x32_bf16 v[32:35], v[194:197], v[210:213], v[32:35]
	v_mfma_f32_16x16x32_bf16 v[20:23], v[186:189], v[218:221], v[20:23]
	v_mfma_f32_16x16x32_bf16 v[16:19], v[194:197], v[218:221], v[16:19]
	v_mfma_f32_16x16x32_bf16 v[4:7], v[186:189], v[226:229], v[4:7]
	v_mfma_f32_16x16x32_bf16 v[0:3], v[194:197], v[226:229], v[0:3]
	s_barrier
	s_setprio 0
	s_add_i32 s65, s65, 2
	s_add_u32 s63, s63, 0x100
	s_addc_u32 s64, s64, 0
	s_add_u32 s12, s12, 0x100
	s_addc_u32 s13, s13, 0
	s_cmp_gt_u32 s65, 13
	s_cbranch_scc0 .LBB0_533
	s_and_b64 vcc, exec, s[22:23]
	s_cbranch_vccz .LBB0_536
	s_barrier

; #define PG8_STAGE(bufoff, gbase, voff) do { _Pragma("unroll") for (int _i = 0; _i < 2; ++_i) \
;         __builtin_amdgcn_global_load_lds((const unsigned*)((const char*)(gbase) + (voff)[_i]), (PG8_LAS unsigned*)(lds + (bufoff) + ldsw + _i * 8192), 16, 0, 0); } while (0)
; #define PG8_LDA(dst, b, h) do { _Pragma("unroll") for (int m = 0; m < 4; ++m) _Pragma("unroll") for (int k = 0; k < 2; ++k) dst[m][k] = *(const PG8_LAS bf16x8*)(lds + PG8_SA(b, h) + aoff + m * 2048 + k * 1024); } while (0)
; #define PG8_LDB(dst, b, h) do { _Pragma("unroll") for (int n = 0; n < 2; ++n) _Pragma("unroll") for (int k = 0; k < 2; ++k) dst[n][k] = *(const PG8_LAS bf16x8*)(lds + PG8_SB(b, h) + boff + n * 2048 + k * 1024); } while (0)
; #define PG8_MMA(ai, bj, At, Bt) do { __builtin_amdgcn_s_setprio(1); _Pragma("unroll") for (int m = 0; m < 4; ++m) _Pragma("unroll") for (int n = 0; n < 2; ++n) _Pragma("unroll") for (int k = 0; k < 2; ++k) \
;         acc[ai][bj][m][n] = __builtin_amdgcn_mfma_f32_16x16x32_bf16(Bt[n][k], At[m][k], acc[ai][bj][m][n], 0, 0, 0); __builtin_amdgcn_s_setprio(0); } while (0)
; #define PG8_WAIT_V(n) asm volatile("s_waitcnt vmcnt(" #n ")" ::: "memory")
; #define PG8_WAIT_L(n) asm volatile("s_waitcnt lgkmcnt(" #n ")" ::: "memory")
; #define PG8_BAR __builtin_amdgcn_s_barrier()
; #define PG8_SCHED __builtin_amdgcn_sched_barrier(0)
; template <class Epi, class Sched, bool ALIGN_EPI = false, bool SP2 = false>
; __device__ __forceinline__ void gemm_phase(PG8_LAS unsigned char* lds, const Gemm g, const Sched& S, const Epi& E, const int tid_arg) {
;     ...
;             PG8_LDB(B0, 0, 0); PG8_LDB(B1, 0, 1); PG8_SCHED; PG8_LDA(At, 0, 0); PG8_STAGE(PG8_SA(1, 1), a1 + hstep, voffA);
;             PG8_WAIT_V(8); PG8_WAIT_L(0); PG8_BAR; PG8_MMA(0, 0, At, B0); PG8_MMA(0, 1, At, B1); PG8_BAR; PG8_SCHED;
;             PG8_LDA(At, 0, 1); PG8_STAGE(PG8_SB(0, 0), b2, voffB); PG8_STAGE(PG8_SB(0, 1), b2 + hstep, voffB); PG8_STAGE(PG8_SA(0, 0), a2, voffA);
;             PG8_WAIT_V(8); PG8_WAIT_L(0); PG8_BAR; PG8_MMA(1, 0, At, B0); PG8_MMA(1, 1, At, B1); PG8_BAR; PG8_SCHED;
.LBB0_685:
	ds_read_b128 v[72:75], v207
	ds_read_b128 v[100:103], v208
	ds_read_b128 v[136:139], v209
	ds_read_b128 v[140:143], v210
	ds_read_b128 v[144:147], v211
	ds_read_b128 v[148:151], v212
	ds_read_b128 v[152:155], v213
	ds_read_b128 v[156:159], v214
	s_add_u32 s10, s4, 0x100
	s_addc_u32 s11, s5, 0
	s_cmp_eq_u32 s79, 12
	s_cselect_b32 s15, s17, s11
	s_cselect_b32 s14, s37, s10
	s_cselect_b32 s1, s35, s78
	s_cselect_b32 s0, s46, s47
	s_mov_b32 m0, s72
	v_lshl_add_u64 v[184:185], s[4:5], 0, v[196:197]
	ds_read_b128 v[160:163], v206
	ds_read_b128 v[164:167], v206 offset:1024
	ds_read_b128 v[168:171], v206 offset:2048
	ds_read_b128 v[172:175], v206 offset:3072
	ds_read_b128 v[176:179], v206 offset:4096
	ds_read_b128 v[180:183], v206 offset:5120
	ds_read_b128 v[226:229], v206 offset:6144
	ds_read_b128 v[230:233], v206 offset:7168
	global_load_lds_dwordx4 v[184:185], off
	v_lshl_add_u64 v[184:185], s[4:5], 0, v[194:195]
	s_mov_b32 m0, s73
	s_nop 0
	global_load_lds_dwordx4 v[184:185], off
	s_waitcnt vmcnt(8)
	s_waitcnt lgkmcnt(0)
	s_setprio 1
	s_barrier
	v_mfma_f32_16x16x32_bf16 v[132:135], v[72:75], v[160:163], v[132:135]
	v_mfma_f32_16x16x32_bf16 v[60:63], v[136:139], v[160:163], v[60:63]
	v_mfma_f32_16x16x32_bf16 v[124:127], v[72:75], v[168:171], v[124:127]
	v_mfma_f32_16x16x32_bf16 v[52:55], v[136:139], v[168:171], v[52:55]
	v_mfma_f32_16x16x32_bf16 v[116:119], v[72:75], v[176:179], v[116:119]
	v_mfma_f32_16x16x32_bf16 v[44:47], v[136:139], v[176:179], v[44:47]
	v_mfma_f32_16x16x32_bf16 v[108:111], v[72:75], v[226:229], v[108:111]
	v_mfma_f32_16x16x32_bf16 v[36:39], v[136:139], v[226:229], v[36:39]
	v_mfma_f32_16x16x32_bf16 v[132:135], v[100:103], v[164:167], v[132:135]
	v_mfma_f32_16x16x32_bf16 v[60:63], v[140:143], v[164:167], v[60:63]
	v_mfma_f32_16x16x32_bf16 v[124:127], v[100:103], v[172:175], v[124:127]
	v_mfma_f32_16x16x32_bf16 v[52:55], v[140:143], v[172:175], v[52:55]
	v_mfma_f32_16x16x32_bf16 v[116:119], v[100:103], v[180:183], v[116:119]
	v_mfma_f32_16x16x32_bf16 v[44:47], v[140:143], v[180:183], v[44:47]
	v_mfma_f32_16x16x32_bf16 v[108:111], v[100:103], v[230:233], v[108:111]
	v_mfma_f32_16x16x32_bf16 v[36:39], v[140:143], v[230:233], v[36:39]
	s_setprio 0
	s_setprio 1
	v_mfma_f32_16x16x32_bf16 v[128:131], v[144:147], v[160:163], v[128:131]
	v_mfma_f32_16x16x32_bf16 v[56:59], v[152:155], v[160:163], v[56:59]
	v_mfma_f32_16x16x32_bf16 v[120:123], v[144:147], v[168:171], v[120:123]
	v_mfma_f32_16x16x32_bf16 v[48:51], v[152:155], v[168:171], v[48:51]
	v_mfma_f32_16x16x32_bf16 v[112:115], v[144:147], v[176:179], v[112:115]
	v_mfma_f32_16x16x32_bf16 v[40:43], v[152:155], v[176:179], v[40:43]
	v_mfma_f32_16x16x32_bf16 v[104:107], v[144:147], v[226:229], v[104:107]
	v_mfma_f32_16x16x32_bf16 v[32:35], v[152:155], v[226:229], v[32:35]
	v_mfma_f32_16x16x32_bf16 v[128:131], v[148:151], v[164:167], v[128:131]
	v_mfma_f32_16x16x32_bf16 v[56:59], v[156:159], v[164:167], v[56:59]
	v_mfma_f32_16x16x32_bf16 v[120:123], v[148:151], v[172:175], v[120:123]
	v_mfma_f32_16x16x32_bf16 v[48:51], v[156:159], v[172:175], v[48:51]
	v_mfma_f32_16x16x32_bf16 v[112:115], v[148:151], v[180:183], v[112:115]
	v_mfma_f32_16x16x32_bf16 v[40:43], v[156:159], v[180:183], v[40:43]
	v_mfma_f32_16x16x32_bf16 v[104:107], v[148:151], v[230:233], v[104:107]
	v_mfma_f32_16x16x32_bf16 v[32:35], v[156:159], v[230:233], v[32:35]
	s_barrier
	s_setprio 0
	s_mov_b32 m0, s43
	v_lshl_add_u64 v[184:185], s[0:1], 0, v[188:189]
	s_add_u32 s4, s0, 0x40000
	ds_read_b128 v[160:163], v206 offset:16384
	ds_read_b128 v[164:167], v206 offset:17408
	ds_read_b128 v[168:171], v206 offset:18432
	ds_read_b128 v[172:175], v206 offset:19456
	ds_read_b128 v[176:179], v206 offset:20480
	ds_read_b128 v[180:183], v206 offset:21504
	ds_read_b128 v[226:229], v206 offset:22528
	ds_read_b128 v[230:233], v206 offset:23552
	global_load_lds_dwordx4 v[184:185], off
	v_lshl_add_u64 v[202:203], s[0:1], 0, v[192:193]
	s_mov_b32 m0, s45
	s_addc_u32 s5, s1, 0
	global_load_lds_dwordx4 v[202:203], off
	v_lshl_add_u64 v[234:235], s[4:5], 0, v[188:189]
	s_mov_b32 m0, s50
	v_lshl_add_u64 v[236:237], s[14:15], 0, v[190:191]
	global_load_lds_dwordx4 v[234:235], off
	v_lshl_add_u64 v[234:235], s[4:5], 0, v[192:193]
	s_mov_b32 m0, s51
	s_nop 0
	global_load_lds_dwordx4 v[234:235], off
	v_lshl_add_u64 v[234:235], s[14:15], 0, v[186:187]
	s_mov_b32 m0, s49
	s_nop 0
	global_load_lds_dwordx4 v[234:235], off
	s_mov_b32 m0, s52
	s_nop 0
	global_load_lds_dwordx4 v[236:237], off
	s_waitcnt vmcnt(8)
	s_waitcnt lgkmcnt(0)
	s_setprio 1
	s_barrier
; #define PG8_STAGE(bufoff, gbase, voff) do { _Pragma("unroll") for (int _i = 0; _i < 2; ++_i) \
;         __builtin_amdgcn_global_load_lds((const unsigned*)((const char*)(gbase) + (voff)[_i]), (PG8_LAS unsigned*)(lds + (bufoff) + ldsw + _i * 8192), 16, 0, 0); } while (0)
; #define PG8_LDA(dst, b, h) do { _Pragma("unroll") for (int m = 0; m < 4; ++m) _Pragma("unroll") for (int k = 0; k < 2; ++k) dst[m][k] = *(const PG8_LAS bf16x8*)(lds + PG8_SA(b, h) + aoff + m * 2048 + k * 1024); } while (0)
; #define PG8_LDB(dst, b, h) do { _Pragma("unroll") for (int n = 0; n < 2; ++n) _Pragma("unroll") for (int k = 0; k < 2; ++k) dst[n][k] = *(const PG8_LAS bf16x8*)(lds + PG8_SB(b, h) + boff + n * 2048 + k * 1024); } while (0)
; #define PG8_MMA(ai, bj, At, Bt) do { __builtin_amdgcn_s_setprio(1); _Pragma("unroll") for (int m = 0; m < 4; ++m) _Pragma("unroll") for (int n = 0; n < 2; ++n) _Pragma("unroll") for (int k = 0; k < 2; ++k) \
;         acc[ai][bj][m][n] = __builtin_amdgcn_mfma_f32_16x16x32_bf16(Bt[n][k], At[m][k], acc[ai][bj][m][n], 0, 0, 0); __builtin_amdgcn_s_setprio(0); } while (0)
; #define PG8_WAIT_V(n) asm volatile("s_waitcnt vmcnt(" #n ")" ::: "memory")
; #define PG8_WAIT_L(n) asm volatile("s_waitcnt lgkmcnt(" #n ")" ::: "memory")
; #define PG8_BAR __builtin_amdgcn_s_barrier()
; #define PG8_SCHED __builtin_amdgcn_sched_barrier(0)
; template <class Epi, class Sched, bool ALIGN_EPI = false, bool SP2 = false>
; __device__ __forceinline__ void gemm_phase(PG8_LAS unsigned char* lds, const Gemm g, const Sched& S, const Epi& E, const int tid_arg) {
;     ...
;             PG8_WAIT_V(8); PG8_WAIT_L(0); PG8_BAR; PG8_MMA(1, 0, At, B0); PG8_MMA(1, 1, At, B1); PG8_BAR; PG8_SCHED;
;             PG8_LDB(B0, 1, 0); PG8_LDB(B1, 1, 1); PG8_SCHED; PG8_LDA(At, 1, 0); PG8_STAGE(PG8_SA(0, 1), a2 + hstep, voffA);
;             PG8_WAIT_V(8); PG8_WAIT_L(0); PG8_BAR; PG8_MMA(0, 0, At, B0); PG8_MMA(0, 1, At, B1); PG8_BAR; PG8_SCHED;
	v_mfma_f32_16x16x32_bf16 v[96:99], v[72:75], v[160:163], v[96:99]
	v_mfma_f32_16x16x32_bf16 v[28:31], v[136:139], v[160:163], v[28:31]
	v_mfma_f32_16x16x32_bf16 v[88:91], v[72:75], v[168:171], v[88:91]
	v_mfma_f32_16x16x32_bf16 v[20:23], v[136:139], v[168:171], v[20:23]
	v_mfma_f32_16x16x32_bf16 v[80:83], v[72:75], v[176:179], v[80:83]
	v_mfma_f32_16x16x32_bf16 v[12:15], v[136:139], v[176:179], v[12:15]
	v_mfma_f32_16x16x32_bf16 v[68:71], v[72:75], v[226:229], v[68:71]
	v_mfma_f32_16x16x32_bf16 v[4:7], v[136:139], v[226:229], v[4:7]
	v_mfma_f32_16x16x32_bf16 v[96:99], v[100:103], v[164:167], v[96:99]
	v_mfma_f32_16x16x32_bf16 v[28:31], v[140:143], v[164:167], v[28:31]
	v_mfma_f32_16x16x32_bf16 v[88:91], v[100:103], v[172:175], v[88:91]
	v_mfma_f32_16x16x32_bf16 v[20:23], v[140:143], v[172:175], v[20:23]
	v_mfma_f32_16x16x32_bf16 v[80:83], v[100:103], v[180:183], v[80:83]
	v_mfma_f32_16x16x32_bf16 v[12:15], v[140:143], v[180:183], v[12:15]
	v_mfma_f32_16x16x32_bf16 v[68:71], v[100:103], v[230:233], v[68:71]
	v_mfma_f32_16x16x32_bf16 v[4:7], v[140:143], v[230:233], v[4:7]
	s_setprio 0
	s_setprio 1
	v_mfma_f32_16x16x32_bf16 v[24:27], v[152:155], v[160:163], v[24:27]
	v_mfma_f32_16x16x32_bf16 v[84:87], v[144:147], v[168:171], v[84:87]
	v_mfma_f32_16x16x32_bf16 v[16:19], v[152:155], v[168:171], v[16:19]
	v_mfma_f32_16x16x32_bf16 v[76:79], v[144:147], v[176:179], v[76:79]
	v_mfma_f32_16x16x32_bf16 v[8:11], v[152:155], v[176:179], v[8:11]
	v_mfma_f32_16x16x32_bf16 v[64:67], v[144:147], v[226:229], v[64:67]
	v_mfma_f32_16x16x32_bf16 v[0:3], v[152:155], v[226:229], v[0:3]
	v_mfma_f32_16x16x32_bf16 v[72:75], v[144:147], v[160:163], v[92:95]
	v_mfma_f32_16x16x32_bf16 v[24:27], v[156:159], v[164:167], v[24:27]
	v_mfma_f32_16x16x32_bf16 v[84:87], v[148:151], v[172:175], v[84:87]
	v_mfma_f32_16x16x32_bf16 v[16:19], v[156:159], v[172:175], v[16:19]
	v_mfma_f32_16x16x32_bf16 v[76:79], v[148:151], v[180:183], v[76:79]
	v_mfma_f32_16x16x32_bf16 v[8:11], v[156:159], v[180:183], v[8:11]
	v_mfma_f32_16x16x32_bf16 v[64:67], v[148:151], v[230:233], v[64:67]
	v_mfma_f32_16x16x32_bf16 v[0:3], v[156:159], v[230:233], v[0:3]
	v_mfma_f32_16x16x32_bf16 v[72:75], v[148:151], v[164:167], v[72:75]
	s_barrier
	s_setprio 0
	ds_read_b128 v[92:95], v215
	ds_read_b128 v[100:103], v216
	ds_read_b128 v[136:139], v217
	ds_read_b128 v[140:143], v218
	ds_read_b128 v[144:147], v219
	ds_read_b128 v[148:151], v220
	ds_read_b128 v[152:155], v221
	ds_read_b128 v[156:159], v222
	s_add_u32 s4, s14, 0x40000
	s_addc_u32 s5, s15, 0
	s_mov_b32 m0, s53
	v_lshl_add_u64 v[238:239], s[4:5], 0, v[186:187]
	ds_read_b128 v[160:163], v206 offset:32768
	ds_read_b128 v[164:167], v206 offset:33792
	ds_read_b128 v[168:171], v206 offset:34816
	ds_read_b128 v[172:175], v206 offset:35840
	ds_read_b128 v[176:179], v206 offset:36864
	ds_read_b128 v[180:183], v206 offset:37888
	ds_read_b128 v[226:229], v206 offset:38912
	ds_read_b128 v[230:233], v206 offset:39936
	global_load_lds_dwordx4 v[238:239], off
	v_lshl_add_u64 v[238:239], s[4:5], 0, v[190:191]
	s_mov_b32 m0, s54
	s_nop 0
	global_load_lds_dwordx4 v[238:239], off
	s_waitcnt vmcnt(8)
	s_waitcnt lgkmcnt(0)
	s_setprio 1
	s_barrier
	v_mfma_f32_16x16x32_bf16 v[132:135], v[92:95], v[160:163], v[132:135]
	v_mfma_f32_16x16x32_bf16 v[60:63], v[136:139], v[160:163], v[60:63]
	v_mfma_f32_16x16x32_bf16 v[124:127], v[92:95], v[168:171], v[124:127]
	v_mfma_f32_16x16x32_bf16 v[52:55], v[136:139], v[168:171], v[52:55]
	v_mfma_f32_16x16x32_bf16 v[116:119], v[92:95], v[176:179], v[116:119]
	v_mfma_f32_16x16x32_bf16 v[44:47], v[136:139], v[176:179], v[44:47]
	v_mfma_f32_16x16x32_bf16 v[108:111], v[92:95], v[226:229], v[108:111]
	v_mfma_f32_16x16x32_bf16 v[36:39], v[136:139], v[226:229], v[36:39]
	v_mfma_f32_16x16x32_bf16 v[132:135], v[100:103], v[164:167], v[132:135]
	v_mfma_f32_16x16x32_bf16 v[60:63], v[140:143], v[164:167], v[60:63]
	v_mfma_f32_16x16x32_bf16 v[124:127], v[100:103], v[172:175], v[124:127]
	v_mfma_f32_16x16x32_bf16 v[52:55], v[140:143], v[172:175], v[52:55]
	v_mfma_f32_16x16x32_bf16 v[116:119], v[100:103], v[180:183], v[116:119]
	v_mfma_f32_16x16x32_bf16 v[44:47], v[140:143], v[180:183], v[44:47]
	v_mfma_f32_16x16x32_bf16 v[108:111], v[100:103], v[230:233], v[108:111]
	v_mfma_f32_16x16x32_bf16 v[36:39], v[140:143], v[230:233], v[36:39]
	s_setprio 0
	s_setprio 1
	v_mfma_f32_16x16x32_bf16 v[128:131], v[144:147], v[160:163], v[128:131]
	v_mfma_f32_16x16x32_bf16 v[56:59], v[152:155], v[160:163], v[56:59]
	v_mfma_f32_16x16x32_bf16 v[120:123], v[144:147], v[168:171], v[120:123]
	v_mfma_f32_16x16x32_bf16 v[48:51], v[152:155], v[168:171], v[48:51]
	v_mfma_f32_16x16x32_bf16 v[112:115], v[144:147], v[176:179], v[112:115]
	v_mfma_f32_16x16x32_bf16 v[40:43], v[152:155], v[176:179], v[40:43]
	v_mfma_f32_16x16x32_bf16 v[104:107], v[144:147], v[226:229], v[104:107]
	v_mfma_f32_16x16x32_bf16 v[32:35], v[152:155], v[226:229], v[32:35]
	v_mfma_f32_16x16x32_bf16 v[128:131], v[148:151], v[164:167], v[128:131]
	v_mfma_f32_16x16x32_bf16 v[56:59], v[156:159], v[164:167], v[56:59]
	v_mfma_f32_16x16x32_bf16 v[120:123], v[148:151], v[172:175], v[120:123]
	v_mfma_f32_16x16x32_bf16 v[48:51], v[156:159], v[172:175], v[48:51]
	v_mfma_f32_16x16x32_bf16 v[112:115], v[148:151], v[180:183], v[112:115]
	v_mfma_f32_16x16x32_bf16 v[40:43], v[156:159], v[180:183], v[40:43]
	v_mfma_f32_16x16x32_bf16 v[104:107], v[148:151], v[230:233], v[104:107]
	v_mfma_f32_16x16x32_bf16 v[32:35], v[156:159], v[230:233], v[32:35]
	s_barrier
; #define PG8_STAGE(bufoff, gbase, voff) do { _Pragma("unroll") for (int _i = 0; _i < 2; ++_i) \
;         __builtin_amdgcn_global_load_lds((const unsigned*)((const char*)(gbase) + (voff)[_i]), (PG8_LAS unsigned*)(lds + (bufoff) + ldsw + _i * 8192), 16, 0, 0); } while (0)
; #define PG8_LDA(dst, b, h) do { _Pragma("unroll") for (int m = 0; m < 4; ++m) _Pragma("unroll") for (int k = 0; k < 2; ++k) dst[m][k] = *(const PG8_LAS bf16x8*)(lds + PG8_SA(b, h) + aoff + m * 2048 + k * 1024); } while (0)
; #define PG8_MMA(ai, bj, At, Bt) do { __builtin_amdgcn_s_setprio(1); _Pragma("unroll") for (int m = 0; m < 4; ++m) _Pragma("unroll") for (int n = 0; n < 2; ++n) _Pragma("unroll") for (int k = 0; k < 2; ++k) \
;         acc[ai][bj][m][n] = __builtin_amdgcn_mfma_f32_16x16x32_bf16(Bt[n][k], At[m][k], acc[ai][bj][m][n], 0, 0, 0); __builtin_amdgcn_s_setprio(0); } while (0)
; #define PG8_WAIT_V(n) asm volatile("s_waitcnt vmcnt(" #n ")" ::: "memory")
; #define PG8_WAIT_L(n) asm volatile("s_waitcnt lgkmcnt(" #n ")" ::: "memory")
; #define PG8_BAR __builtin_amdgcn_s_barrier()
; #define PG8_SCHED __builtin_amdgcn_sched_barrier(0)
; template <class Epi, class Sched, bool ALIGN_EPI = false, bool SP2 = false>
; __device__ __forceinline__ void gemm_phase(PG8_LAS unsigned char* lds, const Gemm g, const Sched& S, const Epi& E, const int tid_arg) {
;     ...
;             PG8_WAIT_V(8); PG8_WAIT_L(0); PG8_BAR; PG8_MMA(0, 0, At, B0); PG8_MMA(0, 1, At, B1); PG8_BAR; PG8_SCHED;
;             PG8_LDA(At, 1, 1); PG8_STAGE(PG8_SB(1, 0), b3, voffB); PG8_STAGE(PG8_SB(1, 1), b3 + hstep, voffB); PG8_STAGE(PG8_SA(1, 0), a3, voffA);
;             PG8_WAIT_V(8); PG8_WAIT_L(0); PG8_BAR; PG8_MMA(1, 0, At, B0); PG8_MMA(1, 1, At, B1); PG8_BAR; PG8_SCHED;
	s_setprio 0
	s_mov_b32 m0, s59
	v_lshl_add_u64 v[184:185], v[184:185], 0, s[24:25]
	s_add_u32 s0, s0, 0x40080
	ds_read_b128 v[160:163], v206 offset:49152
	ds_read_b128 v[164:167], v206 offset:50176
	ds_read_b128 v[168:171], v206 offset:51200
	ds_read_b128 v[172:175], v206 offset:52224
	ds_read_b128 v[176:179], v206 offset:53248
	ds_read_b128 v[180:183], v206 offset:54272
	ds_read_b128 v[226:229], v206 offset:55296
	ds_read_b128 v[230:233], v206 offset:56320
	global_load_lds_dwordx4 v[184:185], off
	v_lshl_add_u64 v[184:185], v[202:203], 0, s[24:25]
	s_mov_b32 m0, s60
	s_addc_u32 s1, s1, 0
	global_load_lds_dwordx4 v[184:185], off
	v_lshl_add_u64 v[184:185], s[0:1], 0, v[188:189]
	s_mov_b32 m0, s63
	s_nop 0
	global_load_lds_dwordx4 v[184:185], off
	v_lshl_add_u64 v[184:185], s[0:1], 0, v[192:193]
	s_mov_b32 m0, s64
	s_nop 0
	global_load_lds_dwordx4 v[184:185], off
	v_lshl_add_u64 v[184:185], v[234:235], 0, s[24:25]
	s_mov_b32 m0, s61
	s_nop 0
	global_load_lds_dwordx4 v[184:185], off
	v_lshl_add_u64 v[184:185], v[236:237], 0, s[24:25]
	s_mov_b32 m0, s62
	s_nop 0
	global_load_lds_dwordx4 v[184:185], off
	s_waitcnt vmcnt(8)
	s_waitcnt lgkmcnt(0)
	s_setprio 1
	s_barrier
	v_mfma_f32_16x16x32_bf16 v[96:99], v[92:95], v[160:163], v[96:99]
	v_mfma_f32_16x16x32_bf16 v[28:31], v[136:139], v[160:163], v[28:31]
	v_mfma_f32_16x16x32_bf16 v[88:91], v[92:95], v[168:171], v[88:91]
	v_mfma_f32_16x16x32_bf16 v[20:23], v[136:139], v[168:171], v[20:23]
	v_mfma_f32_16x16x32_bf16 v[80:83], v[92:95], v[176:179], v[80:83]
	v_mfma_f32_16x16x32_bf16 v[12:15], v[136:139], v[176:179], v[12:15]
	v_mfma_f32_16x16x32_bf16 v[68:71], v[92:95], v[226:229], v[68:71]
	v_mfma_f32_16x16x32_bf16 v[4:7], v[136:139], v[226:229], v[4:7]
	v_mfma_f32_16x16x32_bf16 v[96:99], v[100:103], v[164:167], v[96:99]
	v_mfma_f32_16x16x32_bf16 v[28:31], v[140:143], v[164:167], v[28:31]
	v_mfma_f32_16x16x32_bf16 v[88:91], v[100:103], v[172:175], v[88:91]
	v_mfma_f32_16x16x32_bf16 v[20:23], v[140:143], v[172:175], v[20:23]
	v_mfma_f32_16x16x32_bf16 v[80:83], v[100:103], v[180:183], v[80:83]
	v_mfma_f32_16x16x32_bf16 v[12:15], v[140:143], v[180:183], v[12:15]
	v_mfma_f32_16x16x32_bf16 v[68:71], v[100:103], v[230:233], v[68:71]
	v_mfma_f32_16x16x32_bf16 v[4:7], v[140:143], v[230:233], v[4:7]
	s_setprio 0
	s_setprio 1
	v_mfma_f32_16x16x32_bf16 v[72:75], v[144:147], v[160:163], v[72:75]
	v_mfma_f32_16x16x32_bf16 v[92:95], v[148:151], v[164:167], v[72:75]
	v_mfma_f32_16x16x32_bf16 v[72:75], v[144:147], v[168:171], v[84:87]
	v_mfma_f32_16x16x32_bf16 v[24:27], v[152:155], v[160:163], v[24:27]
	v_mfma_f32_16x16x32_bf16 v[84:87], v[148:151], v[172:175], v[72:75]
	v_mfma_f32_16x16x32_bf16 v[16:19], v[152:155], v[168:171], v[16:19]
	v_mfma_f32_16x16x32_bf16 v[72:75], v[144:147], v[176:179], v[76:79]
	v_mfma_f32_16x16x32_bf16 v[8:11], v[152:155], v[176:179], v[8:11]
	v_mfma_f32_16x16x32_bf16 v[64:67], v[144:147], v[226:229], v[64:67]
	v_mfma_f32_16x16x32_bf16 v[0:3], v[152:155], v[226:229], v[0:3]
	v_mfma_f32_16x16x32_bf16 v[24:27], v[156:159], v[164:167], v[24:27]
	v_mfma_f32_16x16x32_bf16 v[16:19], v[156:159], v[172:175], v[16:19]
	v_mfma_f32_16x16x32_bf16 v[76:79], v[148:151], v[180:183], v[72:75]
	v_mfma_f32_16x16x32_bf16 v[8:11], v[156:159], v[180:183], v[8:11]
	v_mfma_f32_16x16x32_bf16 v[64:67], v[148:151], v[230:233], v[64:67]
	v_mfma_f32_16x16x32_bf16 v[0:3], v[156:159], v[230:233], v[0:3]
	s_barrier
	s_setprio 0
	s_add_i32 s79, s79, 2
	s_add_u32 s47, s47, 0x100
	s_addc_u32 s78, s78, 0
	s_cmp_gt_u32 s79, 13
	s_mov_b64 s[4:5], s[10:11]
	s_cbranch_scc0 .LBB0_685
	s_and_b64 vcc, exec, s[26:27]
	s_cbranch_vccz .LBB0_688
	s_barrier

; #define PG8_STAGE(bufoff, gbase, voff) do { _Pragma("unroll") for (int _i = 0; _i < 2; ++_i) \
;         __builtin_amdgcn_global_load_lds((const unsigned*)((const char*)(gbase) + (voff)[_i]), (PG8_LAS unsigned*)(lds + (bufoff) + ldsw + _i * 8192), 16, 0, 0); } while (0)
; #define PG8_LDA(dst, b, h) do { _Pragma("unroll") for (int m = 0; m < 4; ++m) _Pragma("unroll") for (int k = 0; k < 2; ++k) dst[m][k] = *(const PG8_LAS bf16x8*)(lds + PG8_SA(b, h) + aoff + m * 2048 + k * 1024); } while (0)
; #define PG8_LDB(dst, b, h) do { _Pragma("unroll") for (int n = 0; n < 2; ++n) _Pragma("unroll") for (int k = 0; k < 2; ++k) dst[n][k] = *(const PG8_LAS bf16x8*)(lds + PG8_SB(b, h) + boff + n * 2048 + k * 1024); } while (0)
; #define PG8_MMA(ai, bj, At, Bt) do { __builtin_amdgcn_s_setprio(1); _Pragma("unroll") for (int m = 0; m < 4; ++m) _Pragma("unroll") for (int n = 0; n < 2; ++n) _Pragma("unroll") for (int k = 0; k < 2; ++k) \
;         acc[ai][bj][m][n] = __builtin_amdgcn_mfma_f32_16x16x32_bf16(Bt[n][k], At[m][k], acc[ai][bj][m][n], 0, 0, 0); __builtin_amdgcn_s_setprio(0); } while (0)
; #define PG8_WAIT_V(n) asm volatile("s_waitcnt vmcnt(" #n ")" ::: "memory")
; #define PG8_WAIT_L(n) asm volatile("s_waitcnt lgkmcnt(" #n ")" ::: "memory")
; #define PG8_BAR __builtin_amdgcn_s_barrier()
; #define PG8_SCHED __builtin_amdgcn_sched_barrier(0)
; template <class Epi, class Sched, bool ALIGN_EPI = false, bool SP2 = false>
; __device__ __forceinline__ void gemm_phase(PG8_LAS unsigned char* lds, const Gemm g, const Sched& S, const Epi& E, const int tid_arg) {
;     ...
;             PG8_LDB(B0, 0, 0); PG8_LDB(B1, 0, 1); PG8_SCHED; PG8_LDA(At, 0, 0); PG8_STAGE(PG8_SA(1, 1), a1 + hstep, voffA);
;             PG8_WAIT_V(8); PG8_WAIT_L(0); PG8_BAR; PG8_MMA(0, 0, At, B0); PG8_MMA(0, 1, At, B1); PG8_BAR; PG8_SCHED;
;             PG8_LDA(At, 0, 1); PG8_STAGE(PG8_SB(0, 0), b2, voffB); PG8_STAGE(PG8_SB(0, 1), b2 + hstep, voffB); PG8_STAGE(PG8_SA(0, 0), a2, voffA);
;             PG8_WAIT_V(8); PG8_WAIT_L(0); PG8_BAR; PG8_MMA(1, 0, At, B0); PG8_MMA(1, 1, At, B1); PG8_BAR; PG8_SCHED;
.LBB0_871:
	ds_read_b128 v[144:147], v151
	ds_read_b128 v[168:171], v152
	ds_read_b128 v[172:175], v153
	ds_read_b128 v[176:179], v154
	ds_read_b128 v[180:183], v155
	ds_read_b128 v[184:187], v156
	ds_read_b128 v[188:191], v157
	ds_read_b128 v[192:195], v158
	s_add_u32 s22, s4, 0x100
	s_addc_u32 s23, s5, 0
	s_cmp_eq_u32 s57, 40
	s_cselect_b32 s25, s13, s23
	s_cselect_b32 s24, s12, s22
	s_cselect_b32 s1, s21, s56
	s_cselect_b32 s0, s20, s55
	s_mov_b32 m0, s48
	v_lshl_add_u64 v[228:229], s[4:5], 0, v[138:139]
	ds_read_b128 v[196:199], v150
	ds_read_b128 v[200:203], v150 offset:1024
	ds_read_b128 v[204:207], v150 offset:2048
	ds_read_b128 v[208:211], v150 offset:3072
	ds_read_b128 v[212:215], v150 offset:4096
	ds_read_b128 v[216:219], v150 offset:5120
	ds_read_b128 v[220:223], v150 offset:6144
	ds_read_b128 v[224:227], v150 offset:7168
	global_load_lds_dwordx4 v[228:229], off
	v_lshl_add_u64 v[228:229], s[4:5], 0, v[136:137]
	s_mov_b32 m0, s49
	s_nop 0
	global_load_lds_dwordx4 v[228:229], off
	s_waitcnt vmcnt(8)
	s_waitcnt lgkmcnt(0)
	s_setprio 1
	s_barrier
	v_mfma_f32_16x16x32_bf16 v[124:127], v[144:147], v[196:199], v[124:127]
	v_mfma_f32_16x16x32_bf16 v[120:123], v[172:175], v[196:199], v[120:123]
	v_mfma_f32_16x16x32_bf16 v[108:111], v[144:147], v[204:207], v[108:111]
	v_mfma_f32_16x16x32_bf16 v[104:107], v[172:175], v[204:207], v[104:107]
	v_mfma_f32_16x16x32_bf16 v[92:95], v[144:147], v[212:215], v[92:95]
	v_mfma_f32_16x16x32_bf16 v[88:91], v[172:175], v[212:215], v[88:91]
	v_mfma_f32_16x16x32_bf16 v[76:79], v[144:147], v[220:223], v[76:79]
	v_mfma_f32_16x16x32_bf16 v[72:75], v[172:175], v[220:223], v[72:75]
	v_mfma_f32_16x16x32_bf16 v[124:127], v[168:171], v[200:203], v[124:127]
	v_mfma_f32_16x16x32_bf16 v[120:123], v[176:179], v[200:203], v[120:123]
	v_mfma_f32_16x16x32_bf16 v[108:111], v[168:171], v[208:211], v[108:111]
	v_mfma_f32_16x16x32_bf16 v[104:107], v[176:179], v[208:211], v[104:107]
	v_mfma_f32_16x16x32_bf16 v[92:95], v[168:171], v[216:219], v[92:95]
	v_mfma_f32_16x16x32_bf16 v[88:91], v[176:179], v[216:219], v[88:91]
	v_mfma_f32_16x16x32_bf16 v[76:79], v[168:171], v[224:227], v[76:79]
	v_mfma_f32_16x16x32_bf16 v[72:75], v[176:179], v[224:227], v[72:75]
	s_setprio 0
	s_setprio 1
	v_mfma_f32_16x16x32_bf16 v[116:119], v[180:183], v[196:199], v[116:119]
	v_mfma_f32_16x16x32_bf16 v[112:115], v[188:191], v[196:199], v[112:115]
	v_mfma_f32_16x16x32_bf16 v[100:103], v[180:183], v[204:207], v[100:103]
	v_mfma_f32_16x16x32_bf16 v[96:99], v[188:191], v[204:207], v[96:99]
	v_mfma_f32_16x16x32_bf16 v[84:87], v[180:183], v[212:215], v[84:87]
	v_mfma_f32_16x16x32_bf16 v[80:83], v[188:191], v[212:215], v[80:83]
	v_mfma_f32_16x16x32_bf16 v[68:71], v[180:183], v[220:223], v[68:71]
	v_mfma_f32_16x16x32_bf16 v[64:67], v[188:191], v[220:223], v[64:67]
	v_mfma_f32_16x16x32_bf16 v[116:119], v[184:187], v[200:203], v[116:119]
	v_mfma_f32_16x16x32_bf16 v[112:115], v[192:195], v[200:203], v[112:115]
	v_mfma_f32_16x16x32_bf16 v[100:103], v[184:187], v[208:211], v[100:103]
	v_mfma_f32_16x16x32_bf16 v[96:99], v[192:195], v[208:211], v[96:99]
	v_mfma_f32_16x16x32_bf16 v[84:87], v[184:187], v[216:219], v[84:87]
	v_mfma_f32_16x16x32_bf16 v[80:83], v[192:195], v[216:219], v[80:83]
	v_mfma_f32_16x16x32_bf16 v[68:71], v[184:187], v[224:227], v[68:71]
	v_mfma_f32_16x16x32_bf16 v[64:67], v[192:195], v[224:227], v[64:67]
	s_barrier
	s_setprio 0
	s_mov_b32 m0, s29
	v_lshl_add_u64 v[228:229], s[0:1], 0, v[130:131]
	s_add_u32 s4, s0, 0xb0000
	ds_read_b128 v[196:199], v150 offset:16384
	ds_read_b128 v[200:203], v150 offset:17408
	ds_read_b128 v[204:207], v150 offset:18432
	ds_read_b128 v[208:211], v150 offset:19456
	ds_read_b128 v[212:215], v150 offset:20480
	ds_read_b128 v[216:219], v150 offset:21504
	ds_read_b128 v[220:223], v150 offset:22528
	ds_read_b128 v[224:227], v150 offset:23552
	global_load_lds_dwordx4 v[228:229], off
	v_lshl_add_u64 v[230:231], s[0:1], 0, v[134:135]
	s_mov_b32 m0, s30
	s_addc_u32 s5, s1, 0
	global_load_lds_dwordx4 v[230:231], off
	v_lshl_add_u64 v[232:233], s[4:5], 0, v[130:131]
	s_mov_b32 m0, s31
	v_lshl_add_u64 v[234:235], s[24:25], 0, v[132:133]
	global_load_lds_dwordx4 v[232:233], off
	v_lshl_add_u64 v[232:233], s[4:5], 0, v[134:135]
	s_mov_b32 m0, s33
	s_nop 0
	global_load_lds_dwordx4 v[232:233], off
	v_lshl_add_u64 v[232:233], s[24:25], 0, v[128:129]
	s_mov_b32 m0, s28
	s_nop 0
	global_load_lds_dwordx4 v[232:233], off
	s_mov_b32 m0, s34
	s_nop 0
	global_load_lds_dwordx4 v[234:235], off
	s_waitcnt vmcnt(8)
	s_waitcnt lgkmcnt(0)
	s_setprio 1
	s_barrier
; #define PG8_STAGE(bufoff, gbase, voff) do { _Pragma("unroll") for (int _i = 0; _i < 2; ++_i) \
;         __builtin_amdgcn_global_load_lds((const unsigned*)((const char*)(gbase) + (voff)[_i]), (PG8_LAS unsigned*)(lds + (bufoff) + ldsw + _i * 8192), 16, 0, 0); } while (0)
; #define PG8_LDA(dst, b, h) do { _Pragma("unroll") for (int m = 0; m < 4; ++m) _Pragma("unroll") for (int k = 0; k < 2; ++k) dst[m][k] = *(const PG8_LAS bf16x8*)(lds + PG8_SA(b, h) + aoff + m * 2048 + k * 1024); } while (0)
; #define PG8_LDB(dst, b, h) do { _Pragma("unroll") for (int n = 0; n < 2; ++n) _Pragma("unroll") for (int k = 0; k < 2; ++k) dst[n][k] = *(const PG8_LAS bf16x8*)(lds + PG8_SB(b, h) + boff + n * 2048 + k * 1024); } while (0)
; #define PG8_MMA(ai, bj, At, Bt) do { __builtin_amdgcn_s_setprio(1); _Pragma("unroll") for (int m = 0; m < 4; ++m) _Pragma("unroll") for (int n = 0; n < 2; ++n) _Pragma("unroll") for (int k = 0; k < 2; ++k) \
;         acc[ai][bj][m][n] = __builtin_amdgcn_mfma_f32_16x16x32_bf16(Bt[n][k], At[m][k], acc[ai][bj][m][n], 0, 0, 0); __builtin_amdgcn_s_setprio(0); } while (0)
; #define PG8_WAIT_V(n) asm volatile("s_waitcnt vmcnt(" #n ")" ::: "memory")
; #define PG8_WAIT_L(n) asm volatile("s_waitcnt lgkmcnt(" #n ")" ::: "memory")
; #define PG8_BAR __builtin_amdgcn_s_barrier()
; #define PG8_SCHED __builtin_amdgcn_sched_barrier(0)
; template <class Epi, class Sched, bool ALIGN_EPI = false, bool SP2 = false>
; __device__ __forceinline__ void gemm_phase(PG8_LAS unsigned char* lds, const Gemm g, const Sched& S, const Epi& E, const int tid_arg) {
;     ...
;             PG8_WAIT_V(8); PG8_WAIT_L(0); PG8_BAR; PG8_MMA(1, 0, At, B0); PG8_MMA(1, 1, At, B1); PG8_BAR; PG8_SCHED;
;             PG8_LDB(B0, 1, 0); PG8_LDB(B1, 1, 1); PG8_SCHED; PG8_LDA(At, 1, 0); PG8_STAGE(PG8_SA(0, 1), a2 + hstep, voffA);
;             PG8_WAIT_V(8); PG8_WAIT_L(0); PG8_BAR; PG8_MMA(0, 0, At, B0); PG8_MMA(0, 1, At, B1); PG8_BAR; PG8_SCHED;
	v_mfma_f32_16x16x32_bf16 v[60:63], v[144:147], v[196:199], v[60:63]
	v_mfma_f32_16x16x32_bf16 v[56:59], v[172:175], v[196:199], v[56:59]
	v_mfma_f32_16x16x32_bf16 v[44:47], v[144:147], v[204:207], v[44:47]
	v_mfma_f32_16x16x32_bf16 v[40:43], v[172:175], v[204:207], v[40:43]
	v_mfma_f32_16x16x32_bf16 v[28:31], v[144:147], v[212:215], v[28:31]
	v_mfma_f32_16x16x32_bf16 v[24:27], v[172:175], v[212:215], v[24:27]
	v_mfma_f32_16x16x32_bf16 v[12:15], v[144:147], v[220:223], v[12:15]
	v_mfma_f32_16x16x32_bf16 v[8:11], v[172:175], v[220:223], v[8:11]
	v_mfma_f32_16x16x32_bf16 v[60:63], v[168:171], v[200:203], v[60:63]
	v_mfma_f32_16x16x32_bf16 v[56:59], v[176:179], v[200:203], v[56:59]
	v_mfma_f32_16x16x32_bf16 v[44:47], v[168:171], v[208:211], v[44:47]
	v_mfma_f32_16x16x32_bf16 v[40:43], v[176:179], v[208:211], v[40:43]
	v_mfma_f32_16x16x32_bf16 v[28:31], v[168:171], v[216:219], v[28:31]
	v_mfma_f32_16x16x32_bf16 v[24:27], v[176:179], v[216:219], v[24:27]
	v_mfma_f32_16x16x32_bf16 v[12:15], v[168:171], v[224:227], v[12:15]
	v_mfma_f32_16x16x32_bf16 v[8:11], v[176:179], v[224:227], v[8:11]
	s_setprio 0
	s_setprio 1
	v_mfma_f32_16x16x32_bf16 v[52:55], v[180:183], v[196:199], v[52:55]
	v_mfma_f32_16x16x32_bf16 v[48:51], v[188:191], v[196:199], v[48:51]
	v_mfma_f32_16x16x32_bf16 v[36:39], v[180:183], v[204:207], v[36:39]
	v_mfma_f32_16x16x32_bf16 v[32:35], v[188:191], v[204:207], v[32:35]
	v_mfma_f32_16x16x32_bf16 v[20:23], v[180:183], v[212:215], v[20:23]
	v_mfma_f32_16x16x32_bf16 v[16:19], v[188:191], v[212:215], v[16:19]
	v_mfma_f32_16x16x32_bf16 v[4:7], v[180:183], v[220:223], v[4:7]
	v_mfma_f32_16x16x32_bf16 v[0:3], v[188:191], v[220:223], v[0:3]
	v_mfma_f32_16x16x32_bf16 v[52:55], v[184:187], v[200:203], v[52:55]
	v_mfma_f32_16x16x32_bf16 v[48:51], v[192:195], v[200:203], v[48:51]
	v_mfma_f32_16x16x32_bf16 v[36:39], v[184:187], v[208:211], v[36:39]
	v_mfma_f32_16x16x32_bf16 v[32:35], v[192:195], v[208:211], v[32:35]
	v_mfma_f32_16x16x32_bf16 v[20:23], v[184:187], v[216:219], v[20:23]
	v_mfma_f32_16x16x32_bf16 v[16:19], v[192:195], v[216:219], v[16:19]
	v_mfma_f32_16x16x32_bf16 v[4:7], v[184:187], v[224:227], v[4:7]
	v_mfma_f32_16x16x32_bf16 v[0:3], v[192:195], v[224:227], v[0:3]
	s_barrier
	s_setprio 0
	ds_read_b128 v[144:147], v159
	ds_read_b128 v[168:171], v160
	ds_read_b128 v[172:175], v161
	ds_read_b128 v[176:179], v162
	ds_read_b128 v[180:183], v163
	ds_read_b128 v[184:187], v164
	ds_read_b128 v[188:191], v165
	ds_read_b128 v[192:195], v166
	s_add_u32 s4, s24, 0xb0000
	s_addc_u32 s5, s25, 0
	s_mov_b32 m0, s35
	v_lshl_add_u64 v[236:237], s[4:5], 0, v[128:129]
	ds_read_b128 v[196:199], v150 offset:32768
	ds_read_b128 v[200:203], v150 offset:33792
	ds_read_b128 v[204:207], v150 offset:34816
	ds_read_b128 v[208:211], v150 offset:35840
	ds_read_b128 v[212:215], v150 offset:36864
	ds_read_b128 v[216:219], v150 offset:37888
	ds_read_b128 v[220:223], v150 offset:38912
	ds_read_b128 v[224:227], v150 offset:39936
	global_load_lds_dwordx4 v[236:237], off
	v_lshl_add_u64 v[236:237], s[4:5], 0, v[132:133]
	s_mov_b32 m0, s36
	s_nop 0
	global_load_lds_dwordx4 v[236:237], off
	s_waitcnt vmcnt(8)
	s_waitcnt lgkmcnt(0)
	s_setprio 1
	s_barrier
	v_mfma_f32_16x16x32_bf16 v[124:127], v[144:147], v[196:199], v[124:127]
	v_mfma_f32_16x16x32_bf16 v[120:123], v[172:175], v[196:199], v[120:123]
	v_mfma_f32_16x16x32_bf16 v[108:111], v[144:147], v[204:207], v[108:111]
	v_mfma_f32_16x16x32_bf16 v[104:107], v[172:175], v[204:207], v[104:107]
	v_mfma_f32_16x16x32_bf16 v[92:95], v[144:147], v[212:215], v[92:95]
	v_mfma_f32_16x16x32_bf16 v[88:91], v[172:175], v[212:215], v[88:91]
	v_mfma_f32_16x16x32_bf16 v[76:79], v[144:147], v[220:223], v[76:79]
	v_mfma_f32_16x16x32_bf16 v[72:75], v[172:175], v[220:223], v[72:75]
	v_mfma_f32_16x16x32_bf16 v[124:127], v[168:171], v[200:203], v[124:127]
	v_mfma_f32_16x16x32_bf16 v[120:123], v[176:179], v[200:203], v[120:123]
	v_mfma_f32_16x16x32_bf16 v[108:111], v[168:171], v[208:211], v[108:111]
	v_mfma_f32_16x16x32_bf16 v[104:107], v[176:179], v[208:211], v[104:107]
	v_mfma_f32_16x16x32_bf16 v[92:95], v[168:171], v[216:219], v[92:95]
	v_mfma_f32_16x16x32_bf16 v[88:91], v[176:179], v[216:219], v[88:91]
	v_mfma_f32_16x16x32_bf16 v[76:79], v[168:171], v[224:227], v[76:79]
	v_mfma_f32_16x16x32_bf16 v[72:75], v[176:179], v[224:227], v[72:75]
	s_setprio 0
	s_setprio 1
	v_mfma_f32_16x16x32_bf16 v[116:119], v[180:183], v[196:199], v[116:119]
	v_mfma_f32_16x16x32_bf16 v[112:115], v[188:191], v[196:199], v[112:115]
	v_mfma_f32_16x16x32_bf16 v[100:103], v[180:183], v[204:207], v[100:103]
	v_mfma_f32_16x16x32_bf16 v[96:99], v[188:191], v[204:207], v[96:99]
	v_mfma_f32_16x16x32_bf16 v[84:87], v[180:183], v[212:215], v[84:87]
	v_mfma_f32_16x16x32_bf16 v[80:83], v[188:191], v[212:215], v[80:83]
	v_mfma_f32_16x16x32_bf16 v[68:71], v[180:183], v[220:223], v[68:71]
	v_mfma_f32_16x16x32_bf16 v[64:67], v[188:191], v[220:223], v[64:67]
	v_mfma_f32_16x16x32_bf16 v[116:119], v[184:187], v[200:203], v[116:119]
	v_mfma_f32_16x16x32_bf16 v[112:115], v[192:195], v[200:203], v[112:115]
	v_mfma_f32_16x16x32_bf16 v[100:103], v[184:187], v[208:211], v[100:103]
	v_mfma_f32_16x16x32_bf16 v[96:99], v[192:195], v[208:211], v[96:99]
	v_mfma_f32_16x16x32_bf16 v[84:87], v[184:187], v[216:219], v[84:87]
	v_mfma_f32_16x16x32_bf16 v[80:83], v[192:195], v[216:219], v[80:83]
	v_mfma_f32_16x16x32_bf16 v[68:71], v[184:187], v[224:227], v[68:71]
	v_mfma_f32_16x16x32_bf16 v[64:67], v[192:195], v[224:227], v[64:67]
	s_barrier
; #define PG8_STAGE(bufoff, gbase, voff) do { _Pragma("unroll") for (int _i = 0; _i < 2; ++_i) \
;         __builtin_amdgcn_global_load_lds((const unsigned*)((const char*)(gbase) + (voff)[_i]), (PG8_LAS unsigned*)(lds + (bufoff) + ldsw + _i * 8192), 16, 0, 0); } while (0)
; #define PG8_LDA(dst, b, h) do { _Pragma("unroll") for (int m = 0; m < 4; ++m) _Pragma("unroll") for (int k = 0; k < 2; ++k) dst[m][k] = *(const PG8_LAS bf16x8*)(lds + PG8_SA(b, h) + aoff + m * 2048 + k * 1024); } while (0)
; #define PG8_MMA(ai, bj, At, Bt) do { __builtin_amdgcn_s_setprio(1); _Pragma("unroll") for (int m = 0; m < 4; ++m) _Pragma("unroll") for (int n = 0; n < 2; ++n) _Pragma("unroll") for (int k = 0; k < 2; ++k) \
;         acc[ai][bj][m][n] = __builtin_amdgcn_mfma_f32_16x16x32_bf16(Bt[n][k], At[m][k], acc[ai][bj][m][n], 0, 0, 0); __builtin_amdgcn_s_setprio(0); } while (0)
; #define PG8_WAIT_V(n) asm volatile("s_waitcnt vmcnt(" #n ")" ::: "memory")
; #define PG8_WAIT_L(n) asm volatile("s_waitcnt lgkmcnt(" #n ")" ::: "memory")
; #define PG8_BAR __builtin_amdgcn_s_barrier()
; #define PG8_SCHED __builtin_amdgcn_sched_barrier(0)
; template <class Epi, class Sched, bool ALIGN_EPI = false, bool SP2 = false>
; __device__ __forceinline__ void gemm_phase(PG8_LAS unsigned char* lds, const Gemm g, const Sched& S, const Epi& E, const int tid_arg) {
;     ...
;             PG8_WAIT_V(8); PG8_WAIT_L(0); PG8_BAR; PG8_MMA(0, 0, At, B0); PG8_MMA(0, 1, At, B1); PG8_BAR; PG8_SCHED;
;             PG8_LDA(At, 1, 1); PG8_STAGE(PG8_SB(1, 0), b3, voffB); PG8_STAGE(PG8_SB(1, 1), b3 + hstep, voffB); PG8_STAGE(PG8_SA(1, 0), a3, voffA);
;             PG8_WAIT_V(8); PG8_WAIT_L(0); PG8_BAR; PG8_MMA(1, 0, At, B0); PG8_MMA(1, 1, At, B1); PG8_BAR; PG8_SCHED;
	s_setprio 0
	s_mov_b32 m0, s40
	v_lshl_add_u64 v[228:229], v[228:229], 0, s[16:17]
	s_add_u32 s0, s0, 0xb0080
	ds_read_b128 v[196:199], v150 offset:49152
	ds_read_b128 v[200:203], v150 offset:50176
	ds_read_b128 v[204:207], v150 offset:51200
	ds_read_b128 v[208:211], v150 offset:52224
	ds_read_b128 v[212:215], v150 offset:53248
	ds_read_b128 v[216:219], v150 offset:54272
	ds_read_b128 v[220:223], v150 offset:55296
	ds_read_b128 v[224:227], v150 offset:56320
	global_load_lds_dwordx4 v[228:229], off
	v_lshl_add_u64 v[228:229], v[230:231], 0, s[16:17]
	s_mov_b32 m0, s41
	s_addc_u32 s1, s1, 0
	global_load_lds_dwordx4 v[228:229], off
	v_lshl_add_u64 v[228:229], s[0:1], 0, v[130:131]
	s_mov_b32 m0, s44
	s_nop 0
	global_load_lds_dwordx4 v[228:229], off
	v_lshl_add_u64 v[228:229], s[0:1], 0, v[134:135]
	s_mov_b32 m0, s45
	s_nop 0
	global_load_lds_dwordx4 v[228:229], off
	v_lshl_add_u64 v[228:229], v[232:233], 0, s[16:17]
	s_mov_b32 m0, s42
	s_nop 0
	global_load_lds_dwordx4 v[228:229], off
	v_lshl_add_u64 v[228:229], v[234:235], 0, s[16:17]
	s_mov_b32 m0, s43
	s_nop 0
	global_load_lds_dwordx4 v[228:229], off
	s_waitcnt vmcnt(8)
	s_waitcnt lgkmcnt(0)
	s_setprio 1
	s_barrier
	v_mfma_f32_16x16x32_bf16 v[60:63], v[144:147], v[196:199], v[60:63]
	v_mfma_f32_16x16x32_bf16 v[56:59], v[172:175], v[196:199], v[56:59]
	v_mfma_f32_16x16x32_bf16 v[44:47], v[144:147], v[204:207], v[44:47]
	v_mfma_f32_16x16x32_bf16 v[40:43], v[172:175], v[204:207], v[40:43]
	v_mfma_f32_16x16x32_bf16 v[28:31], v[144:147], v[212:215], v[28:31]
	v_mfma_f32_16x16x32_bf16 v[24:27], v[172:175], v[212:215], v[24:27]
	v_mfma_f32_16x16x32_bf16 v[12:15], v[144:147], v[220:223], v[12:15]
	v_mfma_f32_16x16x32_bf16 v[8:11], v[172:175], v[220:223], v[8:11]
	v_mfma_f32_16x16x32_bf16 v[60:63], v[168:171], v[200:203], v[60:63]
	v_mfma_f32_16x16x32_bf16 v[56:59], v[176:179], v[200:203], v[56:59]
	v_mfma_f32_16x16x32_bf16 v[44:47], v[168:171], v[208:211], v[44:47]
	v_mfma_f32_16x16x32_bf16 v[40:43], v[176:179], v[208:211], v[40:43]
	v_mfma_f32_16x16x32_bf16 v[28:31], v[168:171], v[216:219], v[28:31]
	v_mfma_f32_16x16x32_bf16 v[24:27], v[176:179], v[216:219], v[24:27]
	v_mfma_f32_16x16x32_bf16 v[12:15], v[168:171], v[224:227], v[12:15]
	v_mfma_f32_16x16x32_bf16 v[8:11], v[176:179], v[224:227], v[8:11]
	s_setprio 0
	s_setprio 1
	v_mfma_f32_16x16x32_bf16 v[52:55], v[180:183], v[196:199], v[52:55]
	v_mfma_f32_16x16x32_bf16 v[48:51], v[188:191], v[196:199], v[48:51]
	v_mfma_f32_16x16x32_bf16 v[36:39], v[180:183], v[204:207], v[36:39]
	v_mfma_f32_16x16x32_bf16 v[32:35], v[188:191], v[204:207], v[32:35]
	v_mfma_f32_16x16x32_bf16 v[20:23], v[180:183], v[212:215], v[20:23]
	v_mfma_f32_16x16x32_bf16 v[16:19], v[188:191], v[212:215], v[16:19]
	v_mfma_f32_16x16x32_bf16 v[4:7], v[180:183], v[220:223], v[4:7]
	v_mfma_f32_16x16x32_bf16 v[0:3], v[188:191], v[220:223], v[0:3]
	v_mfma_f32_16x16x32_bf16 v[52:55], v[184:187], v[200:203], v[52:55]
	v_mfma_f32_16x16x32_bf16 v[48:51], v[192:195], v[200:203], v[48:51]
	v_mfma_f32_16x16x32_bf16 v[36:39], v[184:187], v[208:211], v[36:39]
	v_mfma_f32_16x16x32_bf16 v[32:35], v[192:195], v[208:211], v[32:35]
	v_mfma_f32_16x16x32_bf16 v[20:23], v[184:187], v[216:219], v[20:23]
	v_mfma_f32_16x16x32_bf16 v[16:19], v[192:195], v[216:219], v[16:19]
	v_mfma_f32_16x16x32_bf16 v[4:7], v[184:187], v[224:227], v[4:7]
	v_mfma_f32_16x16x32_bf16 v[0:3], v[192:195], v[224:227], v[0:3]
	s_barrier
	s_setprio 0
	s_add_i32 s57, s57, 2
	s_add_u32 s55, s55, 0x100
	s_addc_u32 s56, s56, 0
	s_cmp_gt_u32 s57, 41
	s_mov_b64 s[4:5], s[22:23]
	s_cbranch_scc0 .LBB0_871
	s_and_b64 vcc, exec, s[18:19]
	s_cbranch_vccz .LBB0_874
	s_barrier

; #define PG8_STAGE(bufoff, gbase, voff) do { _Pragma("unroll") for (int _i = 0; _i < 2; ++_i) \
;         __builtin_amdgcn_global_load_lds((const unsigned*)((const char*)(gbase) + (voff)[_i]), (PG8_LAS unsigned*)(lds + (bufoff) + ldsw + _i * 8192), 16, 0, 0); } while (0)
; #define PG8_LDA(dst, b, h) do { _Pragma("unroll") for (int m = 0; m < 4; ++m) _Pragma("unroll") for (int k = 0; k < 2; ++k) dst[m][k] = *(const PG8_LAS bf16x8*)(lds + PG8_SA(b, h) + aoff + m * 2048 + k * 1024); } while (0)
; #define PG8_LDB(dst, b, h) do { _Pragma("unroll") for (int n = 0; n < 2; ++n) _Pragma("unroll") for (int k = 0; k < 2; ++k) dst[n][k] = *(const PG8_LAS bf16x8*)(lds + PG8_SB(b, h) + boff + n * 2048 + k * 1024); } while (0)
; #define PG8_MMA(ai, bj, At, Bt) do { __builtin_amdgcn_s_setprio(1); _Pragma("unroll") for (int m = 0; m < 4; ++m) _Pragma("unroll") for (int n = 0; n < 2; ++n) _Pragma("unroll") for (int k = 0; k < 2; ++k) \
;         acc[ai][bj][m][n] = __builtin_amdgcn_mfma_f32_16x16x32_bf16(Bt[n][k], At[m][k], acc[ai][bj][m][n], 0, 0, 0); __builtin_amdgcn_s_setprio(0); } while (0)
; #define PG8_WAIT_V(n) asm volatile("s_waitcnt vmcnt(" #n ")" ::: "memory")
; #define PG8_WAIT_L(n) asm volatile("s_waitcnt lgkmcnt(" #n ")" ::: "memory")
; #define PG8_BAR __builtin_amdgcn_s_barrier()
; #define PG8_SCHED __builtin_amdgcn_sched_barrier(0)
; template <class Epi, class Sched, bool ALIGN_EPI = false, bool SP2 = false>
; __device__ __forceinline__ void gemm_phase(PG8_LAS unsigned char* lds, const Gemm g, const Sched& S, const Epi& E, const int tid_arg) {
;     ...
;             PG8_LDB(B0, 0, 0); PG8_LDB(B1, 0, 1); PG8_SCHED; PG8_LDA(At, 0, 0); PG8_STAGE(PG8_SA(1, 1), a1 + hstep, voffA);
;             PG8_WAIT_V(8); PG8_WAIT_L(0); PG8_BAR; PG8_MMA(0, 0, At, B0); PG8_MMA(0, 1, At, B1); PG8_BAR; PG8_SCHED;
;             PG8_LDA(At, 0, 1); PG8_STAGE(PG8_SB(0, 0), b2, voffB); PG8_STAGE(PG8_SB(0, 1), b2 + hstep, voffB); PG8_STAGE(PG8_SA(0, 0), a2, voffA);
;             PG8_WAIT_V(8); PG8_WAIT_L(0); PG8_BAR; PG8_MMA(1, 0, At, B0); PG8_MMA(1, 1, At, B1); PG8_BAR; PG8_SCHED;
.LBB0_965:
	ds_read_b128 v[170:173], v151
	ds_read_b128 v[174:177], v153
	ds_read_b128 v[178:181], v155
	ds_read_b128 v[182:185], v156
	ds_read_b128 v[186:189], v157
	ds_read_b128 v[190:193], v158
	ds_read_b128 v[194:197], v159
	ds_read_b128 v[198:201], v160
	s_add_u32 s0, s40, 0xfffc0080
	s_addc_u32 s1, s41, -1
	s_cmp_eq_u32 s72, 12
	s_cselect_b32 s43, s35, s1
	s_cselect_b32 s42, s68, s0
	s_cselect_b32 s1, s31, s71
	s_cselect_b32 s0, s69, s70
	s_mov_b32 m0, s60
	v_lshl_add_u64 v[234:235], s[40:41], 0, v[138:139]
	ds_read_b128 v[202:205], v149
	ds_read_b128 v[206:209], v149 offset:1024
	ds_read_b128 v[210:213], v149 offset:2048
	ds_read_b128 v[214:217], v149 offset:3072
	ds_read_b128 v[218:221], v149 offset:4096
	ds_read_b128 v[222:225], v149 offset:5120
	ds_read_b128 v[226:229], v149 offset:6144
	ds_read_b128 v[230:233], v149 offset:7168
	global_load_lds_dwordx4 v[234:235], off
	v_lshl_add_u64 v[234:235], s[40:41], 0, v[136:137]
	s_mov_b32 m0, s61
	s_nop 0
	global_load_lds_dwordx4 v[234:235], off
	s_waitcnt vmcnt(8)
	s_waitcnt lgkmcnt(0)
	s_setprio 1
	s_barrier
	v_mfma_f32_16x16x32_bf16 v[124:127], v[170:173], v[202:205], v[124:127]
	v_mfma_f32_16x16x32_bf16 v[120:123], v[178:181], v[202:205], v[120:123]
	v_mfma_f32_16x16x32_bf16 v[108:111], v[170:173], v[210:213], v[108:111]
	v_mfma_f32_16x16x32_bf16 v[104:107], v[178:181], v[210:213], v[104:107]
	v_mfma_f32_16x16x32_bf16 v[92:95], v[170:173], v[218:221], v[92:95]
	v_mfma_f32_16x16x32_bf16 v[88:91], v[178:181], v[218:221], v[88:91]
	v_mfma_f32_16x16x32_bf16 v[76:79], v[170:173], v[226:229], v[76:79]
	v_mfma_f32_16x16x32_bf16 v[72:75], v[178:181], v[226:229], v[72:75]
	v_mfma_f32_16x16x32_bf16 v[124:127], v[174:177], v[206:209], v[124:127]
	v_mfma_f32_16x16x32_bf16 v[120:123], v[182:185], v[206:209], v[120:123]
	v_mfma_f32_16x16x32_bf16 v[108:111], v[174:177], v[214:217], v[108:111]
	v_mfma_f32_16x16x32_bf16 v[104:107], v[182:185], v[214:217], v[104:107]
	v_mfma_f32_16x16x32_bf16 v[92:95], v[174:177], v[222:225], v[92:95]
	v_mfma_f32_16x16x32_bf16 v[88:91], v[182:185], v[222:225], v[88:91]
	v_mfma_f32_16x16x32_bf16 v[76:79], v[174:177], v[230:233], v[76:79]
	v_mfma_f32_16x16x32_bf16 v[72:75], v[182:185], v[230:233], v[72:75]
	s_setprio 0
	s_setprio 1
	v_mfma_f32_16x16x32_bf16 v[116:119], v[186:189], v[202:205], v[116:119]
	v_mfma_f32_16x16x32_bf16 v[112:115], v[194:197], v[202:205], v[112:115]
	v_mfma_f32_16x16x32_bf16 v[100:103], v[186:189], v[210:213], v[100:103]
	v_mfma_f32_16x16x32_bf16 v[96:99], v[194:197], v[210:213], v[96:99]
	v_mfma_f32_16x16x32_bf16 v[84:87], v[186:189], v[218:221], v[84:87]
	v_mfma_f32_16x16x32_bf16 v[80:83], v[194:197], v[218:221], v[80:83]
	v_mfma_f32_16x16x32_bf16 v[68:71], v[186:189], v[226:229], v[68:71]
	v_mfma_f32_16x16x32_bf16 v[64:67], v[194:197], v[226:229], v[64:67]
	v_mfma_f32_16x16x32_bf16 v[116:119], v[190:193], v[206:209], v[116:119]
	v_mfma_f32_16x16x32_bf16 v[112:115], v[198:201], v[206:209], v[112:115]
	v_mfma_f32_16x16x32_bf16 v[100:103], v[190:193], v[214:217], v[100:103]
	v_mfma_f32_16x16x32_bf16 v[96:99], v[198:201], v[214:217], v[96:99]
	v_mfma_f32_16x16x32_bf16 v[84:87], v[190:193], v[222:225], v[84:87]
	v_mfma_f32_16x16x32_bf16 v[80:83], v[198:201], v[222:225], v[80:83]
	v_mfma_f32_16x16x32_bf16 v[68:71], v[190:193], v[230:233], v[68:71]
	v_mfma_f32_16x16x32_bf16 v[64:67], v[198:201], v[230:233], v[64:67]
	s_barrier
	s_setprio 0
	s_mov_b32 m0, s5
	v_lshl_add_u64 v[234:235], s[0:1], 0, v[130:131]
	s_add_u32 s74, s0, 0x40000
	ds_read_b128 v[202:205], v149 offset:16384
	ds_read_b128 v[206:209], v149 offset:17408
	ds_read_b128 v[210:213], v149 offset:18432
	ds_read_b128 v[214:217], v149 offset:19456
	ds_read_b128 v[218:221], v149 offset:20480
	ds_read_b128 v[222:225], v149 offset:21504
	ds_read_b128 v[226:229], v149 offset:22528
	ds_read_b128 v[230:233], v149 offset:23552
	global_load_lds_dwordx4 v[234:235], off
	v_lshl_add_u64 v[236:237], s[0:1], 0, v[134:135]
	s_mov_b32 m0, s47
	s_addc_u32 s75, s1, 0
	global_load_lds_dwordx4 v[236:237], off
	v_lshl_add_u64 v[238:239], s[74:75], 0, v[130:131]
	s_mov_b32 m0, s48
	v_lshl_add_u64 v[240:241], s[42:43], 0, v[132:133]
	global_load_lds_dwordx4 v[238:239], off
	v_lshl_add_u64 v[238:239], s[74:75], 0, v[134:135]
	s_mov_b32 m0, s49
	s_nop 0
	global_load_lds_dwordx4 v[238:239], off
	v_lshl_add_u64 v[238:239], s[42:43], 0, v[128:129]
	s_mov_b32 m0, s46
	s_nop 0
	global_load_lds_dwordx4 v[238:239], off
	s_mov_b32 m0, s50
	s_nop 0
	global_load_lds_dwordx4 v[240:241], off
	s_waitcnt vmcnt(8)
	s_waitcnt lgkmcnt(0)
	s_setprio 1
	s_barrier
; #define PG8_STAGE(bufoff, gbase, voff) do { _Pragma("unroll") for (int _i = 0; _i < 2; ++_i) \
;         __builtin_amdgcn_global_load_lds((const unsigned*)((const char*)(gbase) + (voff)[_i]), (PG8_LAS unsigned*)(lds + (bufoff) + ldsw + _i * 8192), 16, 0, 0); } while (0)
; #define PG8_LDA(dst, b, h) do { _Pragma("unroll") for (int m = 0; m < 4; ++m) _Pragma("unroll") for (int k = 0; k < 2; ++k) dst[m][k] = *(const PG8_LAS bf16x8*)(lds + PG8_SA(b, h) + aoff + m * 2048 + k * 1024); } while (0)
; #define PG8_LDB(dst, b, h) do { _Pragma("unroll") for (int n = 0; n < 2; ++n) _Pragma("unroll") for (int k = 0; k < 2; ++k) dst[n][k] = *(const PG8_LAS bf16x8*)(lds + PG8_SB(b, h) + boff + n * 2048 + k * 1024); } while (0)
; #define PG8_MMA(ai, bj, At, Bt) do { __builtin_amdgcn_s_setprio(1); _Pragma("unroll") for (int m = 0; m < 4; ++m) _Pragma("unroll") for (int n = 0; n < 2; ++n) _Pragma("unroll") for (int k = 0; k < 2; ++k) \
;         acc[ai][bj][m][n] = __builtin_amdgcn_mfma_f32_16x16x32_bf16(Bt[n][k], At[m][k], acc[ai][bj][m][n], 0, 0, 0); __builtin_amdgcn_s_setprio(0); } while (0)
; #define PG8_WAIT_V(n) asm volatile("s_waitcnt vmcnt(" #n ")" ::: "memory")
; #define PG8_WAIT_L(n) asm volatile("s_waitcnt lgkmcnt(" #n ")" ::: "memory")
; #define PG8_BAR __builtin_amdgcn_s_barrier()
; #define PG8_SCHED __builtin_amdgcn_sched_barrier(0)
; template <class Epi, class Sched, bool ALIGN_EPI = false, bool SP2 = false>
; __device__ __forceinline__ void gemm_phase(PG8_LAS unsigned char* lds, const Gemm g, const Sched& S, const Epi& E, const int tid_arg) {
;     ...
;             PG8_WAIT_V(8); PG8_WAIT_L(0); PG8_BAR; PG8_MMA(1, 0, At, B0); PG8_MMA(1, 1, At, B1); PG8_BAR; PG8_SCHED;
;             PG8_LDB(B0, 1, 0); PG8_LDB(B1, 1, 1); PG8_SCHED; PG8_LDA(At, 1, 0); PG8_STAGE(PG8_SA(0, 1), a2 + hstep, voffA);
;             PG8_WAIT_V(8); PG8_WAIT_L(0); PG8_BAR; PG8_MMA(0, 0, At, B0); PG8_MMA(0, 1, At, B1); PG8_BAR; PG8_SCHED;
	v_mfma_f32_16x16x32_bf16 v[60:63], v[170:173], v[202:205], v[60:63]
	v_mfma_f32_16x16x32_bf16 v[56:59], v[178:181], v[202:205], v[56:59]
	v_mfma_f32_16x16x32_bf16 v[44:47], v[170:173], v[210:213], v[44:47]
	v_mfma_f32_16x16x32_bf16 v[40:43], v[178:181], v[210:213], v[40:43]
	v_mfma_f32_16x16x32_bf16 v[28:31], v[170:173], v[218:221], v[28:31]
	v_mfma_f32_16x16x32_bf16 v[24:27], v[178:181], v[218:221], v[24:27]
	v_mfma_f32_16x16x32_bf16 v[12:15], v[170:173], v[226:229], v[12:15]
	v_mfma_f32_16x16x32_bf16 v[8:11], v[178:181], v[226:229], v[8:11]
	v_mfma_f32_16x16x32_bf16 v[60:63], v[174:177], v[206:209], v[60:63]
	v_mfma_f32_16x16x32_bf16 v[56:59], v[182:185], v[206:209], v[56:59]
	v_mfma_f32_16x16x32_bf16 v[44:47], v[174:177], v[214:217], v[44:47]
	v_mfma_f32_16x16x32_bf16 v[40:43], v[182:185], v[214:217], v[40:43]
	v_mfma_f32_16x16x32_bf16 v[28:31], v[174:177], v[222:225], v[28:31]
	v_mfma_f32_16x16x32_bf16 v[24:27], v[182:185], v[222:225], v[24:27]
	v_mfma_f32_16x16x32_bf16 v[12:15], v[174:177], v[230:233], v[12:15]
	v_mfma_f32_16x16x32_bf16 v[8:11], v[182:185], v[230:233], v[8:11]
	s_setprio 0
	s_setprio 1
	v_mfma_f32_16x16x32_bf16 v[52:55], v[186:189], v[202:205], v[52:55]
	v_mfma_f32_16x16x32_bf16 v[48:51], v[194:197], v[202:205], v[48:51]
	v_mfma_f32_16x16x32_bf16 v[36:39], v[186:189], v[210:213], v[36:39]
	v_mfma_f32_16x16x32_bf16 v[32:35], v[194:197], v[210:213], v[32:35]
	v_mfma_f32_16x16x32_bf16 v[20:23], v[186:189], v[218:221], v[20:23]
	v_mfma_f32_16x16x32_bf16 v[16:19], v[194:197], v[218:221], v[16:19]
	v_mfma_f32_16x16x32_bf16 v[4:7], v[186:189], v[226:229], v[4:7]
	v_mfma_f32_16x16x32_bf16 v[0:3], v[194:197], v[226:229], v[0:3]
	v_mfma_f32_16x16x32_bf16 v[52:55], v[190:193], v[206:209], v[52:55]
	v_mfma_f32_16x16x32_bf16 v[48:51], v[198:201], v[206:209], v[48:51]
	v_mfma_f32_16x16x32_bf16 v[36:39], v[190:193], v[214:217], v[36:39]
	v_mfma_f32_16x16x32_bf16 v[32:35], v[198:201], v[214:217], v[32:35]
	v_mfma_f32_16x16x32_bf16 v[20:23], v[190:193], v[222:225], v[20:23]
	v_mfma_f32_16x16x32_bf16 v[16:19], v[198:201], v[222:225], v[16:19]
	v_mfma_f32_16x16x32_bf16 v[4:7], v[190:193], v[230:233], v[4:7]
	v_mfma_f32_16x16x32_bf16 v[0:3], v[198:201], v[230:233], v[0:3]
	s_barrier
	s_setprio 0
	ds_read_b128 v[170:173], v161
	ds_read_b128 v[174:177], v162
	ds_read_b128 v[178:181], v163
	ds_read_b128 v[182:185], v164
	ds_read_b128 v[186:189], v165
	ds_read_b128 v[190:193], v166
	ds_read_b128 v[194:197], v167
	ds_read_b128 v[198:201], v168
	s_add_u32 s42, s42, 0x40000
	s_addc_u32 s43, s43, 0
	s_mov_b32 m0, s51
	v_lshl_add_u64 v[242:243], s[42:43], 0, v[128:129]
	ds_read_b128 v[202:205], v149 offset:32768
	ds_read_b128 v[206:209], v149 offset:33792
	ds_read_b128 v[210:213], v149 offset:34816
	ds_read_b128 v[214:217], v149 offset:35840
	ds_read_b128 v[218:221], v149 offset:36864
	ds_read_b128 v[222:225], v149 offset:37888
	ds_read_b128 v[226:229], v149 offset:38912
	ds_read_b128 v[230:233], v149 offset:39936
	global_load_lds_dwordx4 v[242:243], off
	v_lshl_add_u64 v[242:243], s[42:43], 0, v[132:133]
	s_mov_b32 m0, s52
	s_nop 0
	global_load_lds_dwordx4 v[242:243], off
	s_waitcnt vmcnt(8)
	s_waitcnt lgkmcnt(0)
	s_setprio 1
	s_barrier
	v_mfma_f32_16x16x32_bf16 v[124:127], v[170:173], v[202:205], v[124:127]
	v_mfma_f32_16x16x32_bf16 v[120:123], v[178:181], v[202:205], v[120:123]
	v_mfma_f32_16x16x32_bf16 v[108:111], v[170:173], v[210:213], v[108:111]
	v_mfma_f32_16x16x32_bf16 v[104:107], v[178:181], v[210:213], v[104:107]
	v_mfma_f32_16x16x32_bf16 v[92:95], v[170:173], v[218:221], v[92:95]
	v_mfma_f32_16x16x32_bf16 v[88:91], v[178:181], v[218:221], v[88:91]
	v_mfma_f32_16x16x32_bf16 v[76:79], v[170:173], v[226:229], v[76:79]
	v_mfma_f32_16x16x32_bf16 v[72:75], v[178:181], v[226:229], v[72:75]
	v_mfma_f32_16x16x32_bf16 v[124:127], v[174:177], v[206:209], v[124:127]
	v_mfma_f32_16x16x32_bf16 v[120:123], v[182:185], v[206:209], v[120:123]
	v_mfma_f32_16x16x32_bf16 v[108:111], v[174:177], v[214:217], v[108:111]
	v_mfma_f32_16x16x32_bf16 v[104:107], v[182:185], v[214:217], v[104:107]
	v_mfma_f32_16x16x32_bf16 v[92:95], v[174:177], v[222:225], v[92:95]
	v_mfma_f32_16x16x32_bf16 v[88:91], v[182:185], v[222:225], v[88:91]
	v_mfma_f32_16x16x32_bf16 v[76:79], v[174:177], v[230:233], v[76:79]
	v_mfma_f32_16x16x32_bf16 v[72:75], v[182:185], v[230:233], v[72:75]
	s_setprio 0
	s_setprio 1
	v_mfma_f32_16x16x32_bf16 v[116:119], v[186:189], v[202:205], v[116:119]
	v_mfma_f32_16x16x32_bf16 v[112:115], v[194:197], v[202:205], v[112:115]
	v_mfma_f32_16x16x32_bf16 v[100:103], v[186:189], v[210:213], v[100:103]
	v_mfma_f32_16x16x32_bf16 v[96:99], v[194:197], v[210:213], v[96:99]
	v_mfma_f32_16x16x32_bf16 v[84:87], v[186:189], v[218:221], v[84:87]
	v_mfma_f32_16x16x32_bf16 v[80:83], v[194:197], v[218:221], v[80:83]
	v_mfma_f32_16x16x32_bf16 v[68:71], v[186:189], v[226:229], v[68:71]
	v_mfma_f32_16x16x32_bf16 v[64:67], v[194:197], v[226:229], v[64:67]
	v_mfma_f32_16x16x32_bf16 v[116:119], v[190:193], v[206:209], v[116:119]
	v_mfma_f32_16x16x32_bf16 v[112:115], v[198:201], v[206:209], v[112:115]
	v_mfma_f32_16x16x32_bf16 v[100:103], v[190:193], v[214:217], v[100:103]
	v_mfma_f32_16x16x32_bf16 v[96:99], v[198:201], v[214:217], v[96:99]
	v_mfma_f32_16x16x32_bf16 v[84:87], v[190:193], v[222:225], v[84:87]
	v_mfma_f32_16x16x32_bf16 v[80:83], v[198:201], v[222:225], v[80:83]
	v_mfma_f32_16x16x32_bf16 v[68:71], v[190:193], v[230:233], v[68:71]
	v_mfma_f32_16x16x32_bf16 v[64:67], v[198:201], v[230:233], v[64:67]
	s_barrier
; #define PG8_STAGE(bufoff, gbase, voff) do { _Pragma("unroll") for (int _i = 0; _i < 2; ++_i) \
;         __builtin_amdgcn_global_load_lds((const unsigned*)((const char*)(gbase) + (voff)[_i]), (PG8_LAS unsigned*)(lds + (bufoff) + ldsw + _i * 8192), 16, 0, 0); } while (0)
; #define PG8_LDA(dst, b, h) do { _Pragma("unroll") for (int m = 0; m < 4; ++m) _Pragma("unroll") for (int k = 0; k < 2; ++k) dst[m][k] = *(const PG8_LAS bf16x8*)(lds + PG8_SA(b, h) + aoff + m * 2048 + k * 1024); } while (0)
; #define PG8_MMA(ai, bj, At, Bt) do { __builtin_amdgcn_s_setprio(1); _Pragma("unroll") for (int m = 0; m < 4; ++m) _Pragma("unroll") for (int n = 0; n < 2; ++n) _Pragma("unroll") for (int k = 0; k < 2; ++k) \
;         acc[ai][bj][m][n] = __builtin_amdgcn_mfma_f32_16x16x32_bf16(Bt[n][k], At[m][k], acc[ai][bj][m][n], 0, 0, 0); __builtin_amdgcn_s_setprio(0); } while (0)
; #define PG8_WAIT_V(n) asm volatile("s_waitcnt vmcnt(" #n ")" ::: "memory")
; #define PG8_WAIT_L(n) asm volatile("s_waitcnt lgkmcnt(" #n ")" ::: "memory")
; #define PG8_BAR __builtin_amdgcn_s_barrier()
; #define PG8_SCHED __builtin_amdgcn_sched_barrier(0)
; template <class Epi, class Sched, bool ALIGN_EPI = false, bool SP2 = false>
; __device__ __forceinline__ void gemm_phase(PG8_LAS unsigned char* lds, const Gemm g, const Sched& S, const Epi& E, const int tid_arg) {
;     ...
;             PG8_WAIT_V(8); PG8_WAIT_L(0); PG8_BAR; PG8_MMA(0, 0, At, B0); PG8_MMA(0, 1, At, B1); PG8_BAR; PG8_SCHED;
;             PG8_LDA(At, 1, 1); PG8_STAGE(PG8_SB(1, 0), b3, voffB); PG8_STAGE(PG8_SB(1, 1), b3 + hstep, voffB); PG8_STAGE(PG8_SA(1, 0), a3, voffA);
;             PG8_WAIT_V(8); PG8_WAIT_L(0); PG8_BAR; PG8_MMA(1, 0, At, B0); PG8_MMA(1, 1, At, B1); PG8_BAR; PG8_SCHED;
	s_setprio 0
	s_mov_b32 m0, s54
	v_lshl_add_u64 v[234:235], v[234:235], 0, s[12:13]
	s_add_u32 s0, s0, 0x40080
	ds_read_b128 v[202:205], v149 offset:49152
	ds_read_b128 v[206:209], v149 offset:50176
	ds_read_b128 v[210:213], v149 offset:51200
	ds_read_b128 v[214:217], v149 offset:52224
	ds_read_b128 v[218:221], v149 offset:53248
	ds_read_b128 v[222:225], v149 offset:54272
	ds_read_b128 v[226:229], v149 offset:55296
	ds_read_b128 v[230:233], v149 offset:56320
	global_load_lds_dwordx4 v[234:235], off
	v_lshl_add_u64 v[234:235], v[236:237], 0, s[12:13]
	s_mov_b32 m0, s55
	s_addc_u32 s1, s1, 0
	global_load_lds_dwordx4 v[234:235], off
	v_lshl_add_u64 v[234:235], s[0:1], 0, v[130:131]
	s_mov_b32 m0, s58
	s_nop 0
	global_load_lds_dwordx4 v[234:235], off
	v_lshl_add_u64 v[234:235], s[0:1], 0, v[134:135]
	s_mov_b32 m0, s59
	s_nop 0
	global_load_lds_dwordx4 v[234:235], off
	v_lshl_add_u64 v[234:235], v[238:239], 0, s[12:13]
	s_mov_b32 m0, s56
	s_nop 0
	global_load_lds_dwordx4 v[234:235], off
	v_lshl_add_u64 v[234:235], v[240:241], 0, s[12:13]
	s_mov_b32 m0, s57
	s_nop 0
	global_load_lds_dwordx4 v[234:235], off
	s_waitcnt vmcnt(8)
	s_waitcnt lgkmcnt(0)
	s_setprio 1
	s_barrier
	v_mfma_f32_16x16x32_bf16 v[60:63], v[170:173], v[202:205], v[60:63]
	v_mfma_f32_16x16x32_bf16 v[56:59], v[178:181], v[202:205], v[56:59]
	v_mfma_f32_16x16x32_bf16 v[44:47], v[170:173], v[210:213], v[44:47]
	v_mfma_f32_16x16x32_bf16 v[40:43], v[178:181], v[210:213], v[40:43]
	v_mfma_f32_16x16x32_bf16 v[28:31], v[170:173], v[218:221], v[28:31]
	v_mfma_f32_16x16x32_bf16 v[24:27], v[178:181], v[218:221], v[24:27]
	v_mfma_f32_16x16x32_bf16 v[12:15], v[170:173], v[226:229], v[12:15]
	v_mfma_f32_16x16x32_bf16 v[8:11], v[178:181], v[226:229], v[8:11]
	v_mfma_f32_16x16x32_bf16 v[60:63], v[174:177], v[206:209], v[60:63]
	v_mfma_f32_16x16x32_bf16 v[56:59], v[182:185], v[206:209], v[56:59]
	v_mfma_f32_16x16x32_bf16 v[44:47], v[174:177], v[214:217], v[44:47]
	v_mfma_f32_16x16x32_bf16 v[40:43], v[182:185], v[214:217], v[40:43]
	v_mfma_f32_16x16x32_bf16 v[28:31], v[174:177], v[222:225], v[28:31]
	v_mfma_f32_16x16x32_bf16 v[24:27], v[182:185], v[222:225], v[24:27]
	v_mfma_f32_16x16x32_bf16 v[12:15], v[174:177], v[230:233], v[12:15]
	v_mfma_f32_16x16x32_bf16 v[8:11], v[182:185], v[230:233], v[8:11]
	s_setprio 0
	s_setprio 1
	v_mfma_f32_16x16x32_bf16 v[52:55], v[186:189], v[202:205], v[52:55]
	v_mfma_f32_16x16x32_bf16 v[48:51], v[194:197], v[202:205], v[48:51]
	v_mfma_f32_16x16x32_bf16 v[36:39], v[186:189], v[210:213], v[36:39]
	v_mfma_f32_16x16x32_bf16 v[32:35], v[194:197], v[210:213], v[32:35]
	v_mfma_f32_16x16x32_bf16 v[20:23], v[186:189], v[218:221], v[20:23]
	v_mfma_f32_16x16x32_bf16 v[16:19], v[194:197], v[218:221], v[16:19]
	v_mfma_f32_16x16x32_bf16 v[4:7], v[186:189], v[226:229], v[4:7]
	v_mfma_f32_16x16x32_bf16 v[0:3], v[194:197], v[226:229], v[0:3]
	v_mfma_f32_16x16x32_bf16 v[52:55], v[190:193], v[206:209], v[52:55]
	v_mfma_f32_16x16x32_bf16 v[48:51], v[198:201], v[206:209], v[48:51]
	v_mfma_f32_16x16x32_bf16 v[36:39], v[190:193], v[214:217], v[36:39]
	v_mfma_f32_16x16x32_bf16 v[32:35], v[198:201], v[214:217], v[32:35]
	v_mfma_f32_16x16x32_bf16 v[20:23], v[190:193], v[222:225], v[20:23]
	v_mfma_f32_16x16x32_bf16 v[16:19], v[198:201], v[222:225], v[16:19]
	v_mfma_f32_16x16x32_bf16 v[4:7], v[190:193], v[230:233], v[4:7]
	v_mfma_f32_16x16x32_bf16 v[0:3], v[198:201], v[230:233], v[0:3]
	s_barrier
	s_setprio 0
	s_add_i32 s72, s72, 2
	s_add_u32 s70, s70, 0x100
	s_addc_u32 s71, s71, 0
	s_add_u32 s40, s40, 0x100
	s_addc_u32 s41, s41, 0
	s_cmp_gt_u32 s72, 13
	s_cbranch_scc0 .LBB0_965
	s_and_b64 vcc, exec, s[14:15]
	s_cbranch_vccz .LBB0_968
	s_barrier

; #define PG8_STAGE(bufoff, gbase, voff) do { _Pragma("unroll") for (int _i = 0; _i < 2; ++_i) \
;         __builtin_amdgcn_global_load_lds((const unsigned*)((const char*)(gbase) + (voff)[_i]), (PG8_LAS unsigned*)(lds + (bufoff) + ldsw + _i * 8192), 16, 0, 0); } while (0)
; #define PG8_LDA(dst, b, h) do { _Pragma("unroll") for (int m = 0; m < 4; ++m) _Pragma("unroll") for (int k = 0; k < 2; ++k) dst[m][k] = *(const PG8_LAS bf16x8*)(lds + PG8_SA(b, h) + aoff + m * 2048 + k * 1024); } while (0)
; #define PG8_LDB(dst, b, h) do { _Pragma("unroll") for (int n = 0; n < 2; ++n) _Pragma("unroll") for (int k = 0; k < 2; ++k) dst[n][k] = *(const PG8_LAS bf16x8*)(lds + PG8_SB(b, h) + boff + n * 2048 + k * 1024); } while (0)
; #define PG8_MMA(ai, bj, At, Bt) do { __builtin_amdgcn_s_setprio(1); _Pragma("unroll") for (int m = 0; m < 4; ++m) _Pragma("unroll") for (int n = 0; n < 2; ++n) _Pragma("unroll") for (int k = 0; k < 2; ++k) \
;         acc[ai][bj][m][n] = __builtin_amdgcn_mfma_f32_16x16x32_bf16(Bt[n][k], At[m][k], acc[ai][bj][m][n], 0, 0, 0); __builtin_amdgcn_s_setprio(0); } while (0)
; #define PG8_WAIT_V(n) asm volatile("s_waitcnt vmcnt(" #n ")" ::: "memory")
; #define PG8_WAIT_L(n) asm volatile("s_waitcnt lgkmcnt(" #n ")" ::: "memory")
; #define PG8_BAR __builtin_amdgcn_s_barrier()
; #define PG8_SCHED __builtin_amdgcn_sched_barrier(0)
; template <class Epi, class Sched, bool ALIGN_EPI = false, bool SP2 = false>
; __device__ __forceinline__ void gemm_phase(PG8_LAS unsigned char* lds, const Gemm g, const Sched& S, const Epi& E, const int tid_arg) {
;     ...
;             PG8_LDB(B0, 0, 0); PG8_LDB(B1, 0, 1); PG8_SCHED; PG8_LDA(At, 0, 0); PG8_STAGE(PG8_SA(1, 1), a1 + hstep, voffA);
;             PG8_WAIT_V(8); PG8_WAIT_L(0); PG8_BAR; PG8_MMA(0, 0, At, B0); PG8_MMA(0, 1, At, B1); PG8_BAR; PG8_SCHED;
;             PG8_LDA(At, 0, 1); PG8_STAGE(PG8_SB(0, 0), b2, voffB); PG8_STAGE(PG8_SB(0, 1), b2 + hstep, voffB); PG8_STAGE(PG8_SA(0, 0), a2, voffA);
;             PG8_WAIT_V(8); PG8_WAIT_L(0); PG8_BAR; PG8_MMA(1, 0, At, B0); PG8_MMA(1, 1, At, B1); PG8_BAR; PG8_SCHED;
.LBB0_1046:
	ds_read_b128 v[144:147], v151
	ds_read_b128 v[168:171], v152
	ds_read_b128 v[172:175], v153
	ds_read_b128 v[176:179], v154
	ds_read_b128 v[180:183], v155
	ds_read_b128 v[184:187], v156
	ds_read_b128 v[188:191], v157
	ds_read_b128 v[192:195], v158
	s_add_i32 s30, s0, 2
	s_add_u32 s31, s4, 0x80
	s_addc_u32 s1, s5, 0
	s_cmp_eq_u32 s52, s0
	s_cselect_b32 s0, s14, s31
	s_cselect_b32 s1, s15, s1
	s_cselect_b32 s63, s29, s61
	s_cselect_b32 s62, s28, s60
	s_mov_b32 m0, s53
	v_lshl_add_u64 v[228:229], s[4:5], 0, v[138:139]
	ds_read_b128 v[196:199], v150
	ds_read_b128 v[200:203], v150 offset:1024
	ds_read_b128 v[204:207], v150 offset:2048
	ds_read_b128 v[208:211], v150 offset:3072
	ds_read_b128 v[212:215], v150 offset:4096
	ds_read_b128 v[216:219], v150 offset:5120
	ds_read_b128 v[220:223], v150 offset:6144
	ds_read_b128 v[224:227], v150 offset:7168
	global_load_lds_dwordx4 v[228:229], off
	v_lshl_add_u64 v[228:229], s[4:5], 0, v[136:137]
	s_mov_b32 m0, s54
	s_nop 0
	global_load_lds_dwordx4 v[228:229], off
	s_waitcnt vmcnt(8)
	s_waitcnt lgkmcnt(0)
	s_setprio 1
	s_barrier
	v_mfma_f32_16x16x32_bf16 v[124:127], v[144:147], v[196:199], v[124:127]
	v_mfma_f32_16x16x32_bf16 v[120:123], v[172:175], v[196:199], v[120:123]
	v_mfma_f32_16x16x32_bf16 v[108:111], v[144:147], v[204:207], v[108:111]
	v_mfma_f32_16x16x32_bf16 v[104:107], v[172:175], v[204:207], v[104:107]
	v_mfma_f32_16x16x32_bf16 v[92:95], v[144:147], v[212:215], v[92:95]
	v_mfma_f32_16x16x32_bf16 v[88:91], v[172:175], v[212:215], v[88:91]
	v_mfma_f32_16x16x32_bf16 v[76:79], v[144:147], v[220:223], v[76:79]
	v_mfma_f32_16x16x32_bf16 v[72:75], v[172:175], v[220:223], v[72:75]
	v_mfma_f32_16x16x32_bf16 v[124:127], v[168:171], v[200:203], v[124:127]
	v_mfma_f32_16x16x32_bf16 v[120:123], v[176:179], v[200:203], v[120:123]
	v_mfma_f32_16x16x32_bf16 v[108:111], v[168:171], v[208:211], v[108:111]
	v_mfma_f32_16x16x32_bf16 v[104:107], v[176:179], v[208:211], v[104:107]
	v_mfma_f32_16x16x32_bf16 v[92:95], v[168:171], v[216:219], v[92:95]
	v_mfma_f32_16x16x32_bf16 v[88:91], v[176:179], v[216:219], v[88:91]
	v_mfma_f32_16x16x32_bf16 v[76:79], v[168:171], v[224:227], v[76:79]
	v_mfma_f32_16x16x32_bf16 v[72:75], v[176:179], v[224:227], v[72:75]
	s_setprio 0
	s_setprio 1
	v_mfma_f32_16x16x32_bf16 v[116:119], v[180:183], v[196:199], v[116:119]
	v_mfma_f32_16x16x32_bf16 v[112:115], v[188:191], v[196:199], v[112:115]
	v_mfma_f32_16x16x32_bf16 v[100:103], v[180:183], v[204:207], v[100:103]
	v_mfma_f32_16x16x32_bf16 v[96:99], v[188:191], v[204:207], v[96:99]
	v_mfma_f32_16x16x32_bf16 v[84:87], v[180:183], v[212:215], v[84:87]
	v_mfma_f32_16x16x32_bf16 v[80:83], v[188:191], v[212:215], v[80:83]
	v_mfma_f32_16x16x32_bf16 v[68:71], v[180:183], v[220:223], v[68:71]
	v_mfma_f32_16x16x32_bf16 v[64:67], v[188:191], v[220:223], v[64:67]
	v_mfma_f32_16x16x32_bf16 v[116:119], v[184:187], v[200:203], v[116:119]
	v_mfma_f32_16x16x32_bf16 v[112:115], v[192:195], v[200:203], v[112:115]
	v_mfma_f32_16x16x32_bf16 v[100:103], v[184:187], v[208:211], v[100:103]
	v_mfma_f32_16x16x32_bf16 v[96:99], v[192:195], v[208:211], v[96:99]
	v_mfma_f32_16x16x32_bf16 v[84:87], v[184:187], v[216:219], v[84:87]
	v_mfma_f32_16x16x32_bf16 v[80:83], v[192:195], v[216:219], v[80:83]
	v_mfma_f32_16x16x32_bf16 v[68:71], v[184:187], v[224:227], v[68:71]
	v_mfma_f32_16x16x32_bf16 v[64:67], v[192:195], v[224:227], v[64:67]
	s_barrier
	s_setprio 0
	s_mov_b32 m0, s37
	v_lshl_add_u64 v[228:229], s[62:63], 0, v[130:131]
	v_lshl_add_u64 v[230:231], s[62:63], 0, v[134:135]
	s_add_u32 s62, s62, s6
	ds_read_b128 v[196:199], v150 offset:16384
	ds_read_b128 v[200:203], v150 offset:17408
	ds_read_b128 v[204:207], v150 offset:18432
	ds_read_b128 v[208:211], v150 offset:19456
	ds_read_b128 v[212:215], v150 offset:20480
	ds_read_b128 v[216:219], v150 offset:21504
	ds_read_b128 v[220:223], v150 offset:22528
	ds_read_b128 v[224:227], v150 offset:23552
	global_load_lds_dwordx4 v[228:229], off
	s_mov_b32 m0, s38
	s_addc_u32 s63, s63, s7
	global_load_lds_dwordx4 v[230:231], off
	v_lshl_add_u64 v[232:233], s[62:63], 0, v[130:131]
	s_mov_b32 m0, s39
	v_lshl_add_u64 v[234:235], s[62:63], 0, v[134:135]
	global_load_lds_dwordx4 v[232:233], off
	s_mov_b32 m0, s40
	v_lshl_add_u64 v[236:237], s[0:1], 0, v[128:129]
	global_load_lds_dwordx4 v[234:235], off
	s_mov_b32 m0, s36
	v_lshl_add_u64 v[238:239], s[0:1], 0, v[132:133]
	global_load_lds_dwordx4 v[236:237], off
	s_mov_b32 m0, s41
	s_nop 0
	global_load_lds_dwordx4 v[238:239], off
	s_waitcnt vmcnt(8)
	s_waitcnt lgkmcnt(0)
	s_setprio 1
	s_barrier
; #define PG8_STAGE(bufoff, gbase, voff) do { _Pragma("unroll") for (int _i = 0; _i < 2; ++_i) \
;         __builtin_amdgcn_global_load_lds((const unsigned*)((const char*)(gbase) + (voff)[_i]), (PG8_LAS unsigned*)(lds + (bufoff) + ldsw + _i * 8192), 16, 0, 0); } while (0)
; #define PG8_LDA(dst, b, h) do { _Pragma("unroll") for (int m = 0; m < 4; ++m) _Pragma("unroll") for (int k = 0; k < 2; ++k) dst[m][k] = *(const PG8_LAS bf16x8*)(lds + PG8_SA(b, h) + aoff + m * 2048 + k * 1024); } while (0)
; #define PG8_LDB(dst, b, h) do { _Pragma("unroll") for (int n = 0; n < 2; ++n) _Pragma("unroll") for (int k = 0; k < 2; ++k) dst[n][k] = *(const PG8_LAS bf16x8*)(lds + PG8_SB(b, h) + boff + n * 2048 + k * 1024); } while (0)
; #define PG8_MMA(ai, bj, At, Bt) do { __builtin_amdgcn_s_setprio(1); _Pragma("unroll") for (int m = 0; m < 4; ++m) _Pragma("unroll") for (int n = 0; n < 2; ++n) _Pragma("unroll") for (int k = 0; k < 2; ++k) \
;         acc[ai][bj][m][n] = __builtin_amdgcn_mfma_f32_16x16x32_bf16(Bt[n][k], At[m][k], acc[ai][bj][m][n], 0, 0, 0); __builtin_amdgcn_s_setprio(0); } while (0)
; #define PG8_WAIT_V(n) asm volatile("s_waitcnt vmcnt(" #n ")" ::: "memory")
; #define PG8_WAIT_L(n) asm volatile("s_waitcnt lgkmcnt(" #n ")" ::: "memory")
; #define PG8_BAR __builtin_amdgcn_s_barrier()
; #define PG8_SCHED __builtin_amdgcn_sched_barrier(0)
; template <class Epi, class Sched, bool ALIGN_EPI = false, bool SP2 = false>
; __device__ __forceinline__ void gemm_phase(PG8_LAS unsigned char* lds, const Gemm g, const Sched& S, const Epi& E, const int tid_arg) {
;     ...
;             PG8_WAIT_V(8); PG8_WAIT_L(0); PG8_BAR; PG8_MMA(1, 0, At, B0); PG8_MMA(1, 1, At, B1); PG8_BAR; PG8_SCHED;
;             PG8_LDB(B0, 1, 0); PG8_LDB(B1, 1, 1); PG8_SCHED; PG8_LDA(At, 1, 0); PG8_STAGE(PG8_SA(0, 1), a2 + hstep, voffA);
;             PG8_WAIT_V(8); PG8_WAIT_L(0); PG8_BAR; PG8_MMA(0, 0, At, B0); PG8_MMA(0, 1, At, B1); PG8_BAR; PG8_SCHED;
	v_mfma_f32_16x16x32_bf16 v[60:63], v[144:147], v[196:199], v[60:63]
	v_mfma_f32_16x16x32_bf16 v[56:59], v[172:175], v[196:199], v[56:59]
	v_mfma_f32_16x16x32_bf16 v[44:47], v[144:147], v[204:207], v[44:47]
	v_mfma_f32_16x16x32_bf16 v[40:43], v[172:175], v[204:207], v[40:43]
	v_mfma_f32_16x16x32_bf16 v[28:31], v[144:147], v[212:215], v[28:31]
	v_mfma_f32_16x16x32_bf16 v[24:27], v[172:175], v[212:215], v[24:27]
	v_mfma_f32_16x16x32_bf16 v[12:15], v[144:147], v[220:223], v[12:15]
	v_mfma_f32_16x16x32_bf16 v[8:11], v[172:175], v[220:223], v[8:11]
	v_mfma_f32_16x16x32_bf16 v[60:63], v[168:171], v[200:203], v[60:63]
	v_mfma_f32_16x16x32_bf16 v[56:59], v[176:179], v[200:203], v[56:59]
	v_mfma_f32_16x16x32_bf16 v[44:47], v[168:171], v[208:211], v[44:47]
	v_mfma_f32_16x16x32_bf16 v[40:43], v[176:179], v[208:211], v[40:43]
	v_mfma_f32_16x16x32_bf16 v[28:31], v[168:171], v[216:219], v[28:31]
	v_mfma_f32_16x16x32_bf16 v[24:27], v[176:179], v[216:219], v[24:27]
	v_mfma_f32_16x16x32_bf16 v[12:15], v[168:171], v[224:227], v[12:15]
	v_mfma_f32_16x16x32_bf16 v[8:11], v[176:179], v[224:227], v[8:11]
	s_setprio 0
	s_setprio 1
	v_mfma_f32_16x16x32_bf16 v[52:55], v[180:183], v[196:199], v[52:55]
	v_mfma_f32_16x16x32_bf16 v[48:51], v[188:191], v[196:199], v[48:51]
	v_mfma_f32_16x16x32_bf16 v[36:39], v[180:183], v[204:207], v[36:39]
	v_mfma_f32_16x16x32_bf16 v[32:35], v[188:191], v[204:207], v[32:35]
	v_mfma_f32_16x16x32_bf16 v[20:23], v[180:183], v[212:215], v[20:23]
	v_mfma_f32_16x16x32_bf16 v[16:19], v[188:191], v[212:215], v[16:19]
	v_mfma_f32_16x16x32_bf16 v[4:7], v[180:183], v[220:223], v[4:7]
	v_mfma_f32_16x16x32_bf16 v[0:3], v[188:191], v[220:223], v[0:3]
	v_mfma_f32_16x16x32_bf16 v[52:55], v[184:187], v[200:203], v[52:55]
	v_mfma_f32_16x16x32_bf16 v[48:51], v[192:195], v[200:203], v[48:51]
	v_mfma_f32_16x16x32_bf16 v[36:39], v[184:187], v[208:211], v[36:39]
	v_mfma_f32_16x16x32_bf16 v[32:35], v[192:195], v[208:211], v[32:35]
	v_mfma_f32_16x16x32_bf16 v[20:23], v[184:187], v[216:219], v[20:23]
	v_mfma_f32_16x16x32_bf16 v[16:19], v[192:195], v[216:219], v[16:19]
	v_mfma_f32_16x16x32_bf16 v[4:7], v[184:187], v[224:227], v[4:7]
	v_mfma_f32_16x16x32_bf16 v[0:3], v[192:195], v[224:227], v[0:3]
	s_barrier
	s_setprio 0
	ds_read_b128 v[144:147], v159
	ds_read_b128 v[168:171], v160
	ds_read_b128 v[172:175], v161
	ds_read_b128 v[176:179], v162
	ds_read_b128 v[180:183], v163
	ds_read_b128 v[184:187], v164
	ds_read_b128 v[188:191], v165
	ds_read_b128 v[192:195], v166
	s_add_u32 s0, s0, s6
	s_addc_u32 s1, s1, s7
	s_mov_b32 m0, s42
	v_lshl_add_u64 v[240:241], s[0:1], 0, v[128:129]
	ds_read_b128 v[196:199], v150 offset:32768
	ds_read_b128 v[200:203], v150 offset:33792
	ds_read_b128 v[204:207], v150 offset:34816
	ds_read_b128 v[208:211], v150 offset:35840
	ds_read_b128 v[212:215], v150 offset:36864
	ds_read_b128 v[216:219], v150 offset:37888
	ds_read_b128 v[220:223], v150 offset:38912
	ds_read_b128 v[224:227], v150 offset:39936
	global_load_lds_dwordx4 v[240:241], off
	v_lshl_add_u64 v[240:241], s[0:1], 0, v[132:133]
	s_mov_b32 m0, s43
	s_nop 0
	global_load_lds_dwordx4 v[240:241], off
	s_waitcnt vmcnt(8)
	s_waitcnt lgkmcnt(0)
	s_setprio 1
	s_barrier
	v_mfma_f32_16x16x32_bf16 v[124:127], v[144:147], v[196:199], v[124:127]
	v_mfma_f32_16x16x32_bf16 v[120:123], v[172:175], v[196:199], v[120:123]
	v_mfma_f32_16x16x32_bf16 v[108:111], v[144:147], v[204:207], v[108:111]
	v_mfma_f32_16x16x32_bf16 v[104:107], v[172:175], v[204:207], v[104:107]
	v_mfma_f32_16x16x32_bf16 v[92:95], v[144:147], v[212:215], v[92:95]
	v_mfma_f32_16x16x32_bf16 v[88:91], v[172:175], v[212:215], v[88:91]
	v_mfma_f32_16x16x32_bf16 v[76:79], v[144:147], v[220:223], v[76:79]
	v_mfma_f32_16x16x32_bf16 v[72:75], v[172:175], v[220:223], v[72:75]
	v_mfma_f32_16x16x32_bf16 v[124:127], v[168:171], v[200:203], v[124:127]
	v_mfma_f32_16x16x32_bf16 v[120:123], v[176:179], v[200:203], v[120:123]
	v_mfma_f32_16x16x32_bf16 v[108:111], v[168:171], v[208:211], v[108:111]
	v_mfma_f32_16x16x32_bf16 v[104:107], v[176:179], v[208:211], v[104:107]
	v_mfma_f32_16x16x32_bf16 v[92:95], v[168:171], v[216:219], v[92:95]
	v_mfma_f32_16x16x32_bf16 v[88:91], v[176:179], v[216:219], v[88:91]
	v_mfma_f32_16x16x32_bf16 v[76:79], v[168:171], v[224:227], v[76:79]
	v_mfma_f32_16x16x32_bf16 v[72:75], v[176:179], v[224:227], v[72:75]
	s_setprio 0
	s_setprio 1
	v_mfma_f32_16x16x32_bf16 v[116:119], v[180:183], v[196:199], v[116:119]
	v_mfma_f32_16x16x32_bf16 v[112:115], v[188:191], v[196:199], v[112:115]
	v_mfma_f32_16x16x32_bf16 v[100:103], v[180:183], v[204:207], v[100:103]
	v_mfma_f32_16x16x32_bf16 v[96:99], v[188:191], v[204:207], v[96:99]
	v_mfma_f32_16x16x32_bf16 v[84:87], v[180:183], v[212:215], v[84:87]
	v_mfma_f32_16x16x32_bf16 v[80:83], v[188:191], v[212:215], v[80:83]
	v_mfma_f32_16x16x32_bf16 v[68:71], v[180:183], v[220:223], v[68:71]
	v_mfma_f32_16x16x32_bf16 v[64:67], v[188:191], v[220:223], v[64:67]
	v_mfma_f32_16x16x32_bf16 v[116:119], v[184:187], v[200:203], v[116:119]
	v_mfma_f32_16x16x32_bf16 v[112:115], v[192:195], v[200:203], v[112:115]
	v_mfma_f32_16x16x32_bf16 v[100:103], v[184:187], v[208:211], v[100:103]
	v_mfma_f32_16x16x32_bf16 v[96:99], v[192:195], v[208:211], v[96:99]
	v_mfma_f32_16x16x32_bf16 v[84:87], v[184:187], v[216:219], v[84:87]
	v_mfma_f32_16x16x32_bf16 v[80:83], v[192:195], v[216:219], v[80:83]
	v_mfma_f32_16x16x32_bf16 v[68:71], v[184:187], v[224:227], v[68:71]
	v_mfma_f32_16x16x32_bf16 v[64:67], v[192:195], v[224:227], v[64:67]
	s_barrier
; #define PG8_STAGE(bufoff, gbase, voff) do { _Pragma("unroll") for (int _i = 0; _i < 2; ++_i) \
;         __builtin_amdgcn_global_load_lds((const unsigned*)((const char*)(gbase) + (voff)[_i]), (PG8_LAS unsigned*)(lds + (bufoff) + ldsw + _i * 8192), 16, 0, 0); } while (0)
; #define PG8_LDA(dst, b, h) do { _Pragma("unroll") for (int m = 0; m < 4; ++m) _Pragma("unroll") for (int k = 0; k < 2; ++k) dst[m][k] = *(const PG8_LAS bf16x8*)(lds + PG8_SA(b, h) + aoff + m * 2048 + k * 1024); } while (0)
; #define PG8_MMA(ai, bj, At, Bt) do { __builtin_amdgcn_s_setprio(1); _Pragma("unroll") for (int m = 0; m < 4; ++m) _Pragma("unroll") for (int n = 0; n < 2; ++n) _Pragma("unroll") for (int k = 0; k < 2; ++k) \
;         acc[ai][bj][m][n] = __builtin_amdgcn_mfma_f32_16x16x32_bf16(Bt[n][k], At[m][k], acc[ai][bj][m][n], 0, 0, 0); __builtin_amdgcn_s_setprio(0); } while (0)
; #define PG8_WAIT_V(n) asm volatile("s_waitcnt vmcnt(" #n ")" ::: "memory")
; #define PG8_WAIT_L(n) asm volatile("s_waitcnt lgkmcnt(" #n ")" ::: "memory")
; #define PG8_BAR __builtin_amdgcn_s_barrier()
; #define PG8_SCHED __builtin_amdgcn_sched_barrier(0)
; template <class Epi, class Sched, bool ALIGN_EPI = false, bool SP2 = false>
; __device__ __forceinline__ void gemm_phase(PG8_LAS unsigned char* lds, const Gemm g, const Sched& S, const Epi& E, const int tid_arg) {
;     ...
;             PG8_WAIT_V(8); PG8_WAIT_L(0); PG8_BAR; PG8_MMA(0, 0, At, B0); PG8_MMA(0, 1, At, B1); PG8_BAR; PG8_SCHED;
;             PG8_LDA(At, 1, 1); PG8_STAGE(PG8_SB(1, 0), b3, voffB); PG8_STAGE(PG8_SB(1, 1), b3 + hstep, voffB); PG8_STAGE(PG8_SA(1, 0), a3, voffA);
;             PG8_WAIT_V(8); PG8_WAIT_L(0); PG8_BAR; PG8_MMA(1, 0, At, B0); PG8_MMA(1, 1, At, B1); PG8_BAR; PG8_SCHED;
	s_setprio 0
	s_mov_b32 m0, s44
	v_lshl_add_u64 v[228:229], v[228:229], 0, s[22:23]
	ds_read_b128 v[196:199], v150 offset:49152
	ds_read_b128 v[200:203], v150 offset:50176
	ds_read_b128 v[204:207], v150 offset:51200
	ds_read_b128 v[208:211], v150 offset:52224
	ds_read_b128 v[212:215], v150 offset:53248
	ds_read_b128 v[216:219], v150 offset:54272
	ds_read_b128 v[220:223], v150 offset:55296
	ds_read_b128 v[224:227], v150 offset:56320
	global_load_lds_dwordx4 v[228:229], off
	v_lshl_add_u64 v[228:229], v[230:231], 0, s[22:23]
	s_mov_b32 m0, s45
	s_nop 0
	global_load_lds_dwordx4 v[228:229], off
	v_lshl_add_u64 v[228:229], v[232:233], 0, s[22:23]
	s_mov_b32 m0, s48
	s_nop 0
	global_load_lds_dwordx4 v[228:229], off
	v_lshl_add_u64 v[228:229], v[234:235], 0, s[22:23]
	s_mov_b32 m0, s49
	s_nop 0
	global_load_lds_dwordx4 v[228:229], off
	v_lshl_add_u64 v[228:229], v[236:237], 0, s[22:23]
	s_mov_b32 m0, s46
	s_nop 0
	global_load_lds_dwordx4 v[228:229], off
	v_lshl_add_u64 v[228:229], v[238:239], 0, s[22:23]
	s_mov_b32 m0, s47
	s_nop 0
	global_load_lds_dwordx4 v[228:229], off
	s_waitcnt vmcnt(8)
	s_waitcnt lgkmcnt(0)
	s_setprio 1
	s_barrier
	v_mfma_f32_16x16x32_bf16 v[60:63], v[144:147], v[196:199], v[60:63]
	v_mfma_f32_16x16x32_bf16 v[56:59], v[172:175], v[196:199], v[56:59]
	v_mfma_f32_16x16x32_bf16 v[44:47], v[144:147], v[204:207], v[44:47]
	v_mfma_f32_16x16x32_bf16 v[40:43], v[172:175], v[204:207], v[40:43]
	v_mfma_f32_16x16x32_bf16 v[28:31], v[144:147], v[212:215], v[28:31]
	v_mfma_f32_16x16x32_bf16 v[24:27], v[172:175], v[212:215], v[24:27]
	v_mfma_f32_16x16x32_bf16 v[12:15], v[144:147], v[220:223], v[12:15]
	v_mfma_f32_16x16x32_bf16 v[8:11], v[172:175], v[220:223], v[8:11]
	v_mfma_f32_16x16x32_bf16 v[60:63], v[168:171], v[200:203], v[60:63]
	v_mfma_f32_16x16x32_bf16 v[56:59], v[176:179], v[200:203], v[56:59]
	v_mfma_f32_16x16x32_bf16 v[44:47], v[168:171], v[208:211], v[44:47]
	v_mfma_f32_16x16x32_bf16 v[40:43], v[176:179], v[208:211], v[40:43]
	v_mfma_f32_16x16x32_bf16 v[28:31], v[168:171], v[216:219], v[28:31]
	v_mfma_f32_16x16x32_bf16 v[24:27], v[176:179], v[216:219], v[24:27]
	v_mfma_f32_16x16x32_bf16 v[12:15], v[168:171], v[224:227], v[12:15]
	v_mfma_f32_16x16x32_bf16 v[8:11], v[176:179], v[224:227], v[8:11]
	s_setprio 0
	s_setprio 1
	v_mfma_f32_16x16x32_bf16 v[52:55], v[180:183], v[196:199], v[52:55]
	v_mfma_f32_16x16x32_bf16 v[48:51], v[188:191], v[196:199], v[48:51]
	v_mfma_f32_16x16x32_bf16 v[36:39], v[180:183], v[204:207], v[36:39]
	v_mfma_f32_16x16x32_bf16 v[32:35], v[188:191], v[204:207], v[32:35]
	v_mfma_f32_16x16x32_bf16 v[20:23], v[180:183], v[212:215], v[20:23]
	v_mfma_f32_16x16x32_bf16 v[16:19], v[188:191], v[212:215], v[16:19]
	v_mfma_f32_16x16x32_bf16 v[4:7], v[180:183], v[220:223], v[4:7]
	v_mfma_f32_16x16x32_bf16 v[0:3], v[188:191], v[220:223], v[0:3]
	v_mfma_f32_16x16x32_bf16 v[52:55], v[184:187], v[200:203], v[52:55]
	v_mfma_f32_16x16x32_bf16 v[48:51], v[192:195], v[200:203], v[48:51]
	v_mfma_f32_16x16x32_bf16 v[36:39], v[184:187], v[208:211], v[36:39]
	v_mfma_f32_16x16x32_bf16 v[32:35], v[192:195], v[208:211], v[32:35]
	v_mfma_f32_16x16x32_bf16 v[20:23], v[184:187], v[216:219], v[20:23]
	v_mfma_f32_16x16x32_bf16 v[16:19], v[192:195], v[216:219], v[16:19]
	v_mfma_f32_16x16x32_bf16 v[4:7], v[184:187], v[224:227], v[4:7]
	v_mfma_f32_16x16x32_bf16 v[0:3], v[192:195], v[224:227], v[0:3]
	s_barrier
	s_setprio 0
	s_add_u32 s60, s60, 0x100
	s_addc_u32 s61, s61, 0
	s_add_u32 s4, s4, 0x100
	s_addc_u32 s5, s5, 0
	s_cmp_ge_i32 s30, s50
	s_mov_b32 s0, s30
	s_cbranch_scc0 .LBB0_1046

; #define PG8_STAGE(bufoff, gbase, voff) do { _Pragma("unroll") for (int _i = 0; _i < 2; ++_i) \
;         __builtin_amdgcn_global_load_lds((const unsigned*)((const char*)(gbase) + (voff)[_i]), (PG8_LAS unsigned*)(lds + (bufoff) + ldsw + _i * 8192), 16, 0, 0); } while (0)
; #define PG8_LDA(dst, b, h) do { _Pragma("unroll") for (int m = 0; m < 4; ++m) _Pragma("unroll") for (int k = 0; k < 2; ++k) dst[m][k] = *(const PG8_LAS bf16x8*)(lds + PG8_SA(b, h) + aoff + m * 2048 + k * 1024); } while (0)
; #define PG8_LDB(dst, b, h) do { _Pragma("unroll") for (int n = 0; n < 2; ++n) _Pragma("unroll") for (int k = 0; k < 2; ++k) dst[n][k] = *(const PG8_LAS bf16x8*)(lds + PG8_SB(b, h) + boff + n * 2048 + k * 1024); } while (0)
; #define PG8_MMA(ai, bj, At, Bt) do { __builtin_amdgcn_s_setprio(1); _Pragma("unroll") for (int m = 0; m < 4; ++m) _Pragma("unroll") for (int n = 0; n < 2; ++n) _Pragma("unroll") for (int k = 0; k < 2; ++k) \
;         acc[ai][bj][m][n] = __builtin_amdgcn_mfma_f32_16x16x32_bf16(Bt[n][k], At[m][k], acc[ai][bj][m][n], 0, 0, 0); __builtin_amdgcn_s_setprio(0); } while (0)
; #define PG8_WAIT_V(n) asm volatile("s_waitcnt vmcnt(" #n ")" ::: "memory")
; #define PG8_WAIT_L(n) asm volatile("s_waitcnt lgkmcnt(" #n ")" ::: "memory")
; #define PG8_BAR __builtin_amdgcn_s_barrier()
; #define PG8_SCHED __builtin_amdgcn_sched_barrier(0)
; template <class Epi, class Sched, bool ALIGN_EPI = false, bool SP2 = false>
; __device__ __forceinline__ void gemm_phase(PG8_LAS unsigned char* lds, const Gemm g, const Sched& S, const Epi& E, const int tid_arg) {
;     ...
;             PG8_LDB(B0, 0, 0); PG8_LDB(B1, 0, 1); PG8_SCHED; PG8_LDA(At, 0, 0); PG8_STAGE(PG8_SA(1, 1), a1 + hstep, voffA);
;             PG8_WAIT_V(8); PG8_WAIT_L(0); PG8_BAR; PG8_MMA(0, 0, At, B0); PG8_MMA(0, 1, At, B1); PG8_BAR; PG8_SCHED;
;             PG8_LDA(At, 0, 1); PG8_STAGE(PG8_SB(0, 0), b2, voffB); PG8_STAGE(PG8_SB(0, 1), b2 + hstep, voffB); PG8_STAGE(PG8_SA(0, 0), a2, voffA);
;             PG8_WAIT_V(8); PG8_WAIT_L(0); PG8_BAR; PG8_MMA(1, 0, At, B0); PG8_MMA(1, 1, At, B1); PG8_BAR; PG8_SCHED;
.LBB0_1179:
	ds_read_b128 v[144:147], v166
	ds_read_b128 v[148:151], v167
	ds_read_b128 v[152:155], v168
	ds_read_b128 v[156:159], v169
	ds_read_b128 v[184:187], v170
	ds_read_b128 v[188:191], v171
	ds_read_b128 v[192:195], v172
	ds_read_b128 v[196:199], v173
	s_add_u32 s0, s4, 0xfffc0080
	s_addc_u32 s1, s5, -1
	s_cmp_eq_u32 s68, 12
	s_cselect_b32 s11, s25, s1
	s_cselect_b32 s10, s36, s0
	s_cselect_b32 s1, s23, s67
	s_cselect_b32 s0, s37, s66
	s_mov_b32 m0, s55
	v_lshl_add_u64 v[160:161], s[4:5], 0, v[138:139]
	ds_read_b128 v[200:203], v165
	ds_read_b128 v[204:207], v165 offset:1024
	ds_read_b128 v[208:211], v165 offset:2048
	ds_read_b128 v[212:215], v165 offset:3072
	ds_read_b128 v[216:219], v165 offset:4096
	ds_read_b128 v[220:223], v165 offset:5120
	ds_read_b128 v[224:227], v165 offset:6144
	ds_read_b128 v[228:231], v165 offset:7168
	global_load_lds_dwordx4 v[160:161], off
	v_lshl_add_u64 v[160:161], s[4:5], 0, v[136:137]
	s_mov_b32 m0, s56
	s_nop 0
	global_load_lds_dwordx4 v[160:161], off
	s_waitcnt vmcnt(8)
	s_waitcnt lgkmcnt(0)
	s_setprio 1
	s_barrier
	v_mfma_f32_16x16x32_bf16 v[124:127], v[144:147], v[200:203], v[124:127]
	v_mfma_f32_16x16x32_bf16 v[120:123], v[152:155], v[200:203], v[120:123]
	v_mfma_f32_16x16x32_bf16 v[108:111], v[144:147], v[208:211], v[108:111]
	v_mfma_f32_16x16x32_bf16 v[104:107], v[152:155], v[208:211], v[104:107]
	v_mfma_f32_16x16x32_bf16 v[92:95], v[144:147], v[216:219], v[92:95]
	v_mfma_f32_16x16x32_bf16 v[88:91], v[152:155], v[216:219], v[88:91]
	v_mfma_f32_16x16x32_bf16 v[76:79], v[144:147], v[224:227], v[76:79]
	v_mfma_f32_16x16x32_bf16 v[72:75], v[152:155], v[224:227], v[72:75]
	v_mfma_f32_16x16x32_bf16 v[124:127], v[148:151], v[204:207], v[124:127]
	v_mfma_f32_16x16x32_bf16 v[120:123], v[156:159], v[204:207], v[120:123]
	v_mfma_f32_16x16x32_bf16 v[108:111], v[148:151], v[212:215], v[108:111]
	v_mfma_f32_16x16x32_bf16 v[104:107], v[156:159], v[212:215], v[104:107]
	v_mfma_f32_16x16x32_bf16 v[92:95], v[148:151], v[220:223], v[92:95]
	v_mfma_f32_16x16x32_bf16 v[88:91], v[156:159], v[220:223], v[88:91]
	v_mfma_f32_16x16x32_bf16 v[76:79], v[148:151], v[228:231], v[76:79]
	v_mfma_f32_16x16x32_bf16 v[72:75], v[156:159], v[228:231], v[72:75]
	s_setprio 0
	s_setprio 1
	v_mfma_f32_16x16x32_bf16 v[116:119], v[184:187], v[200:203], v[116:119]
	v_mfma_f32_16x16x32_bf16 v[112:115], v[192:195], v[200:203], v[112:115]
	v_mfma_f32_16x16x32_bf16 v[100:103], v[184:187], v[208:211], v[100:103]
	v_mfma_f32_16x16x32_bf16 v[96:99], v[192:195], v[208:211], v[96:99]
	v_mfma_f32_16x16x32_bf16 v[84:87], v[184:187], v[216:219], v[84:87]
	v_mfma_f32_16x16x32_bf16 v[80:83], v[192:195], v[216:219], v[80:83]
	v_mfma_f32_16x16x32_bf16 v[68:71], v[184:187], v[224:227], v[68:71]
	v_mfma_f32_16x16x32_bf16 v[64:67], v[192:195], v[224:227], v[64:67]
	v_mfma_f32_16x16x32_bf16 v[116:119], v[188:191], v[204:207], v[116:119]
	v_mfma_f32_16x16x32_bf16 v[112:115], v[196:199], v[204:207], v[112:115]
	v_mfma_f32_16x16x32_bf16 v[100:103], v[188:191], v[212:215], v[100:103]
	v_mfma_f32_16x16x32_bf16 v[96:99], v[196:199], v[212:215], v[96:99]
	v_mfma_f32_16x16x32_bf16 v[84:87], v[188:191], v[220:223], v[84:87]
	v_mfma_f32_16x16x32_bf16 v[80:83], v[196:199], v[220:223], v[80:83]
	v_mfma_f32_16x16x32_bf16 v[68:71], v[188:191], v[228:231], v[68:71]
	v_mfma_f32_16x16x32_bf16 v[64:67], v[196:199], v[228:231], v[64:67]
	s_barrier
	s_setprio 0
	s_mov_b32 m0, s31
	v_lshl_add_u64 v[160:161], s[0:1], 0, v[130:131]
	s_add_u32 s70, s0, 0x40000
	ds_read_b128 v[200:203], v165 offset:16384
	ds_read_b128 v[204:207], v165 offset:17408
	ds_read_b128 v[208:211], v165 offset:18432
	ds_read_b128 v[212:215], v165 offset:19456
	ds_read_b128 v[216:219], v165 offset:20480
	ds_read_b128 v[220:223], v165 offset:21504
	ds_read_b128 v[224:227], v165 offset:22528
	ds_read_b128 v[228:231], v165 offset:23552
	global_load_lds_dwordx4 v[160:161], off
	v_lshl_add_u64 v[232:233], s[0:1], 0, v[134:135]
	s_mov_b32 m0, s35
	s_addc_u32 s71, s1, 0
	global_load_lds_dwordx4 v[232:233], off
	v_lshl_add_u64 v[234:235], s[70:71], 0, v[130:131]
	s_mov_b32 m0, s40
	v_lshl_add_u64 v[236:237], s[10:11], 0, v[132:133]
	global_load_lds_dwordx4 v[234:235], off
	v_lshl_add_u64 v[234:235], s[70:71], 0, v[134:135]
	s_mov_b32 m0, s41
	s_nop 0
	global_load_lds_dwordx4 v[234:235], off
	v_lshl_add_u64 v[234:235], s[10:11], 0, v[128:129]
	s_mov_b32 m0, s39
	s_nop 0
	global_load_lds_dwordx4 v[234:235], off
	s_mov_b32 m0, s42
	s_nop 0
	global_load_lds_dwordx4 v[236:237], off
	s_waitcnt vmcnt(8)
	s_waitcnt lgkmcnt(0)
	s_setprio 1
	s_barrier
; #define PG8_STAGE(bufoff, gbase, voff) do { _Pragma("unroll") for (int _i = 0; _i < 2; ++_i) \
;         __builtin_amdgcn_global_load_lds((const unsigned*)((const char*)(gbase) + (voff)[_i]), (PG8_LAS unsigned*)(lds + (bufoff) + ldsw + _i * 8192), 16, 0, 0); } while (0)
; #define PG8_LDA(dst, b, h) do { _Pragma("unroll") for (int m = 0; m < 4; ++m) _Pragma("unroll") for (int k = 0; k < 2; ++k) dst[m][k] = *(const PG8_LAS bf16x8*)(lds + PG8_SA(b, h) + aoff + m * 2048 + k * 1024); } while (0)
; #define PG8_LDB(dst, b, h) do { _Pragma("unroll") for (int n = 0; n < 2; ++n) _Pragma("unroll") for (int k = 0; k < 2; ++k) dst[n][k] = *(const PG8_LAS bf16x8*)(lds + PG8_SB(b, h) + boff + n * 2048 + k * 1024); } while (0)
; #define PG8_MMA(ai, bj, At, Bt) do { __builtin_amdgcn_s_setprio(1); _Pragma("unroll") for (int m = 0; m < 4; ++m) _Pragma("unroll") for (int n = 0; n < 2; ++n) _Pragma("unroll") for (int k = 0; k < 2; ++k) \
;         acc[ai][bj][m][n] = __builtin_amdgcn_mfma_f32_16x16x32_bf16(Bt[n][k], At[m][k], acc[ai][bj][m][n], 0, 0, 0); __builtin_amdgcn_s_setprio(0); } while (0)
; #define PG8_WAIT_V(n) asm volatile("s_waitcnt vmcnt(" #n ")" ::: "memory")
; #define PG8_WAIT_L(n) asm volatile("s_waitcnt lgkmcnt(" #n ")" ::: "memory")
; #define PG8_BAR __builtin_amdgcn_s_barrier()
; #define PG8_SCHED __builtin_amdgcn_sched_barrier(0)
; template <class Epi, class Sched, bool ALIGN_EPI = false, bool SP2 = false>
; __device__ __forceinline__ void gemm_phase(PG8_LAS unsigned char* lds, const Gemm g, const Sched& S, const Epi& E, const int tid_arg) {
;     ...
;             PG8_WAIT_V(8); PG8_WAIT_L(0); PG8_BAR; PG8_MMA(1, 0, At, B0); PG8_MMA(1, 1, At, B1); PG8_BAR; PG8_SCHED;
;             PG8_LDB(B0, 1, 0); PG8_LDB(B1, 1, 1); PG8_SCHED; PG8_LDA(At, 1, 0); PG8_STAGE(PG8_SA(0, 1), a2 + hstep, voffA);
;             PG8_WAIT_V(8); PG8_WAIT_L(0); PG8_BAR; PG8_MMA(0, 0, At, B0); PG8_MMA(0, 1, At, B1); PG8_BAR; PG8_SCHED;
	v_mfma_f32_16x16x32_bf16 v[60:63], v[144:147], v[200:203], v[60:63]
	v_mfma_f32_16x16x32_bf16 v[56:59], v[152:155], v[200:203], v[56:59]
	v_mfma_f32_16x16x32_bf16 v[44:47], v[144:147], v[208:211], v[44:47]
	v_mfma_f32_16x16x32_bf16 v[40:43], v[152:155], v[208:211], v[40:43]
	v_mfma_f32_16x16x32_bf16 v[28:31], v[144:147], v[216:219], v[28:31]
	v_mfma_f32_16x16x32_bf16 v[24:27], v[152:155], v[216:219], v[24:27]
	v_mfma_f32_16x16x32_bf16 v[12:15], v[144:147], v[224:227], v[12:15]
	v_mfma_f32_16x16x32_bf16 v[8:11], v[152:155], v[224:227], v[8:11]
	v_mfma_f32_16x16x32_bf16 v[60:63], v[148:151], v[204:207], v[60:63]
	v_mfma_f32_16x16x32_bf16 v[56:59], v[156:159], v[204:207], v[56:59]
	v_mfma_f32_16x16x32_bf16 v[44:47], v[148:151], v[212:215], v[44:47]
	v_mfma_f32_16x16x32_bf16 v[40:43], v[156:159], v[212:215], v[40:43]
	v_mfma_f32_16x16x32_bf16 v[28:31], v[148:151], v[220:223], v[28:31]
	v_mfma_f32_16x16x32_bf16 v[24:27], v[156:159], v[220:223], v[24:27]
	v_mfma_f32_16x16x32_bf16 v[12:15], v[148:151], v[228:231], v[12:15]
	v_mfma_f32_16x16x32_bf16 v[8:11], v[156:159], v[228:231], v[8:11]
	s_setprio 0
	s_setprio 1
	v_mfma_f32_16x16x32_bf16 v[52:55], v[184:187], v[200:203], v[52:55]
	v_mfma_f32_16x16x32_bf16 v[48:51], v[192:195], v[200:203], v[48:51]
	v_mfma_f32_16x16x32_bf16 v[36:39], v[184:187], v[208:211], v[36:39]
	v_mfma_f32_16x16x32_bf16 v[32:35], v[192:195], v[208:211], v[32:35]
	v_mfma_f32_16x16x32_bf16 v[20:23], v[184:187], v[216:219], v[20:23]
	v_mfma_f32_16x16x32_bf16 v[16:19], v[192:195], v[216:219], v[16:19]
	v_mfma_f32_16x16x32_bf16 v[4:7], v[184:187], v[224:227], v[4:7]
	v_mfma_f32_16x16x32_bf16 v[0:3], v[192:195], v[224:227], v[0:3]
	v_mfma_f32_16x16x32_bf16 v[52:55], v[188:191], v[204:207], v[52:55]
	v_mfma_f32_16x16x32_bf16 v[48:51], v[196:199], v[204:207], v[48:51]
	v_mfma_f32_16x16x32_bf16 v[36:39], v[188:191], v[212:215], v[36:39]
	v_mfma_f32_16x16x32_bf16 v[32:35], v[196:199], v[212:215], v[32:35]
	v_mfma_f32_16x16x32_bf16 v[20:23], v[188:191], v[220:223], v[20:23]
	v_mfma_f32_16x16x32_bf16 v[16:19], v[196:199], v[220:223], v[16:19]
	v_mfma_f32_16x16x32_bf16 v[4:7], v[188:191], v[228:231], v[4:7]
	v_mfma_f32_16x16x32_bf16 v[0:3], v[196:199], v[228:231], v[0:3]
	s_barrier
	s_setprio 0
	ds_read_b128 v[144:147], v174
	ds_read_b128 v[148:151], v175
	ds_read_b128 v[152:155], v176
	ds_read_b128 v[156:159], v177
	ds_read_b128 v[184:187], v178
	ds_read_b128 v[188:191], v179
	ds_read_b128 v[192:195], v180
	ds_read_b128 v[196:199], v181
	s_add_u32 s10, s10, 0x40000
	s_addc_u32 s11, s11, 0
	s_mov_b32 m0, s43
	v_lshl_add_u64 v[238:239], s[10:11], 0, v[128:129]
	ds_read_b128 v[200:203], v165 offset:32768
	ds_read_b128 v[204:207], v165 offset:33792
	ds_read_b128 v[208:211], v165 offset:34816
	ds_read_b128 v[212:215], v165 offset:35840
	ds_read_b128 v[216:219], v165 offset:36864
	ds_read_b128 v[220:223], v165 offset:37888
	ds_read_b128 v[224:227], v165 offset:38912
	ds_read_b128 v[228:231], v165 offset:39936
	global_load_lds_dwordx4 v[238:239], off
	v_lshl_add_u64 v[238:239], s[10:11], 0, v[132:133]
	s_mov_b32 m0, s44
	s_nop 0
	global_load_lds_dwordx4 v[238:239], off
	s_waitcnt vmcnt(8)
	s_waitcnt lgkmcnt(0)
	s_setprio 1
	s_barrier
	v_mfma_f32_16x16x32_bf16 v[124:127], v[144:147], v[200:203], v[124:127]
	v_mfma_f32_16x16x32_bf16 v[120:123], v[152:155], v[200:203], v[120:123]
	v_mfma_f32_16x16x32_bf16 v[108:111], v[144:147], v[208:211], v[108:111]
	v_mfma_f32_16x16x32_bf16 v[104:107], v[152:155], v[208:211], v[104:107]
	v_mfma_f32_16x16x32_bf16 v[92:95], v[144:147], v[216:219], v[92:95]
	v_mfma_f32_16x16x32_bf16 v[88:91], v[152:155], v[216:219], v[88:91]
	v_mfma_f32_16x16x32_bf16 v[76:79], v[144:147], v[224:227], v[76:79]
	v_mfma_f32_16x16x32_bf16 v[72:75], v[152:155], v[224:227], v[72:75]
	v_mfma_f32_16x16x32_bf16 v[124:127], v[148:151], v[204:207], v[124:127]
	v_mfma_f32_16x16x32_bf16 v[120:123], v[156:159], v[204:207], v[120:123]
	v_mfma_f32_16x16x32_bf16 v[108:111], v[148:151], v[212:215], v[108:111]
	v_mfma_f32_16x16x32_bf16 v[104:107], v[156:159], v[212:215], v[104:107]
	v_mfma_f32_16x16x32_bf16 v[92:95], v[148:151], v[220:223], v[92:95]
	v_mfma_f32_16x16x32_bf16 v[88:91], v[156:159], v[220:223], v[88:91]
	v_mfma_f32_16x16x32_bf16 v[76:79], v[148:151], v[228:231], v[76:79]
	v_mfma_f32_16x16x32_bf16 v[72:75], v[156:159], v[228:231], v[72:75]
	s_setprio 0
	s_setprio 1
	v_mfma_f32_16x16x32_bf16 v[116:119], v[184:187], v[200:203], v[116:119]
	v_mfma_f32_16x16x32_bf16 v[112:115], v[192:195], v[200:203], v[112:115]
	v_mfma_f32_16x16x32_bf16 v[100:103], v[184:187], v[208:211], v[100:103]
	v_mfma_f32_16x16x32_bf16 v[96:99], v[192:195], v[208:211], v[96:99]
	v_mfma_f32_16x16x32_bf16 v[84:87], v[184:187], v[216:219], v[84:87]
	v_mfma_f32_16x16x32_bf16 v[80:83], v[192:195], v[216:219], v[80:83]
	v_mfma_f32_16x16x32_bf16 v[68:71], v[184:187], v[224:227], v[68:71]
	v_mfma_f32_16x16x32_bf16 v[64:67], v[192:195], v[224:227], v[64:67]
	v_mfma_f32_16x16x32_bf16 v[116:119], v[188:191], v[204:207], v[116:119]
	v_mfma_f32_16x16x32_bf16 v[112:115], v[196:199], v[204:207], v[112:115]
	v_mfma_f32_16x16x32_bf16 v[100:103], v[188:191], v[212:215], v[100:103]
	v_mfma_f32_16x16x32_bf16 v[96:99], v[196:199], v[212:215], v[96:99]
	v_mfma_f32_16x16x32_bf16 v[84:87], v[188:191], v[220:223], v[84:87]
	v_mfma_f32_16x16x32_bf16 v[80:83], v[196:199], v[220:223], v[80:83]
	v_mfma_f32_16x16x32_bf16 v[68:71], v[188:191], v[228:231], v[68:71]
	v_mfma_f32_16x16x32_bf16 v[64:67], v[196:199], v[228:231], v[64:67]
	s_barrier
; #define PG8_STAGE(bufoff, gbase, voff) do { _Pragma("unroll") for (int _i = 0; _i < 2; ++_i) \
;         __builtin_amdgcn_global_load_lds((const unsigned*)((const char*)(gbase) + (voff)[_i]), (PG8_LAS unsigned*)(lds + (bufoff) + ldsw + _i * 8192), 16, 0, 0); } while (0)
; #define PG8_LDA(dst, b, h) do { _Pragma("unroll") for (int m = 0; m < 4; ++m) _Pragma("unroll") for (int k = 0; k < 2; ++k) dst[m][k] = *(const PG8_LAS bf16x8*)(lds + PG8_SA(b, h) + aoff + m * 2048 + k * 1024); } while (0)
; #define PG8_MMA(ai, bj, At, Bt) do { __builtin_amdgcn_s_setprio(1); _Pragma("unroll") for (int m = 0; m < 4; ++m) _Pragma("unroll") for (int n = 0; n < 2; ++n) _Pragma("unroll") for (int k = 0; k < 2; ++k) \
;         acc[ai][bj][m][n] = __builtin_amdgcn_mfma_f32_16x16x32_bf16(Bt[n][k], At[m][k], acc[ai][bj][m][n], 0, 0, 0); __builtin_amdgcn_s_setprio(0); } while (0)
; #define PG8_WAIT_V(n) asm volatile("s_waitcnt vmcnt(" #n ")" ::: "memory")
; #define PG8_WAIT_L(n) asm volatile("s_waitcnt lgkmcnt(" #n ")" ::: "memory")
; #define PG8_BAR __builtin_amdgcn_s_barrier()
; #define PG8_SCHED __builtin_amdgcn_sched_barrier(0)
; template <class Epi, class Sched, bool ALIGN_EPI = false, bool SP2 = false>
; __device__ __forceinline__ void gemm_phase(PG8_LAS unsigned char* lds, const Gemm g, const Sched& S, const Epi& E, const int tid_arg) {
;     ...
;         for (int t = 0; t < nt; t += 2) {
;             const bool last = (t == nt - 2);
;     ...
;             PG8_LDA(At, 1, 1); PG8_STAGE(PG8_SB(1, 0), b3, voffB); PG8_STAGE(PG8_SB(1, 1), b3 + hstep, voffB); PG8_STAGE(PG8_SA(1, 0), a3, voffA);
;             PG8_WAIT_V(8); PG8_WAIT_L(0); PG8_BAR; PG8_MMA(1, 0, At, B0); PG8_MMA(1, 1, At, B1); PG8_BAR; PG8_SCHED;
;     ...
;         if constexpr (ALIGN_EPI) { if (wr == 0) PG8_BAR; }
	s_setprio 0
	s_mov_b32 m0, s47
	v_lshl_add_u64 v[160:161], v[160:161], 0, s[16:17]
	s_add_u32 s0, s0, 0x40080
	ds_read_b128 v[200:203], v165 offset:49152
	ds_read_b128 v[204:207], v165 offset:50176
	ds_read_b128 v[208:211], v165 offset:51200
	ds_read_b128 v[212:215], v165 offset:52224
	ds_read_b128 v[216:219], v165 offset:53248
	ds_read_b128 v[220:223], v165 offset:54272
	ds_read_b128 v[224:227], v165 offset:55296
	ds_read_b128 v[228:231], v165 offset:56320
	global_load_lds_dwordx4 v[160:161], off
	v_lshl_add_u64 v[160:161], v[232:233], 0, s[16:17]
	s_mov_b32 m0, s48
	s_addc_u32 s1, s1, 0
	global_load_lds_dwordx4 v[160:161], off
	v_lshl_add_u64 v[160:161], s[0:1], 0, v[130:131]
	s_mov_b32 m0, s51
	s_nop 0
	global_load_lds_dwordx4 v[160:161], off
	v_lshl_add_u64 v[160:161], s[0:1], 0, v[134:135]
	s_mov_b32 m0, s52
	s_nop 0
	global_load_lds_dwordx4 v[160:161], off
	v_lshl_add_u64 v[160:161], v[234:235], 0, s[16:17]
	s_mov_b32 m0, s49
	s_nop 0
	global_load_lds_dwordx4 v[160:161], off
	v_lshl_add_u64 v[160:161], v[236:237], 0, s[16:17]
	s_mov_b32 m0, s50
	s_nop 0
	global_load_lds_dwordx4 v[160:161], off
	s_waitcnt vmcnt(8)
	s_waitcnt lgkmcnt(0)
	s_setprio 1
	s_barrier
	v_mfma_f32_16x16x32_bf16 v[60:63], v[144:147], v[200:203], v[60:63]
	v_mfma_f32_16x16x32_bf16 v[56:59], v[152:155], v[200:203], v[56:59]
	v_mfma_f32_16x16x32_bf16 v[44:47], v[144:147], v[208:211], v[44:47]
	v_mfma_f32_16x16x32_bf16 v[40:43], v[152:155], v[208:211], v[40:43]
	v_mfma_f32_16x16x32_bf16 v[28:31], v[144:147], v[216:219], v[28:31]
	v_mfma_f32_16x16x32_bf16 v[24:27], v[152:155], v[216:219], v[24:27]
	v_mfma_f32_16x16x32_bf16 v[12:15], v[144:147], v[224:227], v[12:15]
	v_mfma_f32_16x16x32_bf16 v[8:11], v[152:155], v[224:227], v[8:11]
	v_mfma_f32_16x16x32_bf16 v[60:63], v[148:151], v[204:207], v[60:63]
	v_mfma_f32_16x16x32_bf16 v[56:59], v[156:159], v[204:207], v[56:59]
	v_mfma_f32_16x16x32_bf16 v[44:47], v[148:151], v[212:215], v[44:47]
	v_mfma_f32_16x16x32_bf16 v[40:43], v[156:159], v[212:215], v[40:43]
	v_mfma_f32_16x16x32_bf16 v[28:31], v[148:151], v[220:223], v[28:31]
	v_mfma_f32_16x16x32_bf16 v[24:27], v[156:159], v[220:223], v[24:27]
	v_mfma_f32_16x16x32_bf16 v[12:15], v[148:151], v[228:231], v[12:15]
	v_mfma_f32_16x16x32_bf16 v[8:11], v[156:159], v[228:231], v[8:11]
	s_setprio 0
	s_setprio 1
	v_mfma_f32_16x16x32_bf16 v[52:55], v[184:187], v[200:203], v[52:55]
	v_mfma_f32_16x16x32_bf16 v[48:51], v[192:195], v[200:203], v[48:51]
	v_mfma_f32_16x16x32_bf16 v[36:39], v[184:187], v[208:211], v[36:39]
	v_mfma_f32_16x16x32_bf16 v[32:35], v[192:195], v[208:211], v[32:35]
	v_mfma_f32_16x16x32_bf16 v[20:23], v[184:187], v[216:219], v[20:23]
	v_mfma_f32_16x16x32_bf16 v[16:19], v[192:195], v[216:219], v[16:19]
	v_mfma_f32_16x16x32_bf16 v[4:7], v[184:187], v[224:227], v[4:7]
	v_mfma_f32_16x16x32_bf16 v[0:3], v[192:195], v[224:227], v[0:3]
	v_mfma_f32_16x16x32_bf16 v[52:55], v[188:191], v[204:207], v[52:55]
	v_mfma_f32_16x16x32_bf16 v[48:51], v[196:199], v[204:207], v[48:51]
	v_mfma_f32_16x16x32_bf16 v[36:39], v[188:191], v[212:215], v[36:39]
	v_mfma_f32_16x16x32_bf16 v[32:35], v[196:199], v[212:215], v[32:35]
	v_mfma_f32_16x16x32_bf16 v[20:23], v[188:191], v[220:223], v[20:23]
	v_mfma_f32_16x16x32_bf16 v[16:19], v[196:199], v[220:223], v[16:19]
	v_mfma_f32_16x16x32_bf16 v[4:7], v[188:191], v[228:231], v[4:7]
	v_mfma_f32_16x16x32_bf16 v[0:3], v[196:199], v[228:231], v[0:3]
	s_barrier
	s_setprio 0
	s_add_i32 s68, s68, 2
	s_add_u32 s66, s66, 0x100
	s_addc_u32 s67, s67, 0
	s_add_u32 s4, s4, 0x100
	s_addc_u32 s5, s5, 0
	s_cmp_gt_u32 s68, 13
	s_cbranch_scc0 .LBB0_1179
	s_and_b64 vcc, exec, s[18:19]
	s_cbranch_vccz .LBB0_1182
	s_barrier

; #define PG8_STAGE(bufoff, gbase, voff) do { _Pragma("unroll") for (int _i = 0; _i < 2; ++_i) \
;         __builtin_amdgcn_global_load_lds((const unsigned*)((const char*)(gbase) + (voff)[_i]), (PG8_LAS unsigned*)(lds + (bufoff) + ldsw + _i * 8192), 16, 0, 0); } while (0)
; #define PG8_LDA(dst, b, h) do { _Pragma("unroll") for (int m = 0; m < 4; ++m) _Pragma("unroll") for (int k = 0; k < 2; ++k) dst[m][k] = *(const PG8_LAS bf16x8*)(lds + PG8_SA(b, h) + aoff + m * 2048 + k * 1024); } while (0)
; #define PG8_LDB(dst, b, h) do { _Pragma("unroll") for (int n = 0; n < 2; ++n) _Pragma("unroll") for (int k = 0; k < 2; ++k) dst[n][k] = *(const PG8_LAS bf16x8*)(lds + PG8_SB(b, h) + boff + n * 2048 + k * 1024); } while (0)
; #define PG8_WAIT_V(n) asm volatile("s_waitcnt vmcnt(" #n ")" ::: "memory")
; #define PG8_WAIT_L(n) asm volatile("s_waitcnt lgkmcnt(" #n ")" ::: "memory")
; #define PG8_BAR __builtin_amdgcn_s_barrier()
; #define PG8_SCHED __builtin_amdgcn_sched_barrier(0)
; template <class Epi, class Sched, bool ALIGN_EPI = false, bool SP2 = false>
; __device__ __forceinline__ void gemm_phase(PG8_LAS unsigned char* lds, const Gemm g, const Sched& S, const Epi& E, const int tid_arg) {
;     ...
;         const bool has_next = S.next(ui + 1, nxt);
;         const char* nA = has_next ? (const char*)g.A + (size_t)nxt.pm * tstep : cA; const char* nB = has_next ? (const char*)g.Bt + (size_t)nxt.pn * tstep : cB;
;         for (int t = 0; t < nt; t += 2) {
;             const bool last = (t == nt - 2);
;             const char* a1 = cA + (size_t)(t + 1) * kstep;
;             const char* a2 = last ? nA : cA + (size_t)(t + 2) * kstep; const char* b2 = last ? nB : cB + (size_t)(t + 2) * kstep;
;             const char* a3 = a2 + kstep; const char* b3 = b2 + kstep;
;             if (last && has_next) S.a_ready(nxt);
;             if constexpr (SP2) {
;             PG8_LDB(B0, 0, 0); PG8_LDB(B1, 0, 1); PG8_SCHED; PG8_LDA(At, 0, 0); PG8_STAGE(PG8_SA(1, 1), a1 + hstep, voffA);
;             PG8_WAIT_V(8); PG8_WAIT_L(0); PG8_BAR; PG8_MMA(0, 0, At, B0); PG8_MMA(0, 1, At, B1); PG8_BAR; PG8_SCHED;
;             PG8_LDA(At, 0, 1); PG8_STAGE(PG8_SB(0, 0), b2, voffB); PG8_STAGE(PG8_SB(0, 1), b2 + hstep, voffB); PG8_STAGE(PG8_SA(0, 0), a2, voffA);
;             PG8_WAIT_V(8); PG8_WAIT_L(0); PG8_BAR; PG8_MMA(1, 0, At, B0); PG8_MMA(1, 1, At, B1); PG8_BAR; PG8_SCHED;
.LBB0_1459:
	ds_read_b128 v[144:147], v151
	ds_read_b128 v[168:171], v152
	ds_read_b128 v[172:175], v153
	ds_read_b128 v[176:179], v154
	ds_read_b128 v[180:183], v155
	ds_read_b128 v[184:187], v156
	ds_read_b128 v[188:191], v157
	ds_read_b128 v[192:195], v158
	s_add_u32 s0, s28, 0xfffc0080
	s_addc_u32 s1, s29, -1
	s_cmp_eq_u32 s59, 12
	s_cselect_b32 s31, s21, s1
	s_cselect_b32 s30, s27, s0
	s_cselect_b32 s1, s19, s58
	s_cselect_b32 s0, s56, s57
	s_mov_b32 m0, s53
	v_lshl_add_u64 v[228:229], s[28:29], 0, v[138:139]
	ds_read_b128 v[196:199], v150
	ds_read_b128 v[200:203], v150 offset:1024
	ds_read_b128 v[204:207], v150 offset:2048
	ds_read_b128 v[208:211], v150 offset:3072
	ds_read_b128 v[212:215], v150 offset:4096
	ds_read_b128 v[216:219], v150 offset:5120
	ds_read_b128 v[220:223], v150 offset:6144
	ds_read_b128 v[224:227], v150 offset:7168
	global_load_lds_dwordx4 v[228:229], off
	v_lshl_add_u64 v[228:229], s[28:29], 0, v[136:137]
	s_mov_b32 m0, s54
	s_nop 0
	global_load_lds_dwordx4 v[228:229], off
	s_waitcnt vmcnt(8)
	s_waitcnt lgkmcnt(0)
	s_setprio 1
	s_barrier
	v_mfma_f32_16x16x32_bf16 v[124:127], v[144:147], v[196:199], v[124:127]
	v_mfma_f32_16x16x32_bf16 v[120:123], v[172:175], v[196:199], v[120:123]
	v_mfma_f32_16x16x32_bf16 v[108:111], v[144:147], v[204:207], v[108:111]
	v_mfma_f32_16x16x32_bf16 v[104:107], v[172:175], v[204:207], v[104:107]
	v_mfma_f32_16x16x32_bf16 v[92:95], v[144:147], v[212:215], v[92:95]
	v_mfma_f32_16x16x32_bf16 v[88:91], v[172:175], v[212:215], v[88:91]
	v_mfma_f32_16x16x32_bf16 v[76:79], v[144:147], v[220:223], v[76:79]
	v_mfma_f32_16x16x32_bf16 v[72:75], v[172:175], v[220:223], v[72:75]
	v_mfma_f32_16x16x32_bf16 v[124:127], v[168:171], v[200:203], v[124:127]
	v_mfma_f32_16x16x32_bf16 v[120:123], v[176:179], v[200:203], v[120:123]
	v_mfma_f32_16x16x32_bf16 v[108:111], v[168:171], v[208:211], v[108:111]
	v_mfma_f32_16x16x32_bf16 v[104:107], v[176:179], v[208:211], v[104:107]
	v_mfma_f32_16x16x32_bf16 v[92:95], v[168:171], v[216:219], v[92:95]
	v_mfma_f32_16x16x32_bf16 v[88:91], v[176:179], v[216:219], v[88:91]
	v_mfma_f32_16x16x32_bf16 v[76:79], v[168:171], v[224:227], v[76:79]
	v_mfma_f32_16x16x32_bf16 v[72:75], v[176:179], v[224:227], v[72:75]
	s_setprio 0
	s_setprio 1
	v_mfma_f32_16x16x32_bf16 v[116:119], v[180:183], v[196:199], v[116:119]
	v_mfma_f32_16x16x32_bf16 v[112:115], v[188:191], v[196:199], v[112:115]
	v_mfma_f32_16x16x32_bf16 v[100:103], v[180:183], v[204:207], v[100:103]
	v_mfma_f32_16x16x32_bf16 v[96:99], v[188:191], v[204:207], v[96:99]
	v_mfma_f32_16x16x32_bf16 v[84:87], v[180:183], v[212:215], v[84:87]
	v_mfma_f32_16x16x32_bf16 v[80:83], v[188:191], v[212:215], v[80:83]
	v_mfma_f32_16x16x32_bf16 v[68:71], v[180:183], v[220:223], v[68:71]
	v_mfma_f32_16x16x32_bf16 v[64:67], v[188:191], v[220:223], v[64:67]
	v_mfma_f32_16x16x32_bf16 v[116:119], v[184:187], v[200:203], v[116:119]
	v_mfma_f32_16x16x32_bf16 v[112:115], v[192:195], v[200:203], v[112:115]
	v_mfma_f32_16x16x32_bf16 v[100:103], v[184:187], v[208:211], v[100:103]
	v_mfma_f32_16x16x32_bf16 v[96:99], v[192:195], v[208:211], v[96:99]
	v_mfma_f32_16x16x32_bf16 v[84:87], v[184:187], v[216:219], v[84:87]
	v_mfma_f32_16x16x32_bf16 v[80:83], v[192:195], v[216:219], v[80:83]
	v_mfma_f32_16x16x32_bf16 v[68:71], v[184:187], v[224:227], v[68:71]
	v_mfma_f32_16x16x32_bf16 v[64:67], v[192:195], v[224:227], v[64:67]
	s_barrier
	s_setprio 0
	s_mov_b32 m0, s5
	v_lshl_add_u64 v[228:229], s[0:1], 0, v[130:131]
	s_add_u32 s60, s0, 0x40000
	ds_read_b128 v[196:199], v150 offset:16384
	ds_read_b128 v[200:203], v150 offset:17408
	ds_read_b128 v[204:207], v150 offset:18432
	ds_read_b128 v[208:211], v150 offset:19456
	ds_read_b128 v[212:215], v150 offset:20480
	ds_read_b128 v[216:219], v150 offset:21504
	ds_read_b128 v[220:223], v150 offset:22528
	ds_read_b128 v[224:227], v150 offset:23552
	global_load_lds_dwordx4 v[228:229], off
	v_lshl_add_u64 v[230:231], s[0:1], 0, v[134:135]
	s_mov_b32 m0, s36
	s_addc_u32 s61, s1, 0
	global_load_lds_dwordx4 v[230:231], off
	v_lshl_add_u64 v[232:233], s[60:61], 0, v[130:131]
	s_mov_b32 m0, s37
	v_lshl_add_u64 v[234:235], s[30:31], 0, v[132:133]
	global_load_lds_dwordx4 v[232:233], off
	v_lshl_add_u64 v[232:233], s[60:61], 0, v[134:135]
	s_mov_b32 m0, s38
	s_nop 0
	global_load_lds_dwordx4 v[232:233], off
	v_lshl_add_u64 v[232:233], s[30:31], 0, v[128:129]
	s_mov_b32 m0, s35
	s_nop 0
	global_load_lds_dwordx4 v[232:233], off
	s_mov_b32 m0, s39
	s_nop 0
	global_load_lds_dwordx4 v[234:235], off
	s_waitcnt vmcnt(8)
	s_waitcnt lgkmcnt(0)
	s_setprio 1
	s_barrier
; #define PG8_STAGE(bufoff, gbase, voff) do { _Pragma("unroll") for (int _i = 0; _i < 2; ++_i) \
;         __builtin_amdgcn_global_load_lds((const unsigned*)((const char*)(gbase) + (voff)[_i]), (PG8_LAS unsigned*)(lds + (bufoff) + ldsw + _i * 8192), 16, 0, 0); } while (0)
; #define PG8_LDA(dst, b, h) do { _Pragma("unroll") for (int m = 0; m < 4; ++m) _Pragma("unroll") for (int k = 0; k < 2; ++k) dst[m][k] = *(const PG8_LAS bf16x8*)(lds + PG8_SA(b, h) + aoff + m * 2048 + k * 1024); } while (0)
; #define PG8_LDB(dst, b, h) do { _Pragma("unroll") for (int n = 0; n < 2; ++n) _Pragma("unroll") for (int k = 0; k < 2; ++k) dst[n][k] = *(const PG8_LAS bf16x8*)(lds + PG8_SB(b, h) + boff + n * 2048 + k * 1024); } while (0)
; #define PG8_MMA(ai, bj, At, Bt) do { __builtin_amdgcn_s_setprio(1); _Pragma("unroll") for (int m = 0; m < 4; ++m) _Pragma("unroll") for (int n = 0; n < 2; ++n) _Pragma("unroll") for (int k = 0; k < 2; ++k) \
;         acc[ai][bj][m][n] = __builtin_amdgcn_mfma_f32_16x16x32_bf16(Bt[n][k], At[m][k], acc[ai][bj][m][n], 0, 0, 0); __builtin_amdgcn_s_setprio(0); } while (0)
; #define PG8_WAIT_V(n) asm volatile("s_waitcnt vmcnt(" #n ")" ::: "memory")
; #define PG8_WAIT_L(n) asm volatile("s_waitcnt lgkmcnt(" #n ")" ::: "memory")
; #define PG8_BAR __builtin_amdgcn_s_barrier()
; #define PG8_SCHED __builtin_amdgcn_sched_barrier(0)
; template <class Epi, class Sched, bool ALIGN_EPI = false, bool SP2 = false>
; __device__ __forceinline__ void gemm_phase(PG8_LAS unsigned char* lds, const Gemm g, const Sched& S, const Epi& E, const int tid_arg) {
;     ...
;             PG8_WAIT_V(8); PG8_WAIT_L(0); PG8_BAR; PG8_MMA(1, 0, At, B0); PG8_MMA(1, 1, At, B1); PG8_BAR; PG8_SCHED;
;             PG8_LDB(B0, 1, 0); PG8_LDB(B1, 1, 1); PG8_SCHED; PG8_LDA(At, 1, 0); PG8_STAGE(PG8_SA(0, 1), a2 + hstep, voffA);
;             PG8_WAIT_V(8); PG8_WAIT_L(0); PG8_BAR; PG8_MMA(0, 0, At, B0); PG8_MMA(0, 1, At, B1); PG8_BAR; PG8_SCHED;
	v_mfma_f32_16x16x32_bf16 v[60:63], v[144:147], v[196:199], v[60:63]
	v_mfma_f32_16x16x32_bf16 v[56:59], v[172:175], v[196:199], v[56:59]
	v_mfma_f32_16x16x32_bf16 v[44:47], v[144:147], v[204:207], v[44:47]
	v_mfma_f32_16x16x32_bf16 v[40:43], v[172:175], v[204:207], v[40:43]
	v_mfma_f32_16x16x32_bf16 v[28:31], v[144:147], v[212:215], v[28:31]
	v_mfma_f32_16x16x32_bf16 v[24:27], v[172:175], v[212:215], v[24:27]
	v_mfma_f32_16x16x32_bf16 v[12:15], v[144:147], v[220:223], v[12:15]
	v_mfma_f32_16x16x32_bf16 v[8:11], v[172:175], v[220:223], v[8:11]
	v_mfma_f32_16x16x32_bf16 v[60:63], v[168:171], v[200:203], v[60:63]
	v_mfma_f32_16x16x32_bf16 v[56:59], v[176:179], v[200:203], v[56:59]
	v_mfma_f32_16x16x32_bf16 v[44:47], v[168:171], v[208:211], v[44:47]
	v_mfma_f32_16x16x32_bf16 v[40:43], v[176:179], v[208:211], v[40:43]
	v_mfma_f32_16x16x32_bf16 v[28:31], v[168:171], v[216:219], v[28:31]
	v_mfma_f32_16x16x32_bf16 v[24:27], v[176:179], v[216:219], v[24:27]
	v_mfma_f32_16x16x32_bf16 v[12:15], v[168:171], v[224:227], v[12:15]
	v_mfma_f32_16x16x32_bf16 v[8:11], v[176:179], v[224:227], v[8:11]
	s_setprio 0
	s_setprio 1
	v_mfma_f32_16x16x32_bf16 v[52:55], v[180:183], v[196:199], v[52:55]
	v_mfma_f32_16x16x32_bf16 v[48:51], v[188:191], v[196:199], v[48:51]
	v_mfma_f32_16x16x32_bf16 v[36:39], v[180:183], v[204:207], v[36:39]
	v_mfma_f32_16x16x32_bf16 v[32:35], v[188:191], v[204:207], v[32:35]
	v_mfma_f32_16x16x32_bf16 v[20:23], v[180:183], v[212:215], v[20:23]
	v_mfma_f32_16x16x32_bf16 v[16:19], v[188:191], v[212:215], v[16:19]
	v_mfma_f32_16x16x32_bf16 v[4:7], v[180:183], v[220:223], v[4:7]
	v_mfma_f32_16x16x32_bf16 v[0:3], v[188:191], v[220:223], v[0:3]
	v_mfma_f32_16x16x32_bf16 v[52:55], v[184:187], v[200:203], v[52:55]
	v_mfma_f32_16x16x32_bf16 v[48:51], v[192:195], v[200:203], v[48:51]
	v_mfma_f32_16x16x32_bf16 v[36:39], v[184:187], v[208:211], v[36:39]
	v_mfma_f32_16x16x32_bf16 v[32:35], v[192:195], v[208:211], v[32:35]
	v_mfma_f32_16x16x32_bf16 v[20:23], v[184:187], v[216:219], v[20:23]
	v_mfma_f32_16x16x32_bf16 v[16:19], v[192:195], v[216:219], v[16:19]
	v_mfma_f32_16x16x32_bf16 v[4:7], v[184:187], v[224:227], v[4:7]
	v_mfma_f32_16x16x32_bf16 v[0:3], v[192:195], v[224:227], v[0:3]
	s_barrier
	s_setprio 0
	ds_read_b128 v[144:147], v159
	ds_read_b128 v[168:171], v160
	ds_read_b128 v[172:175], v161
	ds_read_b128 v[176:179], v162
	ds_read_b128 v[180:183], v163
	ds_read_b128 v[184:187], v164
	ds_read_b128 v[188:191], v165
	ds_read_b128 v[192:195], v166
	s_add_u32 s30, s30, 0x40000
	s_addc_u32 s31, s31, 0
	s_mov_b32 m0, s40
	v_lshl_add_u64 v[236:237], s[30:31], 0, v[128:129]
	ds_read_b128 v[196:199], v150 offset:32768
	ds_read_b128 v[200:203], v150 offset:33792
	ds_read_b128 v[204:207], v150 offset:34816
	ds_read_b128 v[208:211], v150 offset:35840
	ds_read_b128 v[212:215], v150 offset:36864
	ds_read_b128 v[216:219], v150 offset:37888
	ds_read_b128 v[220:223], v150 offset:38912
	ds_read_b128 v[224:227], v150 offset:39936
	global_load_lds_dwordx4 v[236:237], off
	v_lshl_add_u64 v[236:237], s[30:31], 0, v[132:133]
	s_mov_b32 m0, s41
	s_nop 0
	global_load_lds_dwordx4 v[236:237], off
	s_waitcnt vmcnt(8)
	s_waitcnt lgkmcnt(0)
	s_setprio 1
	s_barrier
	v_mfma_f32_16x16x32_bf16 v[124:127], v[144:147], v[196:199], v[124:127]
	v_mfma_f32_16x16x32_bf16 v[120:123], v[172:175], v[196:199], v[120:123]
	v_mfma_f32_16x16x32_bf16 v[108:111], v[144:147], v[204:207], v[108:111]
	v_mfma_f32_16x16x32_bf16 v[104:107], v[172:175], v[204:207], v[104:107]
	v_mfma_f32_16x16x32_bf16 v[92:95], v[144:147], v[212:215], v[92:95]
	v_mfma_f32_16x16x32_bf16 v[88:91], v[172:175], v[212:215], v[88:91]
	v_mfma_f32_16x16x32_bf16 v[76:79], v[144:147], v[220:223], v[76:79]
	v_mfma_f32_16x16x32_bf16 v[72:75], v[172:175], v[220:223], v[72:75]
	v_mfma_f32_16x16x32_bf16 v[124:127], v[168:171], v[200:203], v[124:127]
	v_mfma_f32_16x16x32_bf16 v[120:123], v[176:179], v[200:203], v[120:123]
	v_mfma_f32_16x16x32_bf16 v[108:111], v[168:171], v[208:211], v[108:111]
	v_mfma_f32_16x16x32_bf16 v[104:107], v[176:179], v[208:211], v[104:107]
	v_mfma_f32_16x16x32_bf16 v[92:95], v[168:171], v[216:219], v[92:95]
	v_mfma_f32_16x16x32_bf16 v[88:91], v[176:179], v[216:219], v[88:91]
	v_mfma_f32_16x16x32_bf16 v[76:79], v[168:171], v[224:227], v[76:79]
	v_mfma_f32_16x16x32_bf16 v[72:75], v[176:179], v[224:227], v[72:75]
	s_setprio 0
	s_setprio 1
	v_mfma_f32_16x16x32_bf16 v[116:119], v[180:183], v[196:199], v[116:119]
	v_mfma_f32_16x16x32_bf16 v[112:115], v[188:191], v[196:199], v[112:115]
	v_mfma_f32_16x16x32_bf16 v[100:103], v[180:183], v[204:207], v[100:103]
	v_mfma_f32_16x16x32_bf16 v[96:99], v[188:191], v[204:207], v[96:99]
	v_mfma_f32_16x16x32_bf16 v[84:87], v[180:183], v[212:215], v[84:87]
	v_mfma_f32_16x16x32_bf16 v[80:83], v[188:191], v[212:215], v[80:83]
	v_mfma_f32_16x16x32_bf16 v[68:71], v[180:183], v[220:223], v[68:71]
	v_mfma_f32_16x16x32_bf16 v[64:67], v[188:191], v[220:223], v[64:67]
	v_mfma_f32_16x16x32_bf16 v[116:119], v[184:187], v[200:203], v[116:119]
	v_mfma_f32_16x16x32_bf16 v[112:115], v[192:195], v[200:203], v[112:115]
	v_mfma_f32_16x16x32_bf16 v[100:103], v[184:187], v[208:211], v[100:103]
	v_mfma_f32_16x16x32_bf16 v[96:99], v[192:195], v[208:211], v[96:99]
	v_mfma_f32_16x16x32_bf16 v[84:87], v[184:187], v[216:219], v[84:87]
	v_mfma_f32_16x16x32_bf16 v[80:83], v[192:195], v[216:219], v[80:83]
	v_mfma_f32_16x16x32_bf16 v[68:71], v[184:187], v[224:227], v[68:71]
	v_mfma_f32_16x16x32_bf16 v[64:67], v[192:195], v[224:227], v[64:67]
	s_barrier
; #define PG8_STAGE(bufoff, gbase, voff) do { _Pragma("unroll") for (int _i = 0; _i < 2; ++_i) \
;         __builtin_amdgcn_global_load_lds((const unsigned*)((const char*)(gbase) + (voff)[_i]), (PG8_LAS unsigned*)(lds + (bufoff) + ldsw + _i * 8192), 16, 0, 0); } while (0)
; #define PG8_LDA(dst, b, h) do { _Pragma("unroll") for (int m = 0; m < 4; ++m) _Pragma("unroll") for (int k = 0; k < 2; ++k) dst[m][k] = *(const PG8_LAS bf16x8*)(lds + PG8_SA(b, h) + aoff + m * 2048 + k * 1024); } while (0)
; #define PG8_MMA(ai, bj, At, Bt) do { __builtin_amdgcn_s_setprio(1); _Pragma("unroll") for (int m = 0; m < 4; ++m) _Pragma("unroll") for (int n = 0; n < 2; ++n) _Pragma("unroll") for (int k = 0; k < 2; ++k) \
;         acc[ai][bj][m][n] = __builtin_amdgcn_mfma_f32_16x16x32_bf16(Bt[n][k], At[m][k], acc[ai][bj][m][n], 0, 0, 0); __builtin_amdgcn_s_setprio(0); } while (0)
; #define PG8_WAIT_V(n) asm volatile("s_waitcnt vmcnt(" #n ")" ::: "memory")
; #define PG8_WAIT_L(n) asm volatile("s_waitcnt lgkmcnt(" #n ")" ::: "memory")
; #define PG8_BAR __builtin_amdgcn_s_barrier()
; #define PG8_SCHED __builtin_amdgcn_sched_barrier(0)
; template <class Epi, class Sched, bool ALIGN_EPI = false, bool SP2 = false>
; __device__ __forceinline__ void gemm_phase(PG8_LAS unsigned char* lds, const Gemm g, const Sched& S, const Epi& E, const int tid_arg) {
;     ...
;         for (int t = 0; t < nt; t += 2) {
;             const bool last = (t == nt - 2);
;     ...
;             PG8_LDA(At, 1, 1); PG8_STAGE(PG8_SB(1, 0), b3, voffB); PG8_STAGE(PG8_SB(1, 1), b3 + hstep, voffB); PG8_STAGE(PG8_SA(1, 0), a3, voffA);
;             PG8_WAIT_V(8); PG8_WAIT_L(0); PG8_BAR; PG8_MMA(1, 0, At, B0); PG8_MMA(1, 1, At, B1); PG8_BAR; PG8_SCHED;
;     ...
;         if constexpr (ALIGN_EPI) { if (wr == 0) PG8_BAR; }
	s_setprio 0
	s_mov_b32 m0, s45
	v_lshl_add_u64 v[228:229], v[228:229], 0, s[14:15]
	s_add_u32 s0, s0, 0x40080
	ds_read_b128 v[196:199], v150 offset:49152
	ds_read_b128 v[200:203], v150 offset:50176
	ds_read_b128 v[204:207], v150 offset:51200
	ds_read_b128 v[208:211], v150 offset:52224
	ds_read_b128 v[212:215], v150 offset:53248
	ds_read_b128 v[216:219], v150 offset:54272
	ds_read_b128 v[220:223], v150 offset:55296
	ds_read_b128 v[224:227], v150 offset:56320
	global_load_lds_dwordx4 v[228:229], off
	v_lshl_add_u64 v[228:229], v[230:231], 0, s[14:15]
	s_mov_b32 m0, s46
	s_addc_u32 s1, s1, 0
	global_load_lds_dwordx4 v[228:229], off
	v_lshl_add_u64 v[228:229], s[0:1], 0, v[130:131]
	s_mov_b32 m0, s49
	s_nop 0
	global_load_lds_dwordx4 v[228:229], off
	v_lshl_add_u64 v[228:229], s[0:1], 0, v[134:135]
	s_mov_b32 m0, s50
	s_nop 0
	global_load_lds_dwordx4 v[228:229], off
	v_lshl_add_u64 v[228:229], v[232:233], 0, s[14:15]
	s_mov_b32 m0, s47
	s_nop 0
	global_load_lds_dwordx4 v[228:229], off
	v_lshl_add_u64 v[228:229], v[234:235], 0, s[14:15]
	s_mov_b32 m0, s48
	s_nop 0
	global_load_lds_dwordx4 v[228:229], off
	s_waitcnt vmcnt(8)
	s_waitcnt lgkmcnt(0)
	s_setprio 1
	s_barrier
	v_mfma_f32_16x16x32_bf16 v[60:63], v[144:147], v[196:199], v[60:63]
	v_mfma_f32_16x16x32_bf16 v[56:59], v[172:175], v[196:199], v[56:59]
	v_mfma_f32_16x16x32_bf16 v[44:47], v[144:147], v[204:207], v[44:47]
	v_mfma_f32_16x16x32_bf16 v[40:43], v[172:175], v[204:207], v[40:43]
	v_mfma_f32_16x16x32_bf16 v[28:31], v[144:147], v[212:215], v[28:31]
	v_mfma_f32_16x16x32_bf16 v[24:27], v[172:175], v[212:215], v[24:27]
	v_mfma_f32_16x16x32_bf16 v[12:15], v[144:147], v[220:223], v[12:15]
	v_mfma_f32_16x16x32_bf16 v[8:11], v[172:175], v[220:223], v[8:11]
	v_mfma_f32_16x16x32_bf16 v[60:63], v[168:171], v[200:203], v[60:63]
	v_mfma_f32_16x16x32_bf16 v[56:59], v[176:179], v[200:203], v[56:59]
	v_mfma_f32_16x16x32_bf16 v[44:47], v[168:171], v[208:211], v[44:47]
	v_mfma_f32_16x16x32_bf16 v[40:43], v[176:179], v[208:211], v[40:43]
	v_mfma_f32_16x16x32_bf16 v[28:31], v[168:171], v[216:219], v[28:31]
	v_mfma_f32_16x16x32_bf16 v[24:27], v[176:179], v[216:219], v[24:27]
	v_mfma_f32_16x16x32_bf16 v[12:15], v[168:171], v[224:227], v[12:15]
	v_mfma_f32_16x16x32_bf16 v[8:11], v[176:179], v[224:227], v[8:11]
	s_setprio 0
	s_setprio 1
	v_mfma_f32_16x16x32_bf16 v[52:55], v[180:183], v[196:199], v[52:55]
	v_mfma_f32_16x16x32_bf16 v[48:51], v[188:191], v[196:199], v[48:51]
	v_mfma_f32_16x16x32_bf16 v[36:39], v[180:183], v[204:207], v[36:39]
	v_mfma_f32_16x16x32_bf16 v[32:35], v[188:191], v[204:207], v[32:35]
	v_mfma_f32_16x16x32_bf16 v[20:23], v[180:183], v[212:215], v[20:23]
	v_mfma_f32_16x16x32_bf16 v[16:19], v[188:191], v[212:215], v[16:19]
	v_mfma_f32_16x16x32_bf16 v[4:7], v[180:183], v[220:223], v[4:7]
	v_mfma_f32_16x16x32_bf16 v[0:3], v[188:191], v[220:223], v[0:3]
	v_mfma_f32_16x16x32_bf16 v[52:55], v[184:187], v[200:203], v[52:55]
	v_mfma_f32_16x16x32_bf16 v[48:51], v[192:195], v[200:203], v[48:51]
	v_mfma_f32_16x16x32_bf16 v[36:39], v[184:187], v[208:211], v[36:39]
	v_mfma_f32_16x16x32_bf16 v[32:35], v[192:195], v[208:211], v[32:35]
	v_mfma_f32_16x16x32_bf16 v[20:23], v[184:187], v[216:219], v[20:23]
	v_mfma_f32_16x16x32_bf16 v[16:19], v[192:195], v[216:219], v[16:19]
	v_mfma_f32_16x16x32_bf16 v[4:7], v[184:187], v[224:227], v[4:7]
	v_mfma_f32_16x16x32_bf16 v[0:3], v[192:195], v[224:227], v[0:3]
	s_barrier
	s_setprio 0
	s_add_i32 s59, s59, 2
	s_add_u32 s57, s57, 0x100
	s_addc_u32 s58, s58, 0
	s_add_u32 s28, s28, 0x100
	s_addc_u32 s29, s29, 0
	s_cmp_gt_u32 s59, 13
	s_cbranch_scc0 .LBB0_1459
	s_and_b64 vcc, exec, s[16:17]
	s_cbranch_vccz .LBB0_1462
	s_barrier

; #define PG8_STAGE(bufoff, gbase, voff) do { _Pragma("unroll") for (int _i = 0; _i < 2; ++_i) \
;         __builtin_amdgcn_global_load_lds((const unsigned*)((const char*)(gbase) + (voff)[_i]), (PG8_LAS unsigned*)(lds + (bufoff) + ldsw + _i * 8192), 16, 0, 0); } while (0)
; #define PG8_LDA(dst, b, h) do { _Pragma("unroll") for (int m = 0; m < 4; ++m) _Pragma("unroll") for (int k = 0; k < 2; ++k) dst[m][k] = *(const PG8_LAS bf16x8*)(lds + PG8_SA(b, h) + aoff + m * 2048 + k * 1024); } while (0)
; #define PG8_LDB(dst, b, h) do { _Pragma("unroll") for (int n = 0; n < 2; ++n) _Pragma("unroll") for (int k = 0; k < 2; ++k) dst[n][k] = *(const PG8_LAS bf16x8*)(lds + PG8_SB(b, h) + boff + n * 2048 + k * 1024); } while (0)
; #define PG8_WAIT_V(n) asm volatile("s_waitcnt vmcnt(" #n ")" ::: "memory")
; #define PG8_WAIT_L(n) asm volatile("s_waitcnt lgkmcnt(" #n ")" ::: "memory")
; #define PG8_BAR __builtin_amdgcn_s_barrier()
; #define PG8_SCHED __builtin_amdgcn_sched_barrier(0)
; template <class Epi, class Sched, bool ALIGN_EPI = false, bool SP2 = false>
; __device__ __forceinline__ void gemm_phase(PG8_LAS unsigned char* lds, const Gemm g, const Sched& S, const Epi& E, const int tid_arg) {
;     ...
;         const bool has_next = S.next(ui + 1, nxt);
;         const char* nA = has_next ? (const char*)g.A + (size_t)nxt.pm * tstep : cA; const char* nB = has_next ? (const char*)g.Bt + (size_t)nxt.pn * tstep : cB;
;         for (int t = 0; t < nt; t += 2) {
;             const bool last = (t == nt - 2);
;             const char* a1 = cA + (size_t)(t + 1) * kstep;
;             const char* a2 = last ? nA : cA + (size_t)(t + 2) * kstep; const char* b2 = last ? nB : cB + (size_t)(t + 2) * kstep;
;             const char* a3 = a2 + kstep; const char* b3 = b2 + kstep;
;             if (last && has_next) S.a_ready(nxt);
;             if constexpr (SP2) {
;             PG8_LDB(B0, 0, 0); PG8_LDB(B1, 0, 1); PG8_SCHED; PG8_LDA(At, 0, 0); PG8_STAGE(PG8_SA(1, 1), a1 + hstep, voffA);
;             PG8_WAIT_V(8); PG8_WAIT_L(0); PG8_BAR; PG8_MMA(0, 0, At, B0); PG8_MMA(0, 1, At, B1); PG8_BAR; PG8_SCHED;
;             PG8_LDA(At, 0, 1); PG8_STAGE(PG8_SB(0, 0), b2, voffB); PG8_STAGE(PG8_SB(0, 1), b2 + hstep, voffB); PG8_STAGE(PG8_SA(0, 0), a2, voffA);
;             PG8_WAIT_V(8); PG8_WAIT_L(0); PG8_BAR; PG8_MMA(1, 0, At, B0); PG8_MMA(1, 1, At, B1); PG8_BAR; PG8_SCHED;
.LBB0_1547:
	ds_read_b128 v[72:75], v207
	ds_read_b128 v[100:103], v208
	ds_read_b128 v[136:139], v209
	ds_read_b128 v[140:143], v210
	ds_read_b128 v[144:147], v211
	ds_read_b128 v[148:151], v212
	ds_read_b128 v[152:155], v213
	ds_read_b128 v[156:159], v214
	s_add_u32 s6, s4, 0x100
	s_addc_u32 s7, s5, 0
	s_cmp_eq_u32 s78, 12
	s_cselect_b32 s11, s13, s7
	s_cselect_b32 s10, s31, s6
	s_cselect_b32 s1, s29, s75
	s_cselect_b32 s0, s42, s43
	s_mov_b32 m0, s71
	v_lshl_add_u64 v[184:185], s[4:5], 0, v[196:197]
	ds_read_b128 v[160:163], v206
	ds_read_b128 v[164:167], v206 offset:1024
	ds_read_b128 v[168:171], v206 offset:2048
	ds_read_b128 v[172:175], v206 offset:3072
	ds_read_b128 v[176:179], v206 offset:4096
	ds_read_b128 v[180:183], v206 offset:5120
	ds_read_b128 v[226:229], v206 offset:6144
	ds_read_b128 v[230:233], v206 offset:7168
	global_load_lds_dwordx4 v[184:185], off
	v_lshl_add_u64 v[184:185], s[4:5], 0, v[194:195]
	s_mov_b32 m0, s72
	s_nop 0
	global_load_lds_dwordx4 v[184:185], off
	s_waitcnt vmcnt(8)
	s_waitcnt lgkmcnt(0)
	s_setprio 1
	s_barrier
	v_mfma_f32_16x16x32_bf16 v[132:135], v[72:75], v[160:163], v[132:135]
	v_mfma_f32_16x16x32_bf16 v[60:63], v[136:139], v[160:163], v[60:63]
	v_mfma_f32_16x16x32_bf16 v[124:127], v[72:75], v[168:171], v[124:127]
	v_mfma_f32_16x16x32_bf16 v[52:55], v[136:139], v[168:171], v[52:55]
	v_mfma_f32_16x16x32_bf16 v[116:119], v[72:75], v[176:179], v[116:119]
	v_mfma_f32_16x16x32_bf16 v[44:47], v[136:139], v[176:179], v[44:47]
	v_mfma_f32_16x16x32_bf16 v[108:111], v[72:75], v[226:229], v[108:111]
	v_mfma_f32_16x16x32_bf16 v[36:39], v[136:139], v[226:229], v[36:39]
	v_mfma_f32_16x16x32_bf16 v[132:135], v[100:103], v[164:167], v[132:135]
	v_mfma_f32_16x16x32_bf16 v[60:63], v[140:143], v[164:167], v[60:63]
	v_mfma_f32_16x16x32_bf16 v[124:127], v[100:103], v[172:175], v[124:127]
	v_mfma_f32_16x16x32_bf16 v[52:55], v[140:143], v[172:175], v[52:55]
	v_mfma_f32_16x16x32_bf16 v[116:119], v[100:103], v[180:183], v[116:119]
	v_mfma_f32_16x16x32_bf16 v[44:47], v[140:143], v[180:183], v[44:47]
	v_mfma_f32_16x16x32_bf16 v[108:111], v[100:103], v[230:233], v[108:111]
	v_mfma_f32_16x16x32_bf16 v[36:39], v[140:143], v[230:233], v[36:39]
	s_setprio 0
	s_setprio 1
	v_mfma_f32_16x16x32_bf16 v[128:131], v[144:147], v[160:163], v[128:131]
	v_mfma_f32_16x16x32_bf16 v[56:59], v[152:155], v[160:163], v[56:59]
	v_mfma_f32_16x16x32_bf16 v[120:123], v[144:147], v[168:171], v[120:123]
	v_mfma_f32_16x16x32_bf16 v[48:51], v[152:155], v[168:171], v[48:51]
	v_mfma_f32_16x16x32_bf16 v[112:115], v[144:147], v[176:179], v[112:115]
	v_mfma_f32_16x16x32_bf16 v[40:43], v[152:155], v[176:179], v[40:43]
	v_mfma_f32_16x16x32_bf16 v[104:107], v[144:147], v[226:229], v[104:107]
	v_mfma_f32_16x16x32_bf16 v[32:35], v[152:155], v[226:229], v[32:35]
	v_mfma_f32_16x16x32_bf16 v[128:131], v[148:151], v[164:167], v[128:131]
	v_mfma_f32_16x16x32_bf16 v[56:59], v[156:159], v[164:167], v[56:59]
	v_mfma_f32_16x16x32_bf16 v[120:123], v[148:151], v[172:175], v[120:123]
	v_mfma_f32_16x16x32_bf16 v[48:51], v[156:159], v[172:175], v[48:51]
	v_mfma_f32_16x16x32_bf16 v[112:115], v[148:151], v[180:183], v[112:115]
	v_mfma_f32_16x16x32_bf16 v[40:43], v[156:159], v[180:183], v[40:43]
	v_mfma_f32_16x16x32_bf16 v[104:107], v[148:151], v[230:233], v[104:107]
	v_mfma_f32_16x16x32_bf16 v[32:35], v[156:159], v[230:233], v[32:35]
	s_barrier
	s_setprio 0
	s_mov_b32 m0, s39
	v_lshl_add_u64 v[184:185], s[0:1], 0, v[188:189]
	s_add_u32 s4, s0, 0x40000
	ds_read_b128 v[160:163], v206 offset:16384
	ds_read_b128 v[164:167], v206 offset:17408
	ds_read_b128 v[168:171], v206 offset:18432
	ds_read_b128 v[172:175], v206 offset:19456
	ds_read_b128 v[176:179], v206 offset:20480
	ds_read_b128 v[180:183], v206 offset:21504
	ds_read_b128 v[226:229], v206 offset:22528
	ds_read_b128 v[230:233], v206 offset:23552
	global_load_lds_dwordx4 v[184:185], off
	v_lshl_add_u64 v[202:203], s[0:1], 0, v[192:193]
	s_mov_b32 m0, s41
	s_addc_u32 s5, s1, 0
	global_load_lds_dwordx4 v[202:203], off
	v_lshl_add_u64 v[234:235], s[4:5], 0, v[188:189]
	s_mov_b32 m0, s47
	v_lshl_add_u64 v[236:237], s[10:11], 0, v[190:191]
	global_load_lds_dwordx4 v[234:235], off
	v_lshl_add_u64 v[234:235], s[4:5], 0, v[192:193]
	s_mov_b32 m0, s48
	s_nop 0
	global_load_lds_dwordx4 v[234:235], off
	v_lshl_add_u64 v[234:235], s[10:11], 0, v[186:187]
	s_mov_b32 m0, s46
	s_nop 0
	global_load_lds_dwordx4 v[234:235], off
	s_mov_b32 m0, s49
	s_nop 0
	global_load_lds_dwordx4 v[236:237], off
	s_waitcnt vmcnt(8)
	s_waitcnt lgkmcnt(0)
	s_setprio 1
	s_barrier
; #define PG8_STAGE(bufoff, gbase, voff) do { _Pragma("unroll") for (int _i = 0; _i < 2; ++_i) \
;         __builtin_amdgcn_global_load_lds((const unsigned*)((const char*)(gbase) + (voff)[_i]), (PG8_LAS unsigned*)(lds + (bufoff) + ldsw + _i * 8192), 16, 0, 0); } while (0)
; #define PG8_LDA(dst, b, h) do { _Pragma("unroll") for (int m = 0; m < 4; ++m) _Pragma("unroll") for (int k = 0; k < 2; ++k) dst[m][k] = *(const PG8_LAS bf16x8*)(lds + PG8_SA(b, h) + aoff + m * 2048 + k * 1024); } while (0)
; #define PG8_LDB(dst, b, h) do { _Pragma("unroll") for (int n = 0; n < 2; ++n) _Pragma("unroll") for (int k = 0; k < 2; ++k) dst[n][k] = *(const PG8_LAS bf16x8*)(lds + PG8_SB(b, h) + boff + n * 2048 + k * 1024); } while (0)
; #define PG8_MMA(ai, bj, At, Bt) do { __builtin_amdgcn_s_setprio(1); _Pragma("unroll") for (int m = 0; m < 4; ++m) _Pragma("unroll") for (int n = 0; n < 2; ++n) _Pragma("unroll") for (int k = 0; k < 2; ++k) \
;         acc[ai][bj][m][n] = __builtin_amdgcn_mfma_f32_16x16x32_bf16(Bt[n][k], At[m][k], acc[ai][bj][m][n], 0, 0, 0); __builtin_amdgcn_s_setprio(0); } while (0)
; #define PG8_WAIT_V(n) asm volatile("s_waitcnt vmcnt(" #n ")" ::: "memory")
; #define PG8_WAIT_L(n) asm volatile("s_waitcnt lgkmcnt(" #n ")" ::: "memory")
; #define PG8_BAR __builtin_amdgcn_s_barrier()
; #define PG8_SCHED __builtin_amdgcn_sched_barrier(0)
; template <class Epi, class Sched, bool ALIGN_EPI = false, bool SP2 = false>
; __device__ __forceinline__ void gemm_phase(PG8_LAS unsigned char* lds, const Gemm g, const Sched& S, const Epi& E, const int tid_arg) {
;     ...
;             PG8_WAIT_V(8); PG8_WAIT_L(0); PG8_BAR; PG8_MMA(1, 0, At, B0); PG8_MMA(1, 1, At, B1); PG8_BAR; PG8_SCHED;
;             PG8_LDB(B0, 1, 0); PG8_LDB(B1, 1, 1); PG8_SCHED; PG8_LDA(At, 1, 0); PG8_STAGE(PG8_SA(0, 1), a2 + hstep, voffA);
;             PG8_WAIT_V(8); PG8_WAIT_L(0); PG8_BAR; PG8_MMA(0, 0, At, B0); PG8_MMA(0, 1, At, B1); PG8_BAR; PG8_SCHED;
	v_mfma_f32_16x16x32_bf16 v[96:99], v[72:75], v[160:163], v[96:99]
	v_mfma_f32_16x16x32_bf16 v[28:31], v[136:139], v[160:163], v[28:31]
	v_mfma_f32_16x16x32_bf16 v[88:91], v[72:75], v[168:171], v[88:91]
	v_mfma_f32_16x16x32_bf16 v[20:23], v[136:139], v[168:171], v[20:23]
	v_mfma_f32_16x16x32_bf16 v[80:83], v[72:75], v[176:179], v[80:83]
	v_mfma_f32_16x16x32_bf16 v[12:15], v[136:139], v[176:179], v[12:15]
	v_mfma_f32_16x16x32_bf16 v[68:71], v[72:75], v[226:229], v[68:71]
	v_mfma_f32_16x16x32_bf16 v[4:7], v[136:139], v[226:229], v[4:7]
	v_mfma_f32_16x16x32_bf16 v[96:99], v[100:103], v[164:167], v[96:99]
	v_mfma_f32_16x16x32_bf16 v[28:31], v[140:143], v[164:167], v[28:31]
	v_mfma_f32_16x16x32_bf16 v[88:91], v[100:103], v[172:175], v[88:91]
	v_mfma_f32_16x16x32_bf16 v[20:23], v[140:143], v[172:175], v[20:23]
	v_mfma_f32_16x16x32_bf16 v[80:83], v[100:103], v[180:183], v[80:83]
	v_mfma_f32_16x16x32_bf16 v[12:15], v[140:143], v[180:183], v[12:15]
	v_mfma_f32_16x16x32_bf16 v[68:71], v[100:103], v[230:233], v[68:71]
	v_mfma_f32_16x16x32_bf16 v[4:7], v[140:143], v[230:233], v[4:7]
	s_setprio 0
	s_setprio 1
	v_mfma_f32_16x16x32_bf16 v[24:27], v[152:155], v[160:163], v[24:27]
	v_mfma_f32_16x16x32_bf16 v[84:87], v[144:147], v[168:171], v[84:87]
	v_mfma_f32_16x16x32_bf16 v[16:19], v[152:155], v[168:171], v[16:19]
	v_mfma_f32_16x16x32_bf16 v[76:79], v[144:147], v[176:179], v[76:79]
	v_mfma_f32_16x16x32_bf16 v[8:11], v[152:155], v[176:179], v[8:11]
	v_mfma_f32_16x16x32_bf16 v[64:67], v[144:147], v[226:229], v[64:67]
	v_mfma_f32_16x16x32_bf16 v[0:3], v[152:155], v[226:229], v[0:3]
	v_mfma_f32_16x16x32_bf16 v[72:75], v[144:147], v[160:163], v[92:95]
	v_mfma_f32_16x16x32_bf16 v[24:27], v[156:159], v[164:167], v[24:27]
	v_mfma_f32_16x16x32_bf16 v[84:87], v[148:151], v[172:175], v[84:87]
	v_mfma_f32_16x16x32_bf16 v[16:19], v[156:159], v[172:175], v[16:19]
	v_mfma_f32_16x16x32_bf16 v[76:79], v[148:151], v[180:183], v[76:79]
	v_mfma_f32_16x16x32_bf16 v[8:11], v[156:159], v[180:183], v[8:11]
	v_mfma_f32_16x16x32_bf16 v[64:67], v[148:151], v[230:233], v[64:67]
	v_mfma_f32_16x16x32_bf16 v[0:3], v[156:159], v[230:233], v[0:3]
	v_mfma_f32_16x16x32_bf16 v[72:75], v[148:151], v[164:167], v[72:75]
	s_barrier
	s_setprio 0
	ds_read_b128 v[92:95], v215
	ds_read_b128 v[100:103], v216
	ds_read_b128 v[136:139], v217
	ds_read_b128 v[140:143], v218
	ds_read_b128 v[144:147], v219
	ds_read_b128 v[148:151], v220
	ds_read_b128 v[152:155], v221
	ds_read_b128 v[156:159], v222
	s_add_u32 s4, s10, 0x40000
	s_addc_u32 s5, s11, 0
	s_mov_b32 m0, s50
	v_lshl_add_u64 v[238:239], s[4:5], 0, v[186:187]
	ds_read_b128 v[160:163], v206 offset:32768
	ds_read_b128 v[164:167], v206 offset:33792
	ds_read_b128 v[168:171], v206 offset:34816
	ds_read_b128 v[172:175], v206 offset:35840
	ds_read_b128 v[176:179], v206 offset:36864
	ds_read_b128 v[180:183], v206 offset:37888
	ds_read_b128 v[226:229], v206 offset:38912
	ds_read_b128 v[230:233], v206 offset:39936
	global_load_lds_dwordx4 v[238:239], off
	v_lshl_add_u64 v[238:239], s[4:5], 0, v[190:191]
	s_mov_b32 m0, s51
	s_nop 0
	global_load_lds_dwordx4 v[238:239], off
	s_waitcnt vmcnt(8)
	s_waitcnt lgkmcnt(0)
	s_setprio 1
	s_barrier
	v_mfma_f32_16x16x32_bf16 v[132:135], v[92:95], v[160:163], v[132:135]
	v_mfma_f32_16x16x32_bf16 v[60:63], v[136:139], v[160:163], v[60:63]
	v_mfma_f32_16x16x32_bf16 v[124:127], v[92:95], v[168:171], v[124:127]
	v_mfma_f32_16x16x32_bf16 v[52:55], v[136:139], v[168:171], v[52:55]
	v_mfma_f32_16x16x32_bf16 v[116:119], v[92:95], v[176:179], v[116:119]
	v_mfma_f32_16x16x32_bf16 v[44:47], v[136:139], v[176:179], v[44:47]
	v_mfma_f32_16x16x32_bf16 v[108:111], v[92:95], v[226:229], v[108:111]
	v_mfma_f32_16x16x32_bf16 v[36:39], v[136:139], v[226:229], v[36:39]
	v_mfma_f32_16x16x32_bf16 v[132:135], v[100:103], v[164:167], v[132:135]
	v_mfma_f32_16x16x32_bf16 v[60:63], v[140:143], v[164:167], v[60:63]
	v_mfma_f32_16x16x32_bf16 v[124:127], v[100:103], v[172:175], v[124:127]
	v_mfma_f32_16x16x32_bf16 v[52:55], v[140:143], v[172:175], v[52:55]
	v_mfma_f32_16x16x32_bf16 v[116:119], v[100:103], v[180:183], v[116:119]
	v_mfma_f32_16x16x32_bf16 v[44:47], v[140:143], v[180:183], v[44:47]
	v_mfma_f32_16x16x32_bf16 v[108:111], v[100:103], v[230:233], v[108:111]
	v_mfma_f32_16x16x32_bf16 v[36:39], v[140:143], v[230:233], v[36:39]
	s_setprio 0
	s_setprio 1
	v_mfma_f32_16x16x32_bf16 v[128:131], v[144:147], v[160:163], v[128:131]
	v_mfma_f32_16x16x32_bf16 v[56:59], v[152:155], v[160:163], v[56:59]
	v_mfma_f32_16x16x32_bf16 v[120:123], v[144:147], v[168:171], v[120:123]
	v_mfma_f32_16x16x32_bf16 v[48:51], v[152:155], v[168:171], v[48:51]
	v_mfma_f32_16x16x32_bf16 v[112:115], v[144:147], v[176:179], v[112:115]
	v_mfma_f32_16x16x32_bf16 v[40:43], v[152:155], v[176:179], v[40:43]
	v_mfma_f32_16x16x32_bf16 v[104:107], v[144:147], v[226:229], v[104:107]
	v_mfma_f32_16x16x32_bf16 v[32:35], v[152:155], v[226:229], v[32:35]
	v_mfma_f32_16x16x32_bf16 v[128:131], v[148:151], v[164:167], v[128:131]
	v_mfma_f32_16x16x32_bf16 v[56:59], v[156:159], v[164:167], v[56:59]
	v_mfma_f32_16x16x32_bf16 v[120:123], v[148:151], v[172:175], v[120:123]
	v_mfma_f32_16x16x32_bf16 v[48:51], v[156:159], v[172:175], v[48:51]
	v_mfma_f32_16x16x32_bf16 v[112:115], v[148:151], v[180:183], v[112:115]
	v_mfma_f32_16x16x32_bf16 v[40:43], v[156:159], v[180:183], v[40:43]
	v_mfma_f32_16x16x32_bf16 v[104:107], v[148:151], v[230:233], v[104:107]
	v_mfma_f32_16x16x32_bf16 v[32:35], v[156:159], v[230:233], v[32:35]
	s_barrier
; #define PG8_STAGE(bufoff, gbase, voff) do { _Pragma("unroll") for (int _i = 0; _i < 2; ++_i) \
;         __builtin_amdgcn_global_load_lds((const unsigned*)((const char*)(gbase) + (voff)[_i]), (PG8_LAS unsigned*)(lds + (bufoff) + ldsw + _i * 8192), 16, 0, 0); } while (0)
; #define PG8_LDA(dst, b, h) do { _Pragma("unroll") for (int m = 0; m < 4; ++m) _Pragma("unroll") for (int k = 0; k < 2; ++k) dst[m][k] = *(const PG8_LAS bf16x8*)(lds + PG8_SA(b, h) + aoff + m * 2048 + k * 1024); } while (0)
; #define PG8_MMA(ai, bj, At, Bt) do { __builtin_amdgcn_s_setprio(1); _Pragma("unroll") for (int m = 0; m < 4; ++m) _Pragma("unroll") for (int n = 0; n < 2; ++n) _Pragma("unroll") for (int k = 0; k < 2; ++k) \
;         acc[ai][bj][m][n] = __builtin_amdgcn_mfma_f32_16x16x32_bf16(Bt[n][k], At[m][k], acc[ai][bj][m][n], 0, 0, 0); __builtin_amdgcn_s_setprio(0); } while (0)
; #define PG8_WAIT_V(n) asm volatile("s_waitcnt vmcnt(" #n ")" ::: "memory")
; #define PG8_WAIT_L(n) asm volatile("s_waitcnt lgkmcnt(" #n ")" ::: "memory")
; #define PG8_BAR __builtin_amdgcn_s_barrier()
; #define PG8_SCHED __builtin_amdgcn_sched_barrier(0)
; template <class Epi, class Sched, bool ALIGN_EPI = false, bool SP2 = false>
; __device__ __forceinline__ void gemm_phase(PG8_LAS unsigned char* lds, const Gemm g, const Sched& S, const Epi& E, const int tid_arg) {
;     ...
;         for (int t = 0; t < nt; t += 2) {
;             const bool last = (t == nt - 2);
;     ...
;             PG8_LDA(At, 1, 1); PG8_STAGE(PG8_SB(1, 0), b3, voffB); PG8_STAGE(PG8_SB(1, 1), b3 + hstep, voffB); PG8_STAGE(PG8_SA(1, 0), a3, voffA);
;             PG8_WAIT_V(8); PG8_WAIT_L(0); PG8_BAR; PG8_MMA(1, 0, At, B0); PG8_MMA(1, 1, At, B1); PG8_BAR; PG8_SCHED;
;     ...
;         if constexpr (ALIGN_EPI) { if (wr == 0) PG8_BAR; }
	s_setprio 0
	s_mov_b32 m0, s60
	v_lshl_add_u64 v[184:185], v[184:185], 0, s[20:21]
	s_add_u32 s0, s0, 0x40080
	ds_read_b128 v[160:163], v206 offset:49152
	ds_read_b128 v[164:167], v206 offset:50176
	ds_read_b128 v[168:171], v206 offset:51200
	ds_read_b128 v[172:175], v206 offset:52224
	ds_read_b128 v[176:179], v206 offset:53248
	ds_read_b128 v[180:183], v206 offset:54272
	ds_read_b128 v[226:229], v206 offset:55296
	ds_read_b128 v[230:233], v206 offset:56320
	global_load_lds_dwordx4 v[184:185], off
	v_lshl_add_u64 v[184:185], v[202:203], 0, s[20:21]
	s_mov_b32 m0, s61
	s_addc_u32 s1, s1, 0
	global_load_lds_dwordx4 v[184:185], off
	v_lshl_add_u64 v[184:185], s[0:1], 0, v[188:189]
	s_mov_b32 m0, s64
	s_nop 0
	global_load_lds_dwordx4 v[184:185], off
	v_lshl_add_u64 v[184:185], s[0:1], 0, v[192:193]
	s_mov_b32 m0, s65
	s_nop 0
	global_load_lds_dwordx4 v[184:185], off
	v_lshl_add_u64 v[184:185], v[234:235], 0, s[20:21]
	s_mov_b32 m0, s62
	s_nop 0
	global_load_lds_dwordx4 v[184:185], off
	v_lshl_add_u64 v[184:185], v[236:237], 0, s[20:21]
	s_mov_b32 m0, s63
	s_nop 0
	global_load_lds_dwordx4 v[184:185], off
	s_waitcnt vmcnt(8)
	s_waitcnt lgkmcnt(0)
	s_setprio 1
	s_barrier
	v_mfma_f32_16x16x32_bf16 v[96:99], v[92:95], v[160:163], v[96:99]
	v_mfma_f32_16x16x32_bf16 v[28:31], v[136:139], v[160:163], v[28:31]
	v_mfma_f32_16x16x32_bf16 v[88:91], v[92:95], v[168:171], v[88:91]
	v_mfma_f32_16x16x32_bf16 v[20:23], v[136:139], v[168:171], v[20:23]
	v_mfma_f32_16x16x32_bf16 v[80:83], v[92:95], v[176:179], v[80:83]
	v_mfma_f32_16x16x32_bf16 v[12:15], v[136:139], v[176:179], v[12:15]
	v_mfma_f32_16x16x32_bf16 v[68:71], v[92:95], v[226:229], v[68:71]
	v_mfma_f32_16x16x32_bf16 v[4:7], v[136:139], v[226:229], v[4:7]
	v_mfma_f32_16x16x32_bf16 v[96:99], v[100:103], v[164:167], v[96:99]
	v_mfma_f32_16x16x32_bf16 v[28:31], v[140:143], v[164:167], v[28:31]
	v_mfma_f32_16x16x32_bf16 v[88:91], v[100:103], v[172:175], v[88:91]
	v_mfma_f32_16x16x32_bf16 v[20:23], v[140:143], v[172:175], v[20:23]
	v_mfma_f32_16x16x32_bf16 v[80:83], v[100:103], v[180:183], v[80:83]
	v_mfma_f32_16x16x32_bf16 v[12:15], v[140:143], v[180:183], v[12:15]
	v_mfma_f32_16x16x32_bf16 v[68:71], v[100:103], v[230:233], v[68:71]
	v_mfma_f32_16x16x32_bf16 v[4:7], v[140:143], v[230:233], v[4:7]
	s_setprio 0
	s_setprio 1
	v_mfma_f32_16x16x32_bf16 v[72:75], v[144:147], v[160:163], v[72:75]
	v_mfma_f32_16x16x32_bf16 v[92:95], v[148:151], v[164:167], v[72:75]
	v_mfma_f32_16x16x32_bf16 v[72:75], v[144:147], v[168:171], v[84:87]
	v_mfma_f32_16x16x32_bf16 v[24:27], v[152:155], v[160:163], v[24:27]
	v_mfma_f32_16x16x32_bf16 v[84:87], v[148:151], v[172:175], v[72:75]
	v_mfma_f32_16x16x32_bf16 v[16:19], v[152:155], v[168:171], v[16:19]
	v_mfma_f32_16x16x32_bf16 v[72:75], v[144:147], v[176:179], v[76:79]
	v_mfma_f32_16x16x32_bf16 v[8:11], v[152:155], v[176:179], v[8:11]
	v_mfma_f32_16x16x32_bf16 v[64:67], v[144:147], v[226:229], v[64:67]
	v_mfma_f32_16x16x32_bf16 v[0:3], v[152:155], v[226:229], v[0:3]
	v_mfma_f32_16x16x32_bf16 v[24:27], v[156:159], v[164:167], v[24:27]
	v_mfma_f32_16x16x32_bf16 v[16:19], v[156:159], v[172:175], v[16:19]
	v_mfma_f32_16x16x32_bf16 v[76:79], v[148:151], v[180:183], v[72:75]
	v_mfma_f32_16x16x32_bf16 v[8:11], v[156:159], v[180:183], v[8:11]
	v_mfma_f32_16x16x32_bf16 v[64:67], v[148:151], v[230:233], v[64:67]
	v_mfma_f32_16x16x32_bf16 v[0:3], v[156:159], v[230:233], v[0:3]
	s_barrier
	s_setprio 0
	s_add_i32 s78, s78, 2
	s_add_u32 s43, s43, 0x100
	s_addc_u32 s75, s75, 0
	s_cmp_gt_u32 s78, 13
	s_mov_b64 s[4:5], s[6:7]
	s_cbranch_scc0 .LBB0_1547
	s_and_b64 vcc, exec, s[22:23]
	s_cbranch_vccz .LBB0_1550
	s_barrier

; #define PG8_STAGE(bufoff, gbase, voff) do { _Pragma("unroll") for (int _i = 0; _i < 2; ++_i) \
;         __builtin_amdgcn_global_load_lds((const unsigned*)((const char*)(gbase) + (voff)[_i]), (PG8_LAS unsigned*)(lds + (bufoff) + ldsw + _i * 8192), 16, 0, 0); } while (0)
; #define PG8_LDA(dst, b, h) do { _Pragma("unroll") for (int m = 0; m < 4; ++m) _Pragma("unroll") for (int k = 0; k < 2; ++k) dst[m][k] = *(const PG8_LAS bf16x8*)(lds + PG8_SA(b, h) + aoff + m * 2048 + k * 1024); } while (0)
; #define PG8_LDB(dst, b, h) do { _Pragma("unroll") for (int n = 0; n < 2; ++n) _Pragma("unroll") for (int k = 0; k < 2; ++k) dst[n][k] = *(const PG8_LAS bf16x8*)(lds + PG8_SB(b, h) + boff + n * 2048 + k * 1024); } while (0)
; #define PG8_WAIT_V(n) asm volatile("s_waitcnt vmcnt(" #n ")" ::: "memory")
; #define PG8_WAIT_L(n) asm volatile("s_waitcnt lgkmcnt(" #n ")" ::: "memory")
; #define PG8_BAR __builtin_amdgcn_s_barrier()
; #define PG8_SCHED __builtin_amdgcn_sched_barrier(0)
; template <class Epi, class Sched, bool ALIGN_EPI = false, bool SP2 = false>
; __device__ __forceinline__ void gemm_phase(PG8_LAS unsigned char* lds, const Gemm g, const Sched& S, const Epi& E, const int tid_arg) {
;     ...
;         const bool has_next = S.next(ui + 1, nxt);
;         const char* nA = has_next ? (const char*)g.A + (size_t)nxt.pm * tstep : cA; const char* nB = has_next ? (const char*)g.Bt + (size_t)nxt.pn * tstep : cB;
;         for (int t = 0; t < nt; t += 2) {
;             const bool last = (t == nt - 2);
;             const char* a1 = cA + (size_t)(t + 1) * kstep;
;             const char* a2 = last ? nA : cA + (size_t)(t + 2) * kstep; const char* b2 = last ? nB : cB + (size_t)(t + 2) * kstep;
;             const char* a3 = a2 + kstep; const char* b3 = b2 + kstep;
;             if (last && has_next) S.a_ready(nxt);
;             if constexpr (SP2) {
;             PG8_LDB(B0, 0, 0); PG8_LDB(B1, 0, 1); PG8_SCHED; PG8_LDA(At, 0, 0); PG8_STAGE(PG8_SA(1, 1), a1 + hstep, voffA);
;             PG8_WAIT_V(8); PG8_WAIT_L(0); PG8_BAR; PG8_MMA(0, 0, At, B0); PG8_MMA(0, 1, At, B1); PG8_BAR; PG8_SCHED;
;             PG8_LDA(At, 0, 1); PG8_STAGE(PG8_SB(0, 0), b2, voffB); PG8_STAGE(PG8_SB(0, 1), b2 + hstep, voffB); PG8_STAGE(PG8_SA(0, 0), a2, voffA);
;             PG8_WAIT_V(8); PG8_WAIT_L(0); PG8_BAR; PG8_MMA(1, 0, At, B0); PG8_MMA(1, 1, At, B1); PG8_BAR; PG8_SCHED;
.LBB0_1733:
	ds_read_b128 v[144:147], v151
	ds_read_b128 v[168:171], v152
	ds_read_b128 v[172:175], v153
	ds_read_b128 v[176:179], v154
	ds_read_b128 v[180:183], v155
	ds_read_b128 v[184:187], v156
	ds_read_b128 v[188:191], v157
	ds_read_b128 v[192:195], v158
	s_add_u32 s22, s4, 0x100
	s_addc_u32 s23, s5, 0
	s_cmp_eq_u32 s57, 40
	s_cselect_b32 s25, s9, s23
	s_cselect_b32 s24, s8, s22
	s_cselect_b32 s1, s21, s56
	s_cselect_b32 s0, s20, s55
	s_mov_b32 m0, s48
	v_lshl_add_u64 v[228:229], s[4:5], 0, v[138:139]
	ds_read_b128 v[196:199], v150
	ds_read_b128 v[200:203], v150 offset:1024
	ds_read_b128 v[204:207], v150 offset:2048
	ds_read_b128 v[208:211], v150 offset:3072
	ds_read_b128 v[212:215], v150 offset:4096
	ds_read_b128 v[216:219], v150 offset:5120
	ds_read_b128 v[220:223], v150 offset:6144
	ds_read_b128 v[224:227], v150 offset:7168
	global_load_lds_dwordx4 v[228:229], off
	v_lshl_add_u64 v[228:229], s[4:5], 0, v[136:137]
	s_mov_b32 m0, s49
	s_nop 0
	global_load_lds_dwordx4 v[228:229], off
	s_waitcnt vmcnt(8)
	s_waitcnt lgkmcnt(0)
	s_setprio 1
	s_barrier
	v_mfma_f32_16x16x32_bf16 v[124:127], v[144:147], v[196:199], v[124:127]
	v_mfma_f32_16x16x32_bf16 v[120:123], v[172:175], v[196:199], v[120:123]
	v_mfma_f32_16x16x32_bf16 v[108:111], v[144:147], v[204:207], v[108:111]
	v_mfma_f32_16x16x32_bf16 v[104:107], v[172:175], v[204:207], v[104:107]
	v_mfma_f32_16x16x32_bf16 v[92:95], v[144:147], v[212:215], v[92:95]
	v_mfma_f32_16x16x32_bf16 v[88:91], v[172:175], v[212:215], v[88:91]
	v_mfma_f32_16x16x32_bf16 v[76:79], v[144:147], v[220:223], v[76:79]
	v_mfma_f32_16x16x32_bf16 v[72:75], v[172:175], v[220:223], v[72:75]
	v_mfma_f32_16x16x32_bf16 v[124:127], v[168:171], v[200:203], v[124:127]
	v_mfma_f32_16x16x32_bf16 v[120:123], v[176:179], v[200:203], v[120:123]
	v_mfma_f32_16x16x32_bf16 v[108:111], v[168:171], v[208:211], v[108:111]
	v_mfma_f32_16x16x32_bf16 v[104:107], v[176:179], v[208:211], v[104:107]
	v_mfma_f32_16x16x32_bf16 v[92:95], v[168:171], v[216:219], v[92:95]
	v_mfma_f32_16x16x32_bf16 v[88:91], v[176:179], v[216:219], v[88:91]
	v_mfma_f32_16x16x32_bf16 v[76:79], v[168:171], v[224:227], v[76:79]
	v_mfma_f32_16x16x32_bf16 v[72:75], v[176:179], v[224:227], v[72:75]
	s_setprio 0
	s_setprio 1
	v_mfma_f32_16x16x32_bf16 v[116:119], v[180:183], v[196:199], v[116:119]
	v_mfma_f32_16x16x32_bf16 v[112:115], v[188:191], v[196:199], v[112:115]
	v_mfma_f32_16x16x32_bf16 v[100:103], v[180:183], v[204:207], v[100:103]
	v_mfma_f32_16x16x32_bf16 v[96:99], v[188:191], v[204:207], v[96:99]
	v_mfma_f32_16x16x32_bf16 v[84:87], v[180:183], v[212:215], v[84:87]
	v_mfma_f32_16x16x32_bf16 v[80:83], v[188:191], v[212:215], v[80:83]
	v_mfma_f32_16x16x32_bf16 v[68:71], v[180:183], v[220:223], v[68:71]
	v_mfma_f32_16x16x32_bf16 v[64:67], v[188:191], v[220:223], v[64:67]
	v_mfma_f32_16x16x32_bf16 v[116:119], v[184:187], v[200:203], v[116:119]
	v_mfma_f32_16x16x32_bf16 v[112:115], v[192:195], v[200:203], v[112:115]
	v_mfma_f32_16x16x32_bf16 v[100:103], v[184:187], v[208:211], v[100:103]
	v_mfma_f32_16x16x32_bf16 v[96:99], v[192:195], v[208:211], v[96:99]
	v_mfma_f32_16x16x32_bf16 v[84:87], v[184:187], v[216:219], v[84:87]
	v_mfma_f32_16x16x32_bf16 v[80:83], v[192:195], v[216:219], v[80:83]
	v_mfma_f32_16x16x32_bf16 v[68:71], v[184:187], v[224:227], v[68:71]
	v_mfma_f32_16x16x32_bf16 v[64:67], v[192:195], v[224:227], v[64:67]
	s_barrier
	s_setprio 0
	s_mov_b32 m0, s29
	v_lshl_add_u64 v[228:229], s[0:1], 0, v[130:131]
	s_add_u32 s4, s0, 0xb0000
	ds_read_b128 v[196:199], v150 offset:16384
	ds_read_b128 v[200:203], v150 offset:17408
	ds_read_b128 v[204:207], v150 offset:18432
	ds_read_b128 v[208:211], v150 offset:19456
	ds_read_b128 v[212:215], v150 offset:20480
	ds_read_b128 v[216:219], v150 offset:21504
	ds_read_b128 v[220:223], v150 offset:22528
	ds_read_b128 v[224:227], v150 offset:23552
	global_load_lds_dwordx4 v[228:229], off
	v_lshl_add_u64 v[230:231], s[0:1], 0, v[134:135]
	s_mov_b32 m0, s30
	s_addc_u32 s5, s1, 0
	global_load_lds_dwordx4 v[230:231], off
	v_lshl_add_u64 v[232:233], s[4:5], 0, v[130:131]
	s_mov_b32 m0, s31
	v_lshl_add_u64 v[234:235], s[24:25], 0, v[132:133]
	global_load_lds_dwordx4 v[232:233], off
	v_lshl_add_u64 v[232:233], s[4:5], 0, v[134:135]
	s_mov_b32 m0, s33
	s_nop 0
	global_load_lds_dwordx4 v[232:233], off
	v_lshl_add_u64 v[232:233], s[24:25], 0, v[128:129]
	s_mov_b32 m0, s28
	s_nop 0
	global_load_lds_dwordx4 v[232:233], off
	s_mov_b32 m0, s34
	s_nop 0
	global_load_lds_dwordx4 v[234:235], off
	s_waitcnt vmcnt(8)
	s_waitcnt lgkmcnt(0)
	s_setprio 1
	s_barrier
; #define PG8_STAGE(bufoff, gbase, voff) do { _Pragma("unroll") for (int _i = 0; _i < 2; ++_i) \
;         __builtin_amdgcn_global_load_lds((const unsigned*)((const char*)(gbase) + (voff)[_i]), (PG8_LAS unsigned*)(lds + (bufoff) + ldsw + _i * 8192), 16, 0, 0); } while (0)
; #define PG8_LDA(dst, b, h) do { _Pragma("unroll") for (int m = 0; m < 4; ++m) _Pragma("unroll") for (int k = 0; k < 2; ++k) dst[m][k] = *(const PG8_LAS bf16x8*)(lds + PG8_SA(b, h) + aoff + m * 2048 + k * 1024); } while (0)
; #define PG8_LDB(dst, b, h) do { _Pragma("unroll") for (int n = 0; n < 2; ++n) _Pragma("unroll") for (int k = 0; k < 2; ++k) dst[n][k] = *(const PG8_LAS bf16x8*)(lds + PG8_SB(b, h) + boff + n * 2048 + k * 1024); } while (0)
; #define PG8_MMA(ai, bj, At, Bt) do { __builtin_amdgcn_s_setprio(1); _Pragma("unroll") for (int m = 0; m < 4; ++m) _Pragma("unroll") for (int n = 0; n < 2; ++n) _Pragma("unroll") for (int k = 0; k < 2; ++k) \
;         acc[ai][bj][m][n] = __builtin_amdgcn_mfma_f32_16x16x32_bf16(Bt[n][k], At[m][k], acc[ai][bj][m][n], 0, 0, 0); __builtin_amdgcn_s_setprio(0); } while (0)
; #define PG8_WAIT_V(n) asm volatile("s_waitcnt vmcnt(" #n ")" ::: "memory")
; #define PG8_WAIT_L(n) asm volatile("s_waitcnt lgkmcnt(" #n ")" ::: "memory")
; #define PG8_BAR __builtin_amdgcn_s_barrier()
; #define PG8_SCHED __builtin_amdgcn_sched_barrier(0)
; template <class Epi, class Sched, bool ALIGN_EPI = false, bool SP2 = false>
; __device__ __forceinline__ void gemm_phase(PG8_LAS unsigned char* lds, const Gemm g, const Sched& S, const Epi& E, const int tid_arg) {
;     ...
;             PG8_WAIT_V(8); PG8_WAIT_L(0); PG8_BAR; PG8_MMA(1, 0, At, B0); PG8_MMA(1, 1, At, B1); PG8_BAR; PG8_SCHED;
;             PG8_LDB(B0, 1, 0); PG8_LDB(B1, 1, 1); PG8_SCHED; PG8_LDA(At, 1, 0); PG8_STAGE(PG8_SA(0, 1), a2 + hstep, voffA);
;             PG8_WAIT_V(8); PG8_WAIT_L(0); PG8_BAR; PG8_MMA(0, 0, At, B0); PG8_MMA(0, 1, At, B1); PG8_BAR; PG8_SCHED;
	v_mfma_f32_16x16x32_bf16 v[60:63], v[144:147], v[196:199], v[60:63]
	v_mfma_f32_16x16x32_bf16 v[56:59], v[172:175], v[196:199], v[56:59]
	v_mfma_f32_16x16x32_bf16 v[44:47], v[144:147], v[204:207], v[44:47]
	v_mfma_f32_16x16x32_bf16 v[40:43], v[172:175], v[204:207], v[40:43]
	v_mfma_f32_16x16x32_bf16 v[28:31], v[144:147], v[212:215], v[28:31]
	v_mfma_f32_16x16x32_bf16 v[24:27], v[172:175], v[212:215], v[24:27]
	v_mfma_f32_16x16x32_bf16 v[12:15], v[144:147], v[220:223], v[12:15]
	v_mfma_f32_16x16x32_bf16 v[8:11], v[172:175], v[220:223], v[8:11]
	v_mfma_f32_16x16x32_bf16 v[60:63], v[168:171], v[200:203], v[60:63]
	v_mfma_f32_16x16x32_bf16 v[56:59], v[176:179], v[200:203], v[56:59]
	v_mfma_f32_16x16x32_bf16 v[44:47], v[168:171], v[208:211], v[44:47]
	v_mfma_f32_16x16x32_bf16 v[40:43], v[176:179], v[208:211], v[40:43]
	v_mfma_f32_16x16x32_bf16 v[28:31], v[168:171], v[216:219], v[28:31]
	v_mfma_f32_16x16x32_bf16 v[24:27], v[176:179], v[216:219], v[24:27]
	v_mfma_f32_16x16x32_bf16 v[12:15], v[168:171], v[224:227], v[12:15]
	v_mfma_f32_16x16x32_bf16 v[8:11], v[176:179], v[224:227], v[8:11]
	s_setprio 0
	s_setprio 1
	v_mfma_f32_16x16x32_bf16 v[52:55], v[180:183], v[196:199], v[52:55]
	v_mfma_f32_16x16x32_bf16 v[48:51], v[188:191], v[196:199], v[48:51]
	v_mfma_f32_16x16x32_bf16 v[36:39], v[180:183], v[204:207], v[36:39]
	v_mfma_f32_16x16x32_bf16 v[32:35], v[188:191], v[204:207], v[32:35]
	v_mfma_f32_16x16x32_bf16 v[20:23], v[180:183], v[212:215], v[20:23]
	v_mfma_f32_16x16x32_bf16 v[16:19], v[188:191], v[212:215], v[16:19]
	v_mfma_f32_16x16x32_bf16 v[4:7], v[180:183], v[220:223], v[4:7]
	v_mfma_f32_16x16x32_bf16 v[0:3], v[188:191], v[220:223], v[0:3]
	v_mfma_f32_16x16x32_bf16 v[52:55], v[184:187], v[200:203], v[52:55]
	v_mfma_f32_16x16x32_bf16 v[48:51], v[192:195], v[200:203], v[48:51]
	v_mfma_f32_16x16x32_bf16 v[36:39], v[184:187], v[208:211], v[36:39]
	v_mfma_f32_16x16x32_bf16 v[32:35], v[192:195], v[208:211], v[32:35]
	v_mfma_f32_16x16x32_bf16 v[20:23], v[184:187], v[216:219], v[20:23]
	v_mfma_f32_16x16x32_bf16 v[16:19], v[192:195], v[216:219], v[16:19]
	v_mfma_f32_16x16x32_bf16 v[4:7], v[184:187], v[224:227], v[4:7]
	v_mfma_f32_16x16x32_bf16 v[0:3], v[192:195], v[224:227], v[0:3]
	s_barrier
	s_setprio 0
	ds_read_b128 v[144:147], v159
	ds_read_b128 v[168:171], v160
	ds_read_b128 v[172:175], v161
	ds_read_b128 v[176:179], v162
	ds_read_b128 v[180:183], v163
	ds_read_b128 v[184:187], v164
	ds_read_b128 v[188:191], v165
	ds_read_b128 v[192:195], v166
	s_add_u32 s4, s24, 0xb0000
	s_addc_u32 s5, s25, 0
	s_mov_b32 m0, s35
	v_lshl_add_u64 v[236:237], s[4:5], 0, v[128:129]
	ds_read_b128 v[196:199], v150 offset:32768
	ds_read_b128 v[200:203], v150 offset:33792
	ds_read_b128 v[204:207], v150 offset:34816
	ds_read_b128 v[208:211], v150 offset:35840
	ds_read_b128 v[212:215], v150 offset:36864
	ds_read_b128 v[216:219], v150 offset:37888
	ds_read_b128 v[220:223], v150 offset:38912
	ds_read_b128 v[224:227], v150 offset:39936
	global_load_lds_dwordx4 v[236:237], off
	v_lshl_add_u64 v[236:237], s[4:5], 0, v[132:133]
	s_mov_b32 m0, s36
	s_nop 0
	global_load_lds_dwordx4 v[236:237], off
	s_waitcnt vmcnt(8)
	s_waitcnt lgkmcnt(0)
	s_setprio 1
	s_barrier
	v_mfma_f32_16x16x32_bf16 v[124:127], v[144:147], v[196:199], v[124:127]
	v_mfma_f32_16x16x32_bf16 v[120:123], v[172:175], v[196:199], v[120:123]
	v_mfma_f32_16x16x32_bf16 v[108:111], v[144:147], v[204:207], v[108:111]
	v_mfma_f32_16x16x32_bf16 v[104:107], v[172:175], v[204:207], v[104:107]
	v_mfma_f32_16x16x32_bf16 v[92:95], v[144:147], v[212:215], v[92:95]
	v_mfma_f32_16x16x32_bf16 v[88:91], v[172:175], v[212:215], v[88:91]
	v_mfma_f32_16x16x32_bf16 v[76:79], v[144:147], v[220:223], v[76:79]
	v_mfma_f32_16x16x32_bf16 v[72:75], v[172:175], v[220:223], v[72:75]
	v_mfma_f32_16x16x32_bf16 v[124:127], v[168:171], v[200:203], v[124:127]
	v_mfma_f32_16x16x32_bf16 v[120:123], v[176:179], v[200:203], v[120:123]
	v_mfma_f32_16x16x32_bf16 v[108:111], v[168:171], v[208:211], v[108:111]
	v_mfma_f32_16x16x32_bf16 v[104:107], v[176:179], v[208:211], v[104:107]
	v_mfma_f32_16x16x32_bf16 v[92:95], v[168:171], v[216:219], v[92:95]
	v_mfma_f32_16x16x32_bf16 v[88:91], v[176:179], v[216:219], v[88:91]
	v_mfma_f32_16x16x32_bf16 v[76:79], v[168:171], v[224:227], v[76:79]
	v_mfma_f32_16x16x32_bf16 v[72:75], v[176:179], v[224:227], v[72:75]
	s_setprio 0
	s_setprio 1
	v_mfma_f32_16x16x32_bf16 v[116:119], v[180:183], v[196:199], v[116:119]
	v_mfma_f32_16x16x32_bf16 v[112:115], v[188:191], v[196:199], v[112:115]
	v_mfma_f32_16x16x32_bf16 v[100:103], v[180:183], v[204:207], v[100:103]
	v_mfma_f32_16x16x32_bf16 v[96:99], v[188:191], v[204:207], v[96:99]
	v_mfma_f32_16x16x32_bf16 v[84:87], v[180:183], v[212:215], v[84:87]
	v_mfma_f32_16x16x32_bf16 v[80:83], v[188:191], v[212:215], v[80:83]
	v_mfma_f32_16x16x32_bf16 v[68:71], v[180:183], v[220:223], v[68:71]
	v_mfma_f32_16x16x32_bf16 v[64:67], v[188:191], v[220:223], v[64:67]
	v_mfma_f32_16x16x32_bf16 v[116:119], v[184:187], v[200:203], v[116:119]
	v_mfma_f32_16x16x32_bf16 v[112:115], v[192:195], v[200:203], v[112:115]
	v_mfma_f32_16x16x32_bf16 v[100:103], v[184:187], v[208:211], v[100:103]
	v_mfma_f32_16x16x32_bf16 v[96:99], v[192:195], v[208:211], v[96:99]
	v_mfma_f32_16x16x32_bf16 v[84:87], v[184:187], v[216:219], v[84:87]
	v_mfma_f32_16x16x32_bf16 v[80:83], v[192:195], v[216:219], v[80:83]
	v_mfma_f32_16x16x32_bf16 v[68:71], v[184:187], v[224:227], v[68:71]
	v_mfma_f32_16x16x32_bf16 v[64:67], v[192:195], v[224:227], v[64:67]
	s_barrier
; #define PG8_STAGE(bufoff, gbase, voff) do { _Pragma("unroll") for (int _i = 0; _i < 2; ++_i) \
;         __builtin_amdgcn_global_load_lds((const unsigned*)((const char*)(gbase) + (voff)[_i]), (PG8_LAS unsigned*)(lds + (bufoff) + ldsw + _i * 8192), 16, 0, 0); } while (0)
; #define PG8_LDA(dst, b, h) do { _Pragma("unroll") for (int m = 0; m < 4; ++m) _Pragma("unroll") for (int k = 0; k < 2; ++k) dst[m][k] = *(const PG8_LAS bf16x8*)(lds + PG8_SA(b, h) + aoff + m * 2048 + k * 1024); } while (0)
; #define PG8_MMA(ai, bj, At, Bt) do { __builtin_amdgcn_s_setprio(1); _Pragma("unroll") for (int m = 0; m < 4; ++m) _Pragma("unroll") for (int n = 0; n < 2; ++n) _Pragma("unroll") for (int k = 0; k < 2; ++k) \
;         acc[ai][bj][m][n] = __builtin_amdgcn_mfma_f32_16x16x32_bf16(Bt[n][k], At[m][k], acc[ai][bj][m][n], 0, 0, 0); __builtin_amdgcn_s_setprio(0); } while (0)
; #define PG8_WAIT_V(n) asm volatile("s_waitcnt vmcnt(" #n ")" ::: "memory")
; #define PG8_WAIT_L(n) asm volatile("s_waitcnt lgkmcnt(" #n ")" ::: "memory")
; #define PG8_BAR __builtin_amdgcn_s_barrier()
; #define PG8_SCHED __builtin_amdgcn_sched_barrier(0)
; template <class Epi, class Sched, bool ALIGN_EPI = false, bool SP2 = false>
; __device__ __forceinline__ void gemm_phase(PG8_LAS unsigned char* lds, const Gemm g, const Sched& S, const Epi& E, const int tid_arg) {
;     ...
;         for (int t = 0; t < nt; t += 2) {
;             const bool last = (t == nt - 2);
;     ...
;             PG8_LDA(At, 1, 1); PG8_STAGE(PG8_SB(1, 0), b3, voffB); PG8_STAGE(PG8_SB(1, 1), b3 + hstep, voffB); PG8_STAGE(PG8_SA(1, 0), a3, voffA);
;             PG8_WAIT_V(8); PG8_WAIT_L(0); PG8_BAR; PG8_MMA(1, 0, At, B0); PG8_MMA(1, 1, At, B1); PG8_BAR; PG8_SCHED;
;     ...
;         if constexpr (ALIGN_EPI) { if (wr == 0) PG8_BAR; }
	s_setprio 0
	s_mov_b32 m0, s40
	v_lshl_add_u64 v[228:229], v[228:229], 0, s[16:17]
	s_add_u32 s0, s0, 0xb0080
	ds_read_b128 v[196:199], v150 offset:49152
	ds_read_b128 v[200:203], v150 offset:50176
	ds_read_b128 v[204:207], v150 offset:51200
	ds_read_b128 v[208:211], v150 offset:52224
	ds_read_b128 v[212:215], v150 offset:53248
	ds_read_b128 v[216:219], v150 offset:54272
	ds_read_b128 v[220:223], v150 offset:55296
	ds_read_b128 v[224:227], v150 offset:56320
	global_load_lds_dwordx4 v[228:229], off
	v_lshl_add_u64 v[228:229], v[230:231], 0, s[16:17]
	s_mov_b32 m0, s41
	s_addc_u32 s1, s1, 0
	global_load_lds_dwordx4 v[228:229], off
	v_lshl_add_u64 v[228:229], s[0:1], 0, v[130:131]
	s_mov_b32 m0, s44
	s_nop 0
	global_load_lds_dwordx4 v[228:229], off
	v_lshl_add_u64 v[228:229], s[0:1], 0, v[134:135]
	s_mov_b32 m0, s45
	s_nop 0
	global_load_lds_dwordx4 v[228:229], off
	v_lshl_add_u64 v[228:229], v[232:233], 0, s[16:17]
	s_mov_b32 m0, s42
	s_nop 0
	global_load_lds_dwordx4 v[228:229], off
	v_lshl_add_u64 v[228:229], v[234:235], 0, s[16:17]
	s_mov_b32 m0, s43
	s_nop 0
	global_load_lds_dwordx4 v[228:229], off
	s_waitcnt vmcnt(8)
	s_waitcnt lgkmcnt(0)
	s_setprio 1
	s_barrier
	v_mfma_f32_16x16x32_bf16 v[60:63], v[144:147], v[196:199], v[60:63]
	v_mfma_f32_16x16x32_bf16 v[56:59], v[172:175], v[196:199], v[56:59]
	v_mfma_f32_16x16x32_bf16 v[44:47], v[144:147], v[204:207], v[44:47]
	v_mfma_f32_16x16x32_bf16 v[40:43], v[172:175], v[204:207], v[40:43]
	v_mfma_f32_16x16x32_bf16 v[28:31], v[144:147], v[212:215], v[28:31]
	v_mfma_f32_16x16x32_bf16 v[24:27], v[172:175], v[212:215], v[24:27]
	v_mfma_f32_16x16x32_bf16 v[12:15], v[144:147], v[220:223], v[12:15]
	v_mfma_f32_16x16x32_bf16 v[8:11], v[172:175], v[220:223], v[8:11]
	v_mfma_f32_16x16x32_bf16 v[60:63], v[168:171], v[200:203], v[60:63]
	v_mfma_f32_16x16x32_bf16 v[56:59], v[176:179], v[200:203], v[56:59]
	v_mfma_f32_16x16x32_bf16 v[44:47], v[168:171], v[208:211], v[44:47]
	v_mfma_f32_16x16x32_bf16 v[40:43], v[176:179], v[208:211], v[40:43]
	v_mfma_f32_16x16x32_bf16 v[28:31], v[168:171], v[216:219], v[28:31]
	v_mfma_f32_16x16x32_bf16 v[24:27], v[176:179], v[216:219], v[24:27]
	v_mfma_f32_16x16x32_bf16 v[12:15], v[168:171], v[224:227], v[12:15]
	v_mfma_f32_16x16x32_bf16 v[8:11], v[176:179], v[224:227], v[8:11]
	s_setprio 0
	s_setprio 1
	v_mfma_f32_16x16x32_bf16 v[52:55], v[180:183], v[196:199], v[52:55]
	v_mfma_f32_16x16x32_bf16 v[48:51], v[188:191], v[196:199], v[48:51]
	v_mfma_f32_16x16x32_bf16 v[36:39], v[180:183], v[204:207], v[36:39]
	v_mfma_f32_16x16x32_bf16 v[32:35], v[188:191], v[204:207], v[32:35]
	v_mfma_f32_16x16x32_bf16 v[20:23], v[180:183], v[212:215], v[20:23]
	v_mfma_f32_16x16x32_bf16 v[16:19], v[188:191], v[212:215], v[16:19]
	v_mfma_f32_16x16x32_bf16 v[4:7], v[180:183], v[220:223], v[4:7]
	v_mfma_f32_16x16x32_bf16 v[0:3], v[188:191], v[220:223], v[0:3]
	v_mfma_f32_16x16x32_bf16 v[52:55], v[184:187], v[200:203], v[52:55]
	v_mfma_f32_16x16x32_bf16 v[48:51], v[192:195], v[200:203], v[48:51]
	v_mfma_f32_16x16x32_bf16 v[36:39], v[184:187], v[208:211], v[36:39]
	v_mfma_f32_16x16x32_bf16 v[32:35], v[192:195], v[208:211], v[32:35]
	v_mfma_f32_16x16x32_bf16 v[20:23], v[184:187], v[216:219], v[20:23]
	v_mfma_f32_16x16x32_bf16 v[16:19], v[192:195], v[216:219], v[16:19]
	v_mfma_f32_16x16x32_bf16 v[4:7], v[184:187], v[224:227], v[4:7]
	v_mfma_f32_16x16x32_bf16 v[0:3], v[192:195], v[224:227], v[0:3]
	s_barrier
	s_setprio 0
	s_add_i32 s57, s57, 2
	s_add_u32 s55, s55, 0x100
	s_addc_u32 s56, s56, 0
	s_cmp_gt_u32 s57, 41
	s_mov_b64 s[4:5], s[22:23]
	s_cbranch_scc0 .LBB0_1733
	s_and_b64 vcc, exec, s[18:19]
	s_cbranch_vccz .LBB0_1736
	s_barrier

; #define PG8_STAGE(bufoff, gbase, voff) do { _Pragma("unroll") for (int _i = 0; _i < 2; ++_i) \
;         __builtin_amdgcn_global_load_lds((const unsigned*)((const char*)(gbase) + (voff)[_i]), (PG8_LAS unsigned*)(lds + (bufoff) + ldsw + _i * 8192), 16, 0, 0); } while (0)
; #define PG8_LDA(dst, b, h) do { _Pragma("unroll") for (int m = 0; m < 4; ++m) _Pragma("unroll") for (int k = 0; k < 2; ++k) dst[m][k] = *(const PG8_LAS bf16x8*)(lds + PG8_SA(b, h) + aoff + m * 2048 + k * 1024); } while (0)
; #define PG8_LDB(dst, b, h) do { _Pragma("unroll") for (int n = 0; n < 2; ++n) _Pragma("unroll") for (int k = 0; k < 2; ++k) dst[n][k] = *(const PG8_LAS bf16x8*)(lds + PG8_SB(b, h) + boff + n * 2048 + k * 1024); } while (0)
; #define PG8_WAIT_V(n) asm volatile("s_waitcnt vmcnt(" #n ")" ::: "memory")
; #define PG8_WAIT_L(n) asm volatile("s_waitcnt lgkmcnt(" #n ")" ::: "memory")
; #define PG8_BAR __builtin_amdgcn_s_barrier()
; #define PG8_SCHED __builtin_amdgcn_sched_barrier(0)
; template <class Epi, class Sched, bool ALIGN_EPI = false, bool SP2 = false>
; __device__ __forceinline__ void gemm_phase(PG8_LAS unsigned char* lds, const Gemm g, const Sched& S, const Epi& E, const int tid_arg) {
;     ...
;         const bool has_next = S.next(ui + 1, nxt);
;         const char* nA = has_next ? (const char*)g.A + (size_t)nxt.pm * tstep : cA; const char* nB = has_next ? (const char*)g.Bt + (size_t)nxt.pn * tstep : cB;
;         for (int t = 0; t < nt; t += 2) {
;             const bool last = (t == nt - 2);
;             const char* a1 = cA + (size_t)(t + 1) * kstep;
;             const char* a2 = last ? nA : cA + (size_t)(t + 2) * kstep; const char* b2 = last ? nB : cB + (size_t)(t + 2) * kstep;
;             const char* a3 = a2 + kstep; const char* b3 = b2 + kstep;
;             if (last && has_next) S.a_ready(nxt);
;             if constexpr (SP2) {
;             PG8_LDB(B0, 0, 0); PG8_LDB(B1, 0, 1); PG8_SCHED; PG8_LDA(At, 0, 0); PG8_STAGE(PG8_SA(1, 1), a1 + hstep, voffA);
;             PG8_WAIT_V(8); PG8_WAIT_L(0); PG8_BAR; PG8_MMA(0, 0, At, B0); PG8_MMA(0, 1, At, B1); PG8_BAR; PG8_SCHED;
;             PG8_LDA(At, 0, 1); PG8_STAGE(PG8_SB(0, 0), b2, voffB); PG8_STAGE(PG8_SB(0, 1), b2 + hstep, voffB); PG8_STAGE(PG8_SA(0, 0), a2, voffA);
;             PG8_WAIT_V(8); PG8_WAIT_L(0); PG8_BAR; PG8_MMA(1, 0, At, B0); PG8_MMA(1, 1, At, B1); PG8_BAR; PG8_SCHED;
.LBB0_1827:
	ds_read_b128 v[170:173], v151
	ds_read_b128 v[174:177], v153
	ds_read_b128 v[178:181], v155
	ds_read_b128 v[182:185], v156
	ds_read_b128 v[186:189], v157
	ds_read_b128 v[190:193], v158
	ds_read_b128 v[194:197], v159
	ds_read_b128 v[198:201], v160
	s_add_u32 s0, s44, 0xfffc0080
	s_addc_u32 s1, s45, -1
	s_cmp_eq_u32 s81, 12
	s_cselect_b32 s47, s39, s1
	s_cselect_b32 s46, s75, s0
	s_cselect_b32 s1, s37, s80
	s_cselect_b32 s0, s78, s79
	s_mov_b32 m0, s67
	v_lshl_add_u64 v[234:235], s[44:45], 0, v[138:139]
	ds_read_b128 v[202:205], v149
	ds_read_b128 v[206:209], v149 offset:1024
	ds_read_b128 v[210:213], v149 offset:2048
	ds_read_b128 v[214:217], v149 offset:3072
	ds_read_b128 v[218:221], v149 offset:4096
	ds_read_b128 v[222:225], v149 offset:5120
	ds_read_b128 v[226:229], v149 offset:6144
	ds_read_b128 v[230:233], v149 offset:7168
	global_load_lds_dwordx4 v[234:235], off
	v_lshl_add_u64 v[234:235], s[44:45], 0, v[136:137]
	s_mov_b32 m0, s68
	s_nop 0
	global_load_lds_dwordx4 v[234:235], off
	s_waitcnt vmcnt(8)
	s_waitcnt lgkmcnt(0)
	s_setprio 1
	s_barrier
	v_mfma_f32_16x16x32_bf16 v[124:127], v[170:173], v[202:205], v[124:127]
	v_mfma_f32_16x16x32_bf16 v[120:123], v[178:181], v[202:205], v[120:123]
	v_mfma_f32_16x16x32_bf16 v[108:111], v[170:173], v[210:213], v[108:111]
	v_mfma_f32_16x16x32_bf16 v[104:107], v[178:181], v[210:213], v[104:107]
	v_mfma_f32_16x16x32_bf16 v[92:95], v[170:173], v[218:221], v[92:95]
	v_mfma_f32_16x16x32_bf16 v[88:91], v[178:181], v[218:221], v[88:91]
	v_mfma_f32_16x16x32_bf16 v[76:79], v[170:173], v[226:229], v[76:79]
	v_mfma_f32_16x16x32_bf16 v[72:75], v[178:181], v[226:229], v[72:75]
	v_mfma_f32_16x16x32_bf16 v[124:127], v[174:177], v[206:209], v[124:127]
	v_mfma_f32_16x16x32_bf16 v[120:123], v[182:185], v[206:209], v[120:123]
	v_mfma_f32_16x16x32_bf16 v[108:111], v[174:177], v[214:217], v[108:111]
	v_mfma_f32_16x16x32_bf16 v[104:107], v[182:185], v[214:217], v[104:107]
	v_mfma_f32_16x16x32_bf16 v[92:95], v[174:177], v[222:225], v[92:95]
	v_mfma_f32_16x16x32_bf16 v[88:91], v[182:185], v[222:225], v[88:91]
	v_mfma_f32_16x16x32_bf16 v[76:79], v[174:177], v[230:233], v[76:79]
	v_mfma_f32_16x16x32_bf16 v[72:75], v[182:185], v[230:233], v[72:75]
	s_setprio 0
	s_setprio 1
	v_mfma_f32_16x16x32_bf16 v[116:119], v[186:189], v[202:205], v[116:119]
	v_mfma_f32_16x16x32_bf16 v[112:115], v[194:197], v[202:205], v[112:115]
	v_mfma_f32_16x16x32_bf16 v[100:103], v[186:189], v[210:213], v[100:103]
	v_mfma_f32_16x16x32_bf16 v[96:99], v[194:197], v[210:213], v[96:99]
	v_mfma_f32_16x16x32_bf16 v[84:87], v[186:189], v[218:221], v[84:87]
	v_mfma_f32_16x16x32_bf16 v[80:83], v[194:197], v[218:221], v[80:83]
	v_mfma_f32_16x16x32_bf16 v[68:71], v[186:189], v[226:229], v[68:71]
	v_mfma_f32_16x16x32_bf16 v[64:67], v[194:197], v[226:229], v[64:67]
	v_mfma_f32_16x16x32_bf16 v[116:119], v[190:193], v[206:209], v[116:119]
	v_mfma_f32_16x16x32_bf16 v[112:115], v[198:201], v[206:209], v[112:115]
	v_mfma_f32_16x16x32_bf16 v[100:103], v[190:193], v[214:217], v[100:103]
	v_mfma_f32_16x16x32_bf16 v[96:99], v[198:201], v[214:217], v[96:99]
	v_mfma_f32_16x16x32_bf16 v[84:87], v[190:193], v[222:225], v[84:87]
	v_mfma_f32_16x16x32_bf16 v[80:83], v[198:201], v[222:225], v[80:83]
	v_mfma_f32_16x16x32_bf16 v[68:71], v[190:193], v[230:233], v[68:71]
	v_mfma_f32_16x16x32_bf16 v[64:67], v[198:201], v[230:233], v[64:67]
	s_barrier
	s_setprio 0
	s_mov_b32 m0, s5
	v_lshl_add_u64 v[234:235], s[0:1], 0, v[130:131]
	s_add_u32 s82, s0, 0x40000
	ds_read_b128 v[202:205], v149 offset:16384
	ds_read_b128 v[206:209], v149 offset:17408
	ds_read_b128 v[210:213], v149 offset:18432
	ds_read_b128 v[214:217], v149 offset:19456
	ds_read_b128 v[218:221], v149 offset:20480
	ds_read_b128 v[222:225], v149 offset:21504
	ds_read_b128 v[226:229], v149 offset:22528
	ds_read_b128 v[230:233], v149 offset:23552
	global_load_lds_dwordx4 v[234:235], off
	v_lshl_add_u64 v[236:237], s[0:1], 0, v[134:135]
	s_mov_b32 m0, s51
	s_addc_u32 s83, s1, 0
	global_load_lds_dwordx4 v[236:237], off
	v_lshl_add_u64 v[238:239], s[82:83], 0, v[130:131]
	s_mov_b32 m0, s52
	v_lshl_add_u64 v[240:241], s[46:47], 0, v[132:133]
	global_load_lds_dwordx4 v[238:239], off
	v_lshl_add_u64 v[238:239], s[82:83], 0, v[134:135]
	s_mov_b32 m0, s53
	s_nop 0
	global_load_lds_dwordx4 v[238:239], off
	v_lshl_add_u64 v[238:239], s[46:47], 0, v[128:129]
	s_mov_b32 m0, s50
	s_nop 0
	global_load_lds_dwordx4 v[238:239], off
	s_mov_b32 m0, s54
	s_nop 0
	global_load_lds_dwordx4 v[240:241], off
	s_waitcnt vmcnt(8)
	s_waitcnt lgkmcnt(0)
	s_setprio 1
	s_barrier
; #define PG8_STAGE(bufoff, gbase, voff) do { _Pragma("unroll") for (int _i = 0; _i < 2; ++_i) \
;         __builtin_amdgcn_global_load_lds((const unsigned*)((const char*)(gbase) + (voff)[_i]), (PG8_LAS unsigned*)(lds + (bufoff) + ldsw + _i * 8192), 16, 0, 0); } while (0)
; #define PG8_LDA(dst, b, h) do { _Pragma("unroll") for (int m = 0; m < 4; ++m) _Pragma("unroll") for (int k = 0; k < 2; ++k) dst[m][k] = *(const PG8_LAS bf16x8*)(lds + PG8_SA(b, h) + aoff + m * 2048 + k * 1024); } while (0)
; #define PG8_LDB(dst, b, h) do { _Pragma("unroll") for (int n = 0; n < 2; ++n) _Pragma("unroll") for (int k = 0; k < 2; ++k) dst[n][k] = *(const PG8_LAS bf16x8*)(lds + PG8_SB(b, h) + boff + n * 2048 + k * 1024); } while (0)
; #define PG8_MMA(ai, bj, At, Bt) do { __builtin_amdgcn_s_setprio(1); _Pragma("unroll") for (int m = 0; m < 4; ++m) _Pragma("unroll") for (int n = 0; n < 2; ++n) _Pragma("unroll") for (int k = 0; k < 2; ++k) \
;         acc[ai][bj][m][n] = __builtin_amdgcn_mfma_f32_16x16x32_bf16(Bt[n][k], At[m][k], acc[ai][bj][m][n], 0, 0, 0); __builtin_amdgcn_s_setprio(0); } while (0)
; #define PG8_WAIT_V(n) asm volatile("s_waitcnt vmcnt(" #n ")" ::: "memory")
; #define PG8_WAIT_L(n) asm volatile("s_waitcnt lgkmcnt(" #n ")" ::: "memory")
; #define PG8_BAR __builtin_amdgcn_s_barrier()
; #define PG8_SCHED __builtin_amdgcn_sched_barrier(0)
; template <class Epi, class Sched, bool ALIGN_EPI = false, bool SP2 = false>
; __device__ __forceinline__ void gemm_phase(PG8_LAS unsigned char* lds, const Gemm g, const Sched& S, const Epi& E, const int tid_arg) {
;     ...
;             PG8_WAIT_V(8); PG8_WAIT_L(0); PG8_BAR; PG8_MMA(1, 0, At, B0); PG8_MMA(1, 1, At, B1); PG8_BAR; PG8_SCHED;
;             PG8_LDB(B0, 1, 0); PG8_LDB(B1, 1, 1); PG8_SCHED; PG8_LDA(At, 1, 0); PG8_STAGE(PG8_SA(0, 1), a2 + hstep, voffA);
;             PG8_WAIT_V(8); PG8_WAIT_L(0); PG8_BAR; PG8_MMA(0, 0, At, B0); PG8_MMA(0, 1, At, B1); PG8_BAR; PG8_SCHED;
	v_mfma_f32_16x16x32_bf16 v[60:63], v[170:173], v[202:205], v[60:63]
	v_mfma_f32_16x16x32_bf16 v[56:59], v[178:181], v[202:205], v[56:59]
	v_mfma_f32_16x16x32_bf16 v[44:47], v[170:173], v[210:213], v[44:47]
	v_mfma_f32_16x16x32_bf16 v[40:43], v[178:181], v[210:213], v[40:43]
	v_mfma_f32_16x16x32_bf16 v[28:31], v[170:173], v[218:221], v[28:31]
	v_mfma_f32_16x16x32_bf16 v[24:27], v[178:181], v[218:221], v[24:27]
	v_mfma_f32_16x16x32_bf16 v[12:15], v[170:173], v[226:229], v[12:15]
	v_mfma_f32_16x16x32_bf16 v[8:11], v[178:181], v[226:229], v[8:11]
	v_mfma_f32_16x16x32_bf16 v[60:63], v[174:177], v[206:209], v[60:63]
	v_mfma_f32_16x16x32_bf16 v[56:59], v[182:185], v[206:209], v[56:59]
	v_mfma_f32_16x16x32_bf16 v[44:47], v[174:177], v[214:217], v[44:47]
	v_mfma_f32_16x16x32_bf16 v[40:43], v[182:185], v[214:217], v[40:43]
	v_mfma_f32_16x16x32_bf16 v[28:31], v[174:177], v[222:225], v[28:31]
	v_mfma_f32_16x16x32_bf16 v[24:27], v[182:185], v[222:225], v[24:27]
	v_mfma_f32_16x16x32_bf16 v[12:15], v[174:177], v[230:233], v[12:15]
	v_mfma_f32_16x16x32_bf16 v[8:11], v[182:185], v[230:233], v[8:11]
	s_setprio 0
	s_setprio 1
	v_mfma_f32_16x16x32_bf16 v[52:55], v[186:189], v[202:205], v[52:55]
	v_mfma_f32_16x16x32_bf16 v[48:51], v[194:197], v[202:205], v[48:51]
	v_mfma_f32_16x16x32_bf16 v[36:39], v[186:189], v[210:213], v[36:39]
	v_mfma_f32_16x16x32_bf16 v[32:35], v[194:197], v[210:213], v[32:35]
	v_mfma_f32_16x16x32_bf16 v[20:23], v[186:189], v[218:221], v[20:23]
	v_mfma_f32_16x16x32_bf16 v[16:19], v[194:197], v[218:221], v[16:19]
	v_mfma_f32_16x16x32_bf16 v[4:7], v[186:189], v[226:229], v[4:7]
	v_mfma_f32_16x16x32_bf16 v[0:3], v[194:197], v[226:229], v[0:3]
	v_mfma_f32_16x16x32_bf16 v[52:55], v[190:193], v[206:209], v[52:55]
	v_mfma_f32_16x16x32_bf16 v[48:51], v[198:201], v[206:209], v[48:51]
	v_mfma_f32_16x16x32_bf16 v[36:39], v[190:193], v[214:217], v[36:39]
	v_mfma_f32_16x16x32_bf16 v[32:35], v[198:201], v[214:217], v[32:35]
	v_mfma_f32_16x16x32_bf16 v[20:23], v[190:193], v[222:225], v[20:23]
	v_mfma_f32_16x16x32_bf16 v[16:19], v[198:201], v[222:225], v[16:19]
	v_mfma_f32_16x16x32_bf16 v[4:7], v[190:193], v[230:233], v[4:7]
	v_mfma_f32_16x16x32_bf16 v[0:3], v[198:201], v[230:233], v[0:3]
	s_barrier
	s_setprio 0
	ds_read_b128 v[170:173], v161
	ds_read_b128 v[174:177], v162
	ds_read_b128 v[178:181], v163
	ds_read_b128 v[182:185], v164
	ds_read_b128 v[186:189], v165
	ds_read_b128 v[190:193], v166
	ds_read_b128 v[194:197], v167
	ds_read_b128 v[198:201], v168
	s_add_u32 s46, s46, 0x40000
	s_addc_u32 s47, s47, 0
	s_mov_b32 m0, s55
	v_lshl_add_u64 v[242:243], s[46:47], 0, v[128:129]
	ds_read_b128 v[202:205], v149 offset:32768
	ds_read_b128 v[206:209], v149 offset:33792
	ds_read_b128 v[210:213], v149 offset:34816
	ds_read_b128 v[214:217], v149 offset:35840
	ds_read_b128 v[218:221], v149 offset:36864
	ds_read_b128 v[222:225], v149 offset:37888
	ds_read_b128 v[226:229], v149 offset:38912
	ds_read_b128 v[230:233], v149 offset:39936
	global_load_lds_dwordx4 v[242:243], off
	v_lshl_add_u64 v[242:243], s[46:47], 0, v[132:133]
	s_mov_b32 m0, s56
	s_nop 0
	global_load_lds_dwordx4 v[242:243], off
	s_waitcnt vmcnt(8)
	s_waitcnt lgkmcnt(0)
	s_setprio 1
	s_barrier
	v_mfma_f32_16x16x32_bf16 v[124:127], v[170:173], v[202:205], v[124:127]
	v_mfma_f32_16x16x32_bf16 v[120:123], v[178:181], v[202:205], v[120:123]
	v_mfma_f32_16x16x32_bf16 v[108:111], v[170:173], v[210:213], v[108:111]
	v_mfma_f32_16x16x32_bf16 v[104:107], v[178:181], v[210:213], v[104:107]
	v_mfma_f32_16x16x32_bf16 v[92:95], v[170:173], v[218:221], v[92:95]
	v_mfma_f32_16x16x32_bf16 v[88:91], v[178:181], v[218:221], v[88:91]
	v_mfma_f32_16x16x32_bf16 v[76:79], v[170:173], v[226:229], v[76:79]
	v_mfma_f32_16x16x32_bf16 v[72:75], v[178:181], v[226:229], v[72:75]
	v_mfma_f32_16x16x32_bf16 v[124:127], v[174:177], v[206:209], v[124:127]
	v_mfma_f32_16x16x32_bf16 v[120:123], v[182:185], v[206:209], v[120:123]
	v_mfma_f32_16x16x32_bf16 v[108:111], v[174:177], v[214:217], v[108:111]
	v_mfma_f32_16x16x32_bf16 v[104:107], v[182:185], v[214:217], v[104:107]
	v_mfma_f32_16x16x32_bf16 v[92:95], v[174:177], v[222:225], v[92:95]
	v_mfma_f32_16x16x32_bf16 v[88:91], v[182:185], v[222:225], v[88:91]
	v_mfma_f32_16x16x32_bf16 v[76:79], v[174:177], v[230:233], v[76:79]
	v_mfma_f32_16x16x32_bf16 v[72:75], v[182:185], v[230:233], v[72:75]
	s_setprio 0
	s_setprio 1
	v_mfma_f32_16x16x32_bf16 v[116:119], v[186:189], v[202:205], v[116:119]
	v_mfma_f32_16x16x32_bf16 v[112:115], v[194:197], v[202:205], v[112:115]
	v_mfma_f32_16x16x32_bf16 v[100:103], v[186:189], v[210:213], v[100:103]
	v_mfma_f32_16x16x32_bf16 v[96:99], v[194:197], v[210:213], v[96:99]
	v_mfma_f32_16x16x32_bf16 v[84:87], v[186:189], v[218:221], v[84:87]
	v_mfma_f32_16x16x32_bf16 v[80:83], v[194:197], v[218:221], v[80:83]
	v_mfma_f32_16x16x32_bf16 v[68:71], v[186:189], v[226:229], v[68:71]
	v_mfma_f32_16x16x32_bf16 v[64:67], v[194:197], v[226:229], v[64:67]
	v_mfma_f32_16x16x32_bf16 v[116:119], v[190:193], v[206:209], v[116:119]
	v_mfma_f32_16x16x32_bf16 v[112:115], v[198:201], v[206:209], v[112:115]
	v_mfma_f32_16x16x32_bf16 v[100:103], v[190:193], v[214:217], v[100:103]
	v_mfma_f32_16x16x32_bf16 v[96:99], v[198:201], v[214:217], v[96:99]
	v_mfma_f32_16x16x32_bf16 v[84:87], v[190:193], v[222:225], v[84:87]
	v_mfma_f32_16x16x32_bf16 v[80:83], v[198:201], v[222:225], v[80:83]
	v_mfma_f32_16x16x32_bf16 v[68:71], v[190:193], v[230:233], v[68:71]
	v_mfma_f32_16x16x32_bf16 v[64:67], v[198:201], v[230:233], v[64:67]
	s_barrier
; #define PG8_STAGE(bufoff, gbase, voff) do { _Pragma("unroll") for (int _i = 0; _i < 2; ++_i) \
;         __builtin_amdgcn_global_load_lds((const unsigned*)((const char*)(gbase) + (voff)[_i]), (PG8_LAS unsigned*)(lds + (bufoff) + ldsw + _i * 8192), 16, 0, 0); } while (0)
; #define PG8_LDA(dst, b, h) do { _Pragma("unroll") for (int m = 0; m < 4; ++m) _Pragma("unroll") for (int k = 0; k < 2; ++k) dst[m][k] = *(const PG8_LAS bf16x8*)(lds + PG8_SA(b, h) + aoff + m * 2048 + k * 1024); } while (0)
; #define PG8_MMA(ai, bj, At, Bt) do { __builtin_amdgcn_s_setprio(1); _Pragma("unroll") for (int m = 0; m < 4; ++m) _Pragma("unroll") for (int n = 0; n < 2; ++n) _Pragma("unroll") for (int k = 0; k < 2; ++k) \
;         acc[ai][bj][m][n] = __builtin_amdgcn_mfma_f32_16x16x32_bf16(Bt[n][k], At[m][k], acc[ai][bj][m][n], 0, 0, 0); __builtin_amdgcn_s_setprio(0); } while (0)
; #define PG8_WAIT_V(n) asm volatile("s_waitcnt vmcnt(" #n ")" ::: "memory")
; #define PG8_WAIT_L(n) asm volatile("s_waitcnt lgkmcnt(" #n ")" ::: "memory")
; #define PG8_BAR __builtin_amdgcn_s_barrier()
; #define PG8_SCHED __builtin_amdgcn_sched_barrier(0)
; template <class Epi, class Sched, bool ALIGN_EPI = false, bool SP2 = false>
; __device__ __forceinline__ void gemm_phase(PG8_LAS unsigned char* lds, const Gemm g, const Sched& S, const Epi& E, const int tid_arg) {
;     ...
;         for (int t = 0; t < nt; t += 2) {
;             const bool last = (t == nt - 2);
;     ...
;             PG8_LDA(At, 1, 1); PG8_STAGE(PG8_SB(1, 0), b3, voffB); PG8_STAGE(PG8_SB(1, 1), b3 + hstep, voffB); PG8_STAGE(PG8_SA(1, 0), a3, voffA);
;             PG8_WAIT_V(8); PG8_WAIT_L(0); PG8_BAR; PG8_MMA(1, 0, At, B0); PG8_MMA(1, 1, At, B1); PG8_BAR; PG8_SCHED;
;     ...
;         if constexpr (ALIGN_EPI) { if (wr == 0) PG8_BAR; }
	s_setprio 0
	s_mov_b32 m0, s59
	v_lshl_add_u64 v[234:235], v[234:235], 0, s[16:17]
	s_add_u32 s0, s0, 0x40080
	ds_read_b128 v[202:205], v149 offset:49152
	ds_read_b128 v[206:209], v149 offset:50176
	ds_read_b128 v[210:213], v149 offset:51200
	ds_read_b128 v[214:217], v149 offset:52224
	ds_read_b128 v[218:221], v149 offset:53248
	ds_read_b128 v[222:225], v149 offset:54272
	ds_read_b128 v[226:229], v149 offset:55296
	ds_read_b128 v[230:233], v149 offset:56320
	global_load_lds_dwordx4 v[234:235], off
	v_lshl_add_u64 v[234:235], v[236:237], 0, s[16:17]
	s_mov_b32 m0, s60
	s_addc_u32 s1, s1, 0
	global_load_lds_dwordx4 v[234:235], off
	v_lshl_add_u64 v[234:235], s[0:1], 0, v[130:131]
	s_mov_b32 m0, s63
	s_nop 0
	global_load_lds_dwordx4 v[234:235], off
	v_lshl_add_u64 v[234:235], s[0:1], 0, v[134:135]
	s_mov_b32 m0, s64
	s_nop 0
	global_load_lds_dwordx4 v[234:235], off
	v_lshl_add_u64 v[234:235], v[238:239], 0, s[16:17]
	s_mov_b32 m0, s61
	s_nop 0
	global_load_lds_dwordx4 v[234:235], off
	v_lshl_add_u64 v[234:235], v[240:241], 0, s[16:17]
	s_mov_b32 m0, s62
	s_nop 0
	global_load_lds_dwordx4 v[234:235], off
	s_waitcnt vmcnt(8)
	s_waitcnt lgkmcnt(0)
	s_setprio 1
	s_barrier
	v_mfma_f32_16x16x32_bf16 v[60:63], v[170:173], v[202:205], v[60:63]
	v_mfma_f32_16x16x32_bf16 v[56:59], v[178:181], v[202:205], v[56:59]
	v_mfma_f32_16x16x32_bf16 v[44:47], v[170:173], v[210:213], v[44:47]
	v_mfma_f32_16x16x32_bf16 v[40:43], v[178:181], v[210:213], v[40:43]
	v_mfma_f32_16x16x32_bf16 v[28:31], v[170:173], v[218:221], v[28:31]
	v_mfma_f32_16x16x32_bf16 v[24:27], v[178:181], v[218:221], v[24:27]
	v_mfma_f32_16x16x32_bf16 v[12:15], v[170:173], v[226:229], v[12:15]
	v_mfma_f32_16x16x32_bf16 v[8:11], v[178:181], v[226:229], v[8:11]
	v_mfma_f32_16x16x32_bf16 v[60:63], v[174:177], v[206:209], v[60:63]
	v_mfma_f32_16x16x32_bf16 v[56:59], v[182:185], v[206:209], v[56:59]
	v_mfma_f32_16x16x32_bf16 v[44:47], v[174:177], v[214:217], v[44:47]
	v_mfma_f32_16x16x32_bf16 v[40:43], v[182:185], v[214:217], v[40:43]
	v_mfma_f32_16x16x32_bf16 v[28:31], v[174:177], v[222:225], v[28:31]
	v_mfma_f32_16x16x32_bf16 v[24:27], v[182:185], v[222:225], v[24:27]
	v_mfma_f32_16x16x32_bf16 v[12:15], v[174:177], v[230:233], v[12:15]
	v_mfma_f32_16x16x32_bf16 v[8:11], v[182:185], v[230:233], v[8:11]
	s_setprio 0
	s_setprio 1
	v_mfma_f32_16x16x32_bf16 v[52:55], v[186:189], v[202:205], v[52:55]
	v_mfma_f32_16x16x32_bf16 v[48:51], v[194:197], v[202:205], v[48:51]
	v_mfma_f32_16x16x32_bf16 v[36:39], v[186:189], v[210:213], v[36:39]
	v_mfma_f32_16x16x32_bf16 v[32:35], v[194:197], v[210:213], v[32:35]
	v_mfma_f32_16x16x32_bf16 v[20:23], v[186:189], v[218:221], v[20:23]
	v_mfma_f32_16x16x32_bf16 v[16:19], v[194:197], v[218:221], v[16:19]
	v_mfma_f32_16x16x32_bf16 v[4:7], v[186:189], v[226:229], v[4:7]
	v_mfma_f32_16x16x32_bf16 v[0:3], v[194:197], v[226:229], v[0:3]
	v_mfma_f32_16x16x32_bf16 v[52:55], v[190:193], v[206:209], v[52:55]
	v_mfma_f32_16x16x32_bf16 v[48:51], v[198:201], v[206:209], v[48:51]
	v_mfma_f32_16x16x32_bf16 v[36:39], v[190:193], v[214:217], v[36:39]
	v_mfma_f32_16x16x32_bf16 v[32:35], v[198:201], v[214:217], v[32:35]
	v_mfma_f32_16x16x32_bf16 v[20:23], v[190:193], v[222:225], v[20:23]
	v_mfma_f32_16x16x32_bf16 v[16:19], v[198:201], v[222:225], v[16:19]
	v_mfma_f32_16x16x32_bf16 v[4:7], v[190:193], v[230:233], v[4:7]
	v_mfma_f32_16x16x32_bf16 v[0:3], v[198:201], v[230:233], v[0:3]
	s_barrier
	s_setprio 0
	s_add_i32 s81, s81, 2
	s_add_u32 s79, s79, 0x100
	s_addc_u32 s80, s80, 0
	s_add_u32 s44, s44, 0x100
	s_addc_u32 s45, s45, 0
	s_cmp_gt_u32 s81, 13
	s_cbranch_scc0 .LBB0_1827
	s_and_b64 vcc, exec, s[18:19]
	s_cbranch_vccz .LBB0_1830
	s_barrier

; #define PG8_STAGE(bufoff, gbase, voff) do { _Pragma("unroll") for (int _i = 0; _i < 2; ++_i) \
;         __builtin_amdgcn_global_load_lds((const unsigned*)((const char*)(gbase) + (voff)[_i]), (PG8_LAS unsigned*)(lds + (bufoff) + ldsw + _i * 8192), 16, 0, 0); } while (0)
; #define PG8_LDA(dst, b, h) do { _Pragma("unroll") for (int m = 0; m < 4; ++m) _Pragma("unroll") for (int k = 0; k < 2; ++k) dst[m][k] = *(const PG8_LAS bf16x8*)(lds + PG8_SA(b, h) + aoff + m * 2048 + k * 1024); } while (0)
; #define PG8_LDB(dst, b, h) do { _Pragma("unroll") for (int n = 0; n < 2; ++n) _Pragma("unroll") for (int k = 0; k < 2; ++k) dst[n][k] = *(const PG8_LAS bf16x8*)(lds + PG8_SB(b, h) + boff + n * 2048 + k * 1024); } while (0)
; #define PG8_WAIT_V(n) asm volatile("s_waitcnt vmcnt(" #n ")" ::: "memory")
; #define PG8_WAIT_L(n) asm volatile("s_waitcnt lgkmcnt(" #n ")" ::: "memory")
; #define PG8_BAR __builtin_amdgcn_s_barrier()
; #define PG8_SCHED __builtin_amdgcn_sched_barrier(0)
; template <class Epi, class Sched, bool ALIGN_EPI = false, bool SP2 = false>
; __device__ __forceinline__ void gemm_phase(PG8_LAS unsigned char* lds, const Gemm g, const Sched& S, const Epi& E, const int tid_arg) {
;     ...
;         const bool has_next = S.next(ui + 1, nxt);
;         const char* nA = has_next ? (const char*)g.A + (size_t)nxt.pm * tstep : cA; const char* nB = has_next ? (const char*)g.Bt + (size_t)nxt.pn * tstep : cB;
;         for (int t = 0; t < nt; t += 2) {
;             const bool last = (t == nt - 2);
;             const char* a1 = cA + (size_t)(t + 1) * kstep;
;             const char* a2 = last ? nA : cA + (size_t)(t + 2) * kstep; const char* b2 = last ? nB : cB + (size_t)(t + 2) * kstep;
;             const char* a3 = a2 + kstep; const char* b3 = b2 + kstep;
;             if (last && has_next) S.a_ready(nxt);
;             if constexpr (SP2) {
;             PG8_LDB(B0, 0, 0); PG8_LDB(B1, 0, 1); PG8_SCHED; PG8_LDA(At, 0, 0); PG8_STAGE(PG8_SA(1, 1), a1 + hstep, voffA);
;             PG8_WAIT_V(8); PG8_WAIT_L(0); PG8_BAR; PG8_MMA(0, 0, At, B0); PG8_MMA(0, 1, At, B1); PG8_BAR; PG8_SCHED;
;             PG8_LDA(At, 0, 1); PG8_STAGE(PG8_SB(0, 0), b2, voffB); PG8_STAGE(PG8_SB(0, 1), b2 + hstep, voffB); PG8_STAGE(PG8_SA(0, 0), a2, voffA);
;             PG8_WAIT_V(8); PG8_WAIT_L(0); PG8_BAR; PG8_MMA(1, 0, At, B0); PG8_MMA(1, 1, At, B1); PG8_BAR; PG8_SCHED;
.LBB0_1911:
	ds_read_b128 v[144:147], v157
	ds_read_b128 v[148:151], v158
	ds_read_b128 v[174:177], v159
	ds_read_b128 v[178:181], v160
	ds_read_b128 v[182:185], v161
	ds_read_b128 v[186:189], v162
	ds_read_b128 v[190:193], v163
	ds_read_b128 v[194:197], v164
	s_add_i32 s36, s34, 2
	s_add_u32 s37, s6, 0x80
	s_addc_u32 s35, s7, 0
	s_cmp_eq_u32 s57, s34
	s_cselect_b32 s34, s28, s37
	s_cselect_b32 s35, s29, s35
	s_cselect_b32 s67, s31, s64
	s_cselect_b32 s66, s30, s63
	s_mov_b32 m0, s58
	v_lshl_add_u64 v[152:153], s[6:7], 0, v[138:139]
	ds_read_b128 v[198:201], v156
	ds_read_b128 v[202:205], v156 offset:1024
	ds_read_b128 v[206:209], v156 offset:2048
	ds_read_b128 v[210:213], v156 offset:3072
	ds_read_b128 v[214:217], v156 offset:4096
	ds_read_b128 v[218:221], v156 offset:5120
	ds_read_b128 v[222:225], v156 offset:6144
	ds_read_b128 v[226:229], v156 offset:7168
	global_load_lds_dwordx4 v[152:153], off
	v_lshl_add_u64 v[152:153], s[6:7], 0, v[136:137]
	s_mov_b32 m0, s59
	s_nop 0
	global_load_lds_dwordx4 v[152:153], off
	s_waitcnt vmcnt(8)
	s_waitcnt lgkmcnt(0)
	s_setprio 1
	s_barrier
	v_mfma_f32_16x16x32_bf16 v[124:127], v[144:147], v[198:201], v[124:127]
	v_mfma_f32_16x16x32_bf16 v[120:123], v[174:177], v[198:201], v[120:123]
	v_mfma_f32_16x16x32_bf16 v[108:111], v[144:147], v[206:209], v[108:111]
	v_mfma_f32_16x16x32_bf16 v[104:107], v[174:177], v[206:209], v[104:107]
	v_mfma_f32_16x16x32_bf16 v[92:95], v[144:147], v[214:217], v[92:95]
	v_mfma_f32_16x16x32_bf16 v[88:91], v[174:177], v[214:217], v[88:91]
	v_mfma_f32_16x16x32_bf16 v[76:79], v[144:147], v[222:225], v[76:79]
	v_mfma_f32_16x16x32_bf16 v[72:75], v[174:177], v[222:225], v[72:75]
	v_mfma_f32_16x16x32_bf16 v[124:127], v[148:151], v[202:205], v[124:127]
	v_mfma_f32_16x16x32_bf16 v[120:123], v[178:181], v[202:205], v[120:123]
	v_mfma_f32_16x16x32_bf16 v[108:111], v[148:151], v[210:213], v[108:111]
	v_mfma_f32_16x16x32_bf16 v[104:107], v[178:181], v[210:213], v[104:107]
	v_mfma_f32_16x16x32_bf16 v[92:95], v[148:151], v[218:221], v[92:95]
	v_mfma_f32_16x16x32_bf16 v[88:91], v[178:181], v[218:221], v[88:91]
	v_mfma_f32_16x16x32_bf16 v[76:79], v[148:151], v[226:229], v[76:79]
	v_mfma_f32_16x16x32_bf16 v[72:75], v[178:181], v[226:229], v[72:75]
	s_setprio 0
	s_setprio 1
	v_mfma_f32_16x16x32_bf16 v[116:119], v[182:185], v[198:201], v[116:119]
	v_mfma_f32_16x16x32_bf16 v[112:115], v[190:193], v[198:201], v[112:115]
	v_mfma_f32_16x16x32_bf16 v[100:103], v[182:185], v[206:209], v[100:103]
	v_mfma_f32_16x16x32_bf16 v[96:99], v[190:193], v[206:209], v[96:99]
	v_mfma_f32_16x16x32_bf16 v[84:87], v[182:185], v[214:217], v[84:87]
	v_mfma_f32_16x16x32_bf16 v[80:83], v[190:193], v[214:217], v[80:83]
	v_mfma_f32_16x16x32_bf16 v[68:71], v[182:185], v[222:225], v[68:71]
	v_mfma_f32_16x16x32_bf16 v[64:67], v[190:193], v[222:225], v[64:67]
	v_mfma_f32_16x16x32_bf16 v[116:119], v[186:189], v[202:205], v[116:119]
	v_mfma_f32_16x16x32_bf16 v[112:115], v[194:197], v[202:205], v[112:115]
	v_mfma_f32_16x16x32_bf16 v[100:103], v[186:189], v[210:213], v[100:103]
	v_mfma_f32_16x16x32_bf16 v[96:99], v[194:197], v[210:213], v[96:99]
	v_mfma_f32_16x16x32_bf16 v[84:87], v[186:189], v[218:221], v[84:87]
	v_mfma_f32_16x16x32_bf16 v[80:83], v[194:197], v[218:221], v[80:83]
	v_mfma_f32_16x16x32_bf16 v[68:71], v[186:189], v[226:229], v[68:71]
	v_mfma_f32_16x16x32_bf16 v[64:67], v[194:197], v[226:229], v[64:67]
	s_barrier
	s_setprio 0
	s_mov_b32 m0, s42
	v_lshl_add_u64 v[152:153], s[66:67], 0, v[130:131]
	v_lshl_add_u64 v[230:231], s[66:67], 0, v[134:135]
	s_add_u32 s66, s66, s12
	ds_read_b128 v[198:201], v156 offset:16384
	ds_read_b128 v[202:205], v156 offset:17408
	ds_read_b128 v[206:209], v156 offset:18432
	ds_read_b128 v[210:213], v156 offset:19456
	ds_read_b128 v[214:217], v156 offset:20480
	ds_read_b128 v[218:221], v156 offset:21504
	ds_read_b128 v[222:225], v156 offset:22528
	ds_read_b128 v[226:229], v156 offset:23552
	global_load_lds_dwordx4 v[152:153], off
	s_mov_b32 m0, s43
	s_addc_u32 s67, s67, s13
	global_load_lds_dwordx4 v[230:231], off
	v_lshl_add_u64 v[232:233], s[66:67], 0, v[130:131]
	s_mov_b32 m0, s44
	v_lshl_add_u64 v[234:235], s[66:67], 0, v[134:135]
	global_load_lds_dwordx4 v[232:233], off
	s_mov_b32 m0, s45
	v_lshl_add_u64 v[236:237], s[34:35], 0, v[128:129]
	global_load_lds_dwordx4 v[234:235], off
	s_mov_b32 m0, s41
	v_lshl_add_u64 v[238:239], s[34:35], 0, v[132:133]
	global_load_lds_dwordx4 v[236:237], off
	s_mov_b32 m0, s46
	s_nop 0
	global_load_lds_dwordx4 v[238:239], off
	s_waitcnt vmcnt(8)
	s_waitcnt lgkmcnt(0)
	s_setprio 1
	s_barrier
; #define PG8_STAGE(bufoff, gbase, voff) do { _Pragma("unroll") for (int _i = 0; _i < 2; ++_i) \
;         __builtin_amdgcn_global_load_lds((const unsigned*)((const char*)(gbase) + (voff)[_i]), (PG8_LAS unsigned*)(lds + (bufoff) + ldsw + _i * 8192), 16, 0, 0); } while (0)
; #define PG8_LDA(dst, b, h) do { _Pragma("unroll") for (int m = 0; m < 4; ++m) _Pragma("unroll") for (int k = 0; k < 2; ++k) dst[m][k] = *(const PG8_LAS bf16x8*)(lds + PG8_SA(b, h) + aoff + m * 2048 + k * 1024); } while (0)
; #define PG8_LDB(dst, b, h) do { _Pragma("unroll") for (int n = 0; n < 2; ++n) _Pragma("unroll") for (int k = 0; k < 2; ++k) dst[n][k] = *(const PG8_LAS bf16x8*)(lds + PG8_SB(b, h) + boff + n * 2048 + k * 1024); } while (0)
; #define PG8_MMA(ai, bj, At, Bt) do { __builtin_amdgcn_s_setprio(1); _Pragma("unroll") for (int m = 0; m < 4; ++m) _Pragma("unroll") for (int n = 0; n < 2; ++n) _Pragma("unroll") for (int k = 0; k < 2; ++k) \
;         acc[ai][bj][m][n] = __builtin_amdgcn_mfma_f32_16x16x32_bf16(Bt[n][k], At[m][k], acc[ai][bj][m][n], 0, 0, 0); __builtin_amdgcn_s_setprio(0); } while (0)
; #define PG8_WAIT_V(n) asm volatile("s_waitcnt vmcnt(" #n ")" ::: "memory")
; #define PG8_WAIT_L(n) asm volatile("s_waitcnt lgkmcnt(" #n ")" ::: "memory")
; #define PG8_BAR __builtin_amdgcn_s_barrier()
; #define PG8_SCHED __builtin_amdgcn_sched_barrier(0)
; template <class Epi, class Sched, bool ALIGN_EPI = false, bool SP2 = false>
; __device__ __forceinline__ void gemm_phase(PG8_LAS unsigned char* lds, const Gemm g, const Sched& S, const Epi& E, const int tid_arg) {
;     ...
;             PG8_WAIT_V(8); PG8_WAIT_L(0); PG8_BAR; PG8_MMA(1, 0, At, B0); PG8_MMA(1, 1, At, B1); PG8_BAR; PG8_SCHED;
;             PG8_LDB(B0, 1, 0); PG8_LDB(B1, 1, 1); PG8_SCHED; PG8_LDA(At, 1, 0); PG8_STAGE(PG8_SA(0, 1), a2 + hstep, voffA);
;             PG8_WAIT_V(8); PG8_WAIT_L(0); PG8_BAR; PG8_MMA(0, 0, At, B0); PG8_MMA(0, 1, At, B1); PG8_BAR; PG8_SCHED;
	v_mfma_f32_16x16x32_bf16 v[60:63], v[144:147], v[198:201], v[60:63]
	v_mfma_f32_16x16x32_bf16 v[56:59], v[174:177], v[198:201], v[56:59]
	v_mfma_f32_16x16x32_bf16 v[44:47], v[144:147], v[206:209], v[44:47]
	v_mfma_f32_16x16x32_bf16 v[40:43], v[174:177], v[206:209], v[40:43]
	v_mfma_f32_16x16x32_bf16 v[28:31], v[144:147], v[214:217], v[28:31]
	v_mfma_f32_16x16x32_bf16 v[24:27], v[174:177], v[214:217], v[24:27]
	v_mfma_f32_16x16x32_bf16 v[12:15], v[144:147], v[222:225], v[12:15]
	v_mfma_f32_16x16x32_bf16 v[8:11], v[174:177], v[222:225], v[8:11]
	v_mfma_f32_16x16x32_bf16 v[60:63], v[148:151], v[202:205], v[60:63]
	v_mfma_f32_16x16x32_bf16 v[56:59], v[178:181], v[202:205], v[56:59]
	v_mfma_f32_16x16x32_bf16 v[44:47], v[148:151], v[210:213], v[44:47]
	v_mfma_f32_16x16x32_bf16 v[40:43], v[178:181], v[210:213], v[40:43]
	v_mfma_f32_16x16x32_bf16 v[28:31], v[148:151], v[218:221], v[28:31]
	v_mfma_f32_16x16x32_bf16 v[24:27], v[178:181], v[218:221], v[24:27]
	v_mfma_f32_16x16x32_bf16 v[12:15], v[148:151], v[226:229], v[12:15]
	v_mfma_f32_16x16x32_bf16 v[8:11], v[178:181], v[226:229], v[8:11]
	s_setprio 0
	s_setprio 1
	v_mfma_f32_16x16x32_bf16 v[52:55], v[182:185], v[198:201], v[52:55]
	v_mfma_f32_16x16x32_bf16 v[48:51], v[190:193], v[198:201], v[48:51]
	v_mfma_f32_16x16x32_bf16 v[36:39], v[182:185], v[206:209], v[36:39]
	v_mfma_f32_16x16x32_bf16 v[32:35], v[190:193], v[206:209], v[32:35]
	v_mfma_f32_16x16x32_bf16 v[20:23], v[182:185], v[214:217], v[20:23]
	v_mfma_f32_16x16x32_bf16 v[16:19], v[190:193], v[214:217], v[16:19]
	v_mfma_f32_16x16x32_bf16 v[4:7], v[182:185], v[222:225], v[4:7]
	v_mfma_f32_16x16x32_bf16 v[0:3], v[190:193], v[222:225], v[0:3]
	v_mfma_f32_16x16x32_bf16 v[52:55], v[186:189], v[202:205], v[52:55]
	v_mfma_f32_16x16x32_bf16 v[48:51], v[194:197], v[202:205], v[48:51]
	v_mfma_f32_16x16x32_bf16 v[36:39], v[186:189], v[210:213], v[36:39]
	v_mfma_f32_16x16x32_bf16 v[32:35], v[194:197], v[210:213], v[32:35]
	v_mfma_f32_16x16x32_bf16 v[20:23], v[186:189], v[218:221], v[20:23]
	v_mfma_f32_16x16x32_bf16 v[16:19], v[194:197], v[218:221], v[16:19]
	v_mfma_f32_16x16x32_bf16 v[4:7], v[186:189], v[226:229], v[4:7]
	v_mfma_f32_16x16x32_bf16 v[0:3], v[194:197], v[226:229], v[0:3]
	s_barrier
	s_setprio 0
	ds_read_b128 v[144:147], v165
	ds_read_b128 v[148:151], v166
	ds_read_b128 v[174:177], v167
	ds_read_b128 v[178:181], v168
	ds_read_b128 v[182:185], v169
	ds_read_b128 v[186:189], v170
	ds_read_b128 v[190:193], v171
	ds_read_b128 v[194:197], v172
	s_add_u32 s34, s34, s12
	s_addc_u32 s35, s35, s13
	s_mov_b32 m0, s47
	v_lshl_add_u64 v[240:241], s[34:35], 0, v[128:129]
	ds_read_b128 v[198:201], v156 offset:32768
	ds_read_b128 v[202:205], v156 offset:33792
	ds_read_b128 v[206:209], v156 offset:34816
	ds_read_b128 v[210:213], v156 offset:35840
	ds_read_b128 v[214:217], v156 offset:36864
	ds_read_b128 v[218:221], v156 offset:37888
	ds_read_b128 v[222:225], v156 offset:38912
	ds_read_b128 v[226:229], v156 offset:39936
	global_load_lds_dwordx4 v[240:241], off
	v_lshl_add_u64 v[240:241], s[34:35], 0, v[132:133]
	s_mov_b32 m0, s48
	s_nop 0
	global_load_lds_dwordx4 v[240:241], off
	s_waitcnt vmcnt(8)
	s_waitcnt lgkmcnt(0)
	s_setprio 1
	s_barrier
	v_mfma_f32_16x16x32_bf16 v[124:127], v[144:147], v[198:201], v[124:127]
	v_mfma_f32_16x16x32_bf16 v[120:123], v[174:177], v[198:201], v[120:123]
	v_mfma_f32_16x16x32_bf16 v[108:111], v[144:147], v[206:209], v[108:111]
	v_mfma_f32_16x16x32_bf16 v[104:107], v[174:177], v[206:209], v[104:107]
	v_mfma_f32_16x16x32_bf16 v[92:95], v[144:147], v[214:217], v[92:95]
	v_mfma_f32_16x16x32_bf16 v[88:91], v[174:177], v[214:217], v[88:91]
	v_mfma_f32_16x16x32_bf16 v[76:79], v[144:147], v[222:225], v[76:79]
	v_mfma_f32_16x16x32_bf16 v[72:75], v[174:177], v[222:225], v[72:75]
	v_mfma_f32_16x16x32_bf16 v[124:127], v[148:151], v[202:205], v[124:127]
	v_mfma_f32_16x16x32_bf16 v[120:123], v[178:181], v[202:205], v[120:123]
	v_mfma_f32_16x16x32_bf16 v[108:111], v[148:151], v[210:213], v[108:111]
	v_mfma_f32_16x16x32_bf16 v[104:107], v[178:181], v[210:213], v[104:107]
	v_mfma_f32_16x16x32_bf16 v[92:95], v[148:151], v[218:221], v[92:95]
	v_mfma_f32_16x16x32_bf16 v[88:91], v[178:181], v[218:221], v[88:91]
	v_mfma_f32_16x16x32_bf16 v[76:79], v[148:151], v[226:229], v[76:79]
	v_mfma_f32_16x16x32_bf16 v[72:75], v[178:181], v[226:229], v[72:75]
	s_setprio 0
	s_setprio 1
	v_mfma_f32_16x16x32_bf16 v[116:119], v[182:185], v[198:201], v[116:119]
	v_mfma_f32_16x16x32_bf16 v[112:115], v[190:193], v[198:201], v[112:115]
	v_mfma_f32_16x16x32_bf16 v[100:103], v[182:185], v[206:209], v[100:103]
	v_mfma_f32_16x16x32_bf16 v[96:99], v[190:193], v[206:209], v[96:99]
	v_mfma_f32_16x16x32_bf16 v[84:87], v[182:185], v[214:217], v[84:87]
	v_mfma_f32_16x16x32_bf16 v[80:83], v[190:193], v[214:217], v[80:83]
	v_mfma_f32_16x16x32_bf16 v[68:71], v[182:185], v[222:225], v[68:71]
	v_mfma_f32_16x16x32_bf16 v[64:67], v[190:193], v[222:225], v[64:67]
	v_mfma_f32_16x16x32_bf16 v[116:119], v[186:189], v[202:205], v[116:119]
	v_mfma_f32_16x16x32_bf16 v[112:115], v[194:197], v[202:205], v[112:115]
	v_mfma_f32_16x16x32_bf16 v[100:103], v[186:189], v[210:213], v[100:103]
	v_mfma_f32_16x16x32_bf16 v[96:99], v[194:197], v[210:213], v[96:99]
	v_mfma_f32_16x16x32_bf16 v[84:87], v[186:189], v[218:221], v[84:87]
	v_mfma_f32_16x16x32_bf16 v[80:83], v[194:197], v[218:221], v[80:83]
	v_mfma_f32_16x16x32_bf16 v[68:71], v[186:189], v[226:229], v[68:71]
	v_mfma_f32_16x16x32_bf16 v[64:67], v[194:197], v[226:229], v[64:67]
	s_barrier
; #define PG8_STAGE(bufoff, gbase, voff) do { _Pragma("unroll") for (int _i = 0; _i < 2; ++_i) \
;         __builtin_amdgcn_global_load_lds((const unsigned*)((const char*)(gbase) + (voff)[_i]), (PG8_LAS unsigned*)(lds + (bufoff) + ldsw + _i * 8192), 16, 0, 0); } while (0)
; #define PG8_LDA(dst, b, h) do { _Pragma("unroll") for (int m = 0; m < 4; ++m) _Pragma("unroll") for (int k = 0; k < 2; ++k) dst[m][k] = *(const PG8_LAS bf16x8*)(lds + PG8_SA(b, h) + aoff + m * 2048 + k * 1024); } while (0)
; #define PG8_MMA(ai, bj, At, Bt) do { __builtin_amdgcn_s_setprio(1); _Pragma("unroll") for (int m = 0; m < 4; ++m) _Pragma("unroll") for (int n = 0; n < 2; ++n) _Pragma("unroll") for (int k = 0; k < 2; ++k) \
;         acc[ai][bj][m][n] = __builtin_amdgcn_mfma_f32_16x16x32_bf16(Bt[n][k], At[m][k], acc[ai][bj][m][n], 0, 0, 0); __builtin_amdgcn_s_setprio(0); } while (0)
; #define PG8_WAIT_V(n) asm volatile("s_waitcnt vmcnt(" #n ")" ::: "memory")
; #define PG8_WAIT_L(n) asm volatile("s_waitcnt lgkmcnt(" #n ")" ::: "memory")
; #define PG8_BAR __builtin_amdgcn_s_barrier()
; #define PG8_SCHED __builtin_amdgcn_sched_barrier(0)
; template <class Epi, class Sched, bool ALIGN_EPI = false, bool SP2 = false>
; __device__ __forceinline__ void gemm_phase(PG8_LAS unsigned char* lds, const Gemm g, const Sched& S, const Epi& E, const int tid_arg) {
;     ...
;         for (int t = 0; t < nt; t += 2) {
;             const bool last = (t == nt - 2);
;     ...
;             PG8_LDA(At, 1, 1); PG8_STAGE(PG8_SB(1, 0), b3, voffB); PG8_STAGE(PG8_SB(1, 1), b3 + hstep, voffB); PG8_STAGE(PG8_SA(1, 0), a3, voffA);
;             PG8_WAIT_V(8); PG8_WAIT_L(0); PG8_BAR; PG8_MMA(1, 0, At, B0); PG8_MMA(1, 1, At, B1); PG8_BAR; PG8_SCHED;
	s_setprio 0
	s_mov_b32 m0, s49
	v_lshl_add_u64 v[152:153], v[152:153], 0, s[20:21]
	ds_read_b128 v[198:201], v156 offset:49152
	ds_read_b128 v[202:205], v156 offset:50176
	ds_read_b128 v[206:209], v156 offset:51200
	ds_read_b128 v[210:213], v156 offset:52224
	ds_read_b128 v[214:217], v156 offset:53248
	ds_read_b128 v[218:221], v156 offset:54272
	ds_read_b128 v[222:225], v156 offset:55296
	ds_read_b128 v[226:229], v156 offset:56320
	global_load_lds_dwordx4 v[152:153], off
	v_lshl_add_u64 v[152:153], v[230:231], 0, s[20:21]
	s_mov_b32 m0, s50
	s_nop 0
	global_load_lds_dwordx4 v[152:153], off
	v_lshl_add_u64 v[152:153], v[232:233], 0, s[20:21]
	s_mov_b32 m0, s53
	s_nop 0
	global_load_lds_dwordx4 v[152:153], off
	v_lshl_add_u64 v[152:153], v[234:235], 0, s[20:21]
	s_mov_b32 m0, s54
	s_nop 0
	global_load_lds_dwordx4 v[152:153], off
	v_lshl_add_u64 v[152:153], v[236:237], 0, s[20:21]
	s_mov_b32 m0, s51
	s_nop 0
	global_load_lds_dwordx4 v[152:153], off
	v_lshl_add_u64 v[152:153], v[238:239], 0, s[20:21]
	s_mov_b32 m0, s52
	s_nop 0
	global_load_lds_dwordx4 v[152:153], off
	s_waitcnt vmcnt(8)
	s_waitcnt lgkmcnt(0)
	s_setprio 1
	s_barrier
	v_mfma_f32_16x16x32_bf16 v[60:63], v[144:147], v[198:201], v[60:63]
	v_mfma_f32_16x16x32_bf16 v[56:59], v[174:177], v[198:201], v[56:59]
	v_mfma_f32_16x16x32_bf16 v[44:47], v[144:147], v[206:209], v[44:47]
	v_mfma_f32_16x16x32_bf16 v[40:43], v[174:177], v[206:209], v[40:43]
	v_mfma_f32_16x16x32_bf16 v[28:31], v[144:147], v[214:217], v[28:31]
	v_mfma_f32_16x16x32_bf16 v[24:27], v[174:177], v[214:217], v[24:27]
	v_mfma_f32_16x16x32_bf16 v[12:15], v[144:147], v[222:225], v[12:15]
	v_mfma_f32_16x16x32_bf16 v[8:11], v[174:177], v[222:225], v[8:11]
	v_mfma_f32_16x16x32_bf16 v[60:63], v[148:151], v[202:205], v[60:63]
	v_mfma_f32_16x16x32_bf16 v[56:59], v[178:181], v[202:205], v[56:59]
	v_mfma_f32_16x16x32_bf16 v[44:47], v[148:151], v[210:213], v[44:47]
	v_mfma_f32_16x16x32_bf16 v[40:43], v[178:181], v[210:213], v[40:43]
	v_mfma_f32_16x16x32_bf16 v[28:31], v[148:151], v[218:221], v[28:31]
	v_mfma_f32_16x16x32_bf16 v[24:27], v[178:181], v[218:221], v[24:27]
	v_mfma_f32_16x16x32_bf16 v[12:15], v[148:151], v[226:229], v[12:15]
	v_mfma_f32_16x16x32_bf16 v[8:11], v[178:181], v[226:229], v[8:11]
	s_setprio 0
	s_setprio 1
	v_mfma_f32_16x16x32_bf16 v[52:55], v[182:185], v[198:201], v[52:55]
	v_mfma_f32_16x16x32_bf16 v[48:51], v[190:193], v[198:201], v[48:51]
	v_mfma_f32_16x16x32_bf16 v[36:39], v[182:185], v[206:209], v[36:39]
	v_mfma_f32_16x16x32_bf16 v[32:35], v[190:193], v[206:209], v[32:35]
	v_mfma_f32_16x16x32_bf16 v[20:23], v[182:185], v[214:217], v[20:23]
	v_mfma_f32_16x16x32_bf16 v[16:19], v[190:193], v[214:217], v[16:19]
	v_mfma_f32_16x16x32_bf16 v[4:7], v[182:185], v[222:225], v[4:7]
	v_mfma_f32_16x16x32_bf16 v[0:3], v[190:193], v[222:225], v[0:3]
	v_mfma_f32_16x16x32_bf16 v[52:55], v[186:189], v[202:205], v[52:55]
	v_mfma_f32_16x16x32_bf16 v[48:51], v[194:197], v[202:205], v[48:51]
	v_mfma_f32_16x16x32_bf16 v[36:39], v[186:189], v[210:213], v[36:39]
	v_mfma_f32_16x16x32_bf16 v[32:35], v[194:197], v[210:213], v[32:35]
	v_mfma_f32_16x16x32_bf16 v[20:23], v[186:189], v[218:221], v[20:23]
	v_mfma_f32_16x16x32_bf16 v[16:19], v[194:197], v[218:221], v[16:19]
	v_mfma_f32_16x16x32_bf16 v[4:7], v[186:189], v[226:229], v[4:7]
	v_mfma_f32_16x16x32_bf16 v[0:3], v[194:197], v[226:229], v[0:3]
	s_barrier
	s_setprio 0
	s_add_u32 s63, s63, 0x100
	s_addc_u32 s64, s64, 0
	s_add_u32 s6, s6, 0x100
	s_addc_u32 s7, s7, 0
	s_cmp_ge_i32 s36, s55
	s_mov_b32 s34, s36
	s_cbranch_scc0 .LBB0_1911
